# SSM and GDN long-scan step loops also hand-scheduled (16-step unrolled fast paths shared per kind, appended after s_endpgm)
# speedup vs baseline: 1.0909x; 1.0633x over previous
; #define SCAN_INTERLEAVE(nds, nvalu)                                   \
;   _Pragma("unroll") for (int i_ = 0; i_ < (nds); ++i_) {               \
;     __builtin_amdgcn_sched_group_barrier(0x100, 1, 0);                 \
;     __builtin_amdgcn_sched_group_barrier(0x002, (nvalu), 0);           \
;   }
; __device__ __forceinline__ void scan_gdn(const Params& p, int l, int seq, int h, int qt, char* smem, const unsigned* wflags, unsigned wexpect) {
;     ...
;     const int nsteps = min(16, T - c * 16);
;     const float* vb = vec + cur * 16 * 288;
;     const float* sb = scb + cur * 64;
;     GdRegs RA, RB;
;     float* ydummy = yb + 16 * 32 + tid;
;     gd_load(RA, vb, sb, 0, k0, cl);
;     for (int t = 0; t < nsteps; t += 2) {
;       gd_load(RB, vb, sb, min(t + 1, 15), k0, cl);
;       const float o0v = gd_step(S, RA);
;       *((part == 0) ? (yb + t * 32 + cl) : ydummy) = o0v;
;       SCAN_INTERLEAVE(10, 4);
;       if (t + 1 < nsteps) {
;         gd_load(RA, vb, sb, min(t + 2, 15), k0, cl);
;         const float o1v = gd_step(S, RB);
;         *((part == 0) ? (yb + (t + 1) * 32 + cl) : ydummy) = o1v;
;         SCAN_INTERLEAVE(10, 4);
;       }
;     }
.LBB0_188:
	s_or_b64 exec, exec, s[50:51]
	s_lshl_b32 s52, s14, 4
	s_sub_i32 s51, s18, s52
	s_min_i32 s50, s51, 16
	s_cmp_lt_i32 s51, 1
	s_cbranch_scc1 .LBB0_193
	s_cmp_lg_u32 s50, 16
	s_cbranch_scc1 .Lgdf_slow0
	v_add_u32_e32 v103, 0x9200, v2
	v_mov_b32_e32 v100, v151
	v_mov_b32_e32 v101, v150
	v_mov_b32_e32 v102, 0
	v_cndmask_b32_e64 v103, v149, v103, s[44:45]
	s_mov_b32 s51, 0
	s_branch .Lgdf_body
.Lgdf_slow0:
	ds_read_b128 v[36:39], v3 offset:36864
	ds_read_b128 v[68:71], v151 offset:560
	s_waitcnt lgkmcnt(1)
	ds_read_b32 v39, v150 offset:1024
	ds_read_b128 v[40:43], v151
	ds_read_b128 v[44:47], v151 offset:16
	ds_read_b128 v[48:51], v151 offset:32
	ds_read_b128 v[64:67], v151 offset:544
	ds_read_b128 v[60:63], v151 offset:528
	ds_read_b128 v[52:55], v151 offset:48
	ds_read_b128 v[56:59], v151 offset:512
	s_mov_b32 s51, 0
	s_mov_b32 s53, 0x9010
	v_mov_b32_e32 v161, v156
	v_mov_b32_e32 v162, v155
	v_mov_b32_e32 v163, v2
	s_branch .LBB0_191

; #define SCAN_INTERLEAVE(nds, nvalu)                                   \
;   _Pragma("unroll") for (int i_ = 0; i_ < (nds); ++i_) {               \
;     __builtin_amdgcn_sched_group_barrier(0x100, 1, 0);                 \
;     __builtin_amdgcn_sched_group_barrier(0x002, (nvalu), 0);           \
;   }
; __device__ __forceinline__ void scan_gdn(const Params& p, int l, int seq, int h, int qt, char* smem, const unsigned* wflags, unsigned wexpect) {
;     ...
;     const int nsteps = min(16, T - c * 16);
;     const float* vb = vec + cur * 16 * 288;
;     const float* sb = scb + cur * 64;
;     GdRegs RA, RB;
;     float* ydummy = yb + 16 * 32 + tid;
;     gd_load(RA, vb, sb, 0, k0, cl);
;     for (int t = 0; t < nsteps; t += 2) {
;       gd_load(RB, vb, sb, min(t + 1, 15), k0, cl);
;       const float o0v = gd_step(S, RA);
;       *((part == 0) ? (yb + t * 32 + cl) : ydummy) = o0v;
;       SCAN_INTERLEAVE(10, 4);
;       if (t + 1 < nsteps) {
;         gd_load(RA, vb, sb, min(t + 2, 15), k0, cl);
;         const float o1v = gd_step(S, RB);
;         *((part == 0) ? (yb + (t + 1) * 32 + cl) : ydummy) = o1v;
;         SCAN_INTERLEAVE(10, 4);
;       }
;     }
.LBB0_224:
	s_or_b64 exec, exec, s[50:51]
	s_lshl_b32 s14, s58, 4
	s_sub_i32 s51, s18, s14
	s_min_i32 s50, s51, 16
	s_cmp_lt_i32 s51, 1
	s_cbranch_scc1 .LBB0_229
	s_cmp_lg_u32 s50, 16
	s_cbranch_scc1 .Lgdf_slow1
	v_add_u32_e32 v103, 0x9200, v2
	v_add_u32_e32 v100, 0x4800, v151
	v_add_u32_e32 v101, 0x4800, v150
	v_mov_b32_e32 v102, 0x100
	v_cndmask_b32_e64 v103, v149, v103, s[44:45]
	s_mov_b32 s51, 1
	s_branch .Lgdf_body
.Lgdf_slow1:
	ds_read_b128 v[36:39], v3 offset:37120
	ds_read_b128 v[68:71], v151 offset:18992
	s_waitcnt lgkmcnt(1)
	ds_read_b32 v39, v150 offset:19456
	ds_read_b128 v[40:43], v151 offset:18432
	ds_read_b128 v[44:47], v151 offset:18448
	ds_read_b128 v[48:51], v151 offset:18464
	ds_read_b128 v[64:67], v151 offset:18976
	ds_read_b128 v[60:63], v151 offset:18960
	ds_read_b128 v[52:55], v151 offset:18480
	ds_read_b128 v[56:59], v151 offset:18944
	s_mov_b32 s51, 0
	s_mov_b32 s52, 0x9110
	v_mov_b32_e32 v161, v158
	v_mov_b32_e32 v162, v157
	v_mov_b32_e32 v163, v2
	s_branch .LBB0_227

; #define SCAN_INTERLEAVE(nds, nvalu)                                   \
;   _Pragma("unroll") for (int i_ = 0; i_ < (nds); ++i_) {               \
;     __builtin_amdgcn_sched_group_barrier(0x100, 1, 0);                 \
;     __builtin_amdgcn_sched_group_barrier(0x002, (nvalu), 0);           \
;   }
; __device__ __forceinline__ void scan_ssm(const Params& p, int l, int seq, int h, char* smem, const unsigned* wflags, unsigned wexpect) {
;     ...
;     const int nsteps = min(16, T - c * 16);
;     const float* vb = vec + cur * 16 * 320;
;     const float* sb = scb + cur * 32;
;     SsRegs RA, RB;
;     float* ydummy = yb + 16 * 64 + tid * 2;
;     ss_load(RA, vb, sb, 0, n0, prow0);
;     for (int t = 0; t < nsteps; t += 2) {
;       ss_load(RB, vb, sb, min(t + 1, 15), n0, prow0);
;       const f32x2 y0v = ss_step(S, RA);
;       *(f32x2*)((part == 0) ? (yb + t * 64 + prow0) : ydummy) = y0v;
;       SCAN_INTERLEAVE(10, 5);
;       if (t + 1 < nsteps) {
;         ss_load(RA, vb, sb, min(t + 2, 15), n0, prow0);
;         const f32x2 y1v = ss_step(S, RB);
;         *(f32x2*)((part == 0) ? (yb + (t + 1) * 64 + prow0) : ydummy) = y1v;
;         SCAN_INTERLEAVE(10, 5);
;       }
;     }
.LBB0_643:
	s_or_b64 exec, exec, s[50:51]
	s_lshl_b32 s26, s14, 4
	s_sub_i32 s50, s18, s26
	s_min_i32 s27, s50, 16
	s_cmp_lt_i32 s50, 1
	s_cbranch_scc1 .LBB0_648
	s_cmp_lg_u32 s27, 16
	s_cbranch_scc1 .Lssf_slow0
	v_add_u32_e32 v119, 0xa100, v2
	v_mov_b32_e32 v116, v126
	v_mov_b32_e32 v117, v165
	v_mov_b32_e32 v118, 0
	v_cndmask_b32_e64 v119, v164, v119, s[44:45]
	s_mov_b32 s50, 0
	s_branch .Lssf_body
.Lssf_slow0:
	ds_read_b64 v[150:151], v3 offset:40960
	ds_read_b64 v[152:153], v165 offset:1024
	ds_read_b128 v[60:63], v126
	ds_read_b128 v[64:67], v126 offset:16
	ds_read_b128 v[68:71], v126 offset:32
	ds_read_b128 v[72:75], v126 offset:48
	ds_read_b128 v[88:91], v126 offset:560
	ds_read_b128 v[84:87], v126 offset:544
	ds_read_b128 v[80:83], v126 offset:528
	ds_read_b128 v[76:79], v126 offset:512
	s_mov_b32 s50, 0
	s_mov_b32 s51, 0xa008
	v_mov_b32_e32 v173, v170
	v_mov_b32_e32 v174, v169
	v_mov_b32_e32 v175, v2
	s_branch .LBB0_646

; #define SCAN_INTERLEAVE(nds, nvalu)                                   \
;   _Pragma("unroll") for (int i_ = 0; i_ < (nds); ++i_) {               \
;     __builtin_amdgcn_sched_group_barrier(0x100, 1, 0);                 \
;     __builtin_amdgcn_sched_group_barrier(0x002, (nvalu), 0);           \
;   }
; __device__ __forceinline__ void scan_ssm(const Params& p, int l, int seq, int h, char* smem, const unsigned* wflags, unsigned wexpect) {
;     ...
;     const int nsteps = min(16, T - c * 16);
;     const float* vb = vec + cur * 16 * 320;
;     const float* sb = scb + cur * 32;
;     SsRegs RA, RB;
;     float* ydummy = yb + 16 * 64 + tid * 2;
;     ss_load(RA, vb, sb, 0, n0, prow0);
;     for (int t = 0; t < nsteps; t += 2) {
;       ss_load(RB, vb, sb, min(t + 1, 15), n0, prow0);
;       const f32x2 y0v = ss_step(S, RA);
;       *(f32x2*)((part == 0) ? (yb + t * 64 + prow0) : ydummy) = y0v;
;       SCAN_INTERLEAVE(10, 5);
;       if (t + 1 < nsteps) {
;         ss_load(RA, vb, sb, min(t + 2, 15), n0, prow0);
;         const f32x2 y1v = ss_step(S, RB);
;         *(f32x2*)((part == 0) ? (yb + (t + 1) * 64 + prow0) : ydummy) = y1v;
;         SCAN_INTERLEAVE(10, 5);
;       }
;     }
.LBB0_679:
	s_or_b64 exec, exec, s[50:51]
	s_lshl_b32 s14, s26, 4
	s_sub_i32 s27, s18, s14
	s_min_i32 s26, s27, 16
	s_cmp_lt_i32 s27, 1
	s_cbranch_scc1 .LBB0_684
	s_cmp_lg_u32 s26, 16
	s_cbranch_scc1 .Lssf_slow1
	v_add_u32_e32 v119, 0xa100, v2
	v_add_u32_e32 v116, 0x5000, v126
	v_add_u32_e32 v117, 0x5000, v165
	v_mov_b32_e32 v118, 0x80
	v_cndmask_b32_e64 v119, v164, v119, s[44:45]
	s_mov_b32 s50, 1
	s_branch .Lssf_body
.Lssf_slow1:
	ds_read_b64 v[150:151], v3 offset:41088
	ds_read_b64 v[152:153], v165 offset:21504
	ds_read_b128 v[60:63], v126 offset:20480
	ds_read_b128 v[64:67], v126 offset:20496
	ds_read_b128 v[68:71], v126 offset:20512
	ds_read_b128 v[72:75], v126 offset:20528
	ds_read_b128 v[88:91], v126 offset:21040
	ds_read_b128 v[84:87], v126 offset:21024
	ds_read_b128 v[80:83], v126 offset:21008
	ds_read_b128 v[76:79], v126 offset:20992
	s_mov_b32 s27, 0
	s_mov_b32 s50, 0xa088
	v_mov_b32_e32 v173, v172
	v_mov_b32_e32 v174, v171
	v_mov_b32_e32 v175, v2
	s_branch .LBB0_682

; __device__ __forceinline__ float red8(float v) { v = red4(v); v += dppf<0x141>(v); return v; }
; __device__ __forceinline__ f32x2 lo2(const f32x4& v) { return __builtin_shufflevector(v, v, 0, 1); }
; __device__ __forceinline__ f32x2 hi2(const f32x4& v) { return __builtin_shufflevector(v, v, 2, 3); }
; __device__ __forceinline__ f32x2 splat2(float x) { return (f32x2){x, x}; }
; __device__ __forceinline__ void gd_load(GdRegs& R, const float* vb, const float* sb, int t, int k0, int cl) {
;   const float* vt = vb + t * 288;
; #pragma unroll
;   for (int q = 0; q < 4; ++q) {
;     R.q[q] = *(const f32x4*)(vt + k0 + q * 4);
;     R.k[q] = *(const f32x4*)(vt + 128 + k0 + q * 4);
;   }
;   R.v = vt[256 + cl];
;   R.sc = *(const f32x4*)(sb + t * 4);
; }
; __device__ __forceinline__ float gd_step(f32x2 (&S)[8], const GdRegs& R) {
;   f32x2 k0a = splat2(0.f), k1a = splat2(0.f), q0a = splat2(0.f), q1a = splat2(0.f);
; #pragma unroll
;   for (int q = 0; q < 4; ++q) {
;     k0a += S[2 * q] * lo2(R.k[q]);
;     k1a += S[2 * q + 1] * hi2(R.k[q]);
;     q0a += S[2 * q] * lo2(R.q[q]);
;     q1a += S[2 * q + 1] * hi2(R.q[q]);
;   }
;   k0a += k1a; q0a += q1a;
;   const float dK = red8(k0a.x + k0a.y), dQ = red8(q0a.x + q0a.y);
;   const float vn = R.sc.y * (R.v - R.sc.x * dK);
;   const float o = R.sc.x * dQ + R.sc.z * vn;
;   const f32x2 al2 = splat2(R.sc.x), vn2 = splat2(vn);
; #pragma unroll
;   for (int q = 0; q < 4; ++q) {
;     S[2 * q] = S[2 * q] * al2 + lo2(R.k[q]) * vn2;
;     S[2 * q + 1] = S[2 * q + 1] * al2 + hi2(R.k[q]) * vn2;
;   }
;   return o;
; }
; __device__ __forceinline__ void scan_gdn(const Params& p, int l, int seq, int h, int qt, char* smem, const unsigned* wflags, unsigned wexpect) {
;     ...
;     for (int t = 0; t < nsteps; t += 2) {
;       gd_load(RB, vb, sb, min(t + 1, 15), k0, cl);
;       const float o0v = gd_step(S, RA);
;       *((part == 0) ? (yb + t * 32 + cl) : ydummy) = o0v;
;       SCAN_INTERLEAVE(10, 4);
;       if (t + 1 < nsteps) {
;         gd_load(RA, vb, sb, min(t + 2, 15), k0, cl);
;         const float o1v = gd_step(S, RB);
;         *((part == 0) ? (yb + (t + 1) * 32 + cl) : ydummy) = o1v;
;         SCAN_INTERLEAVE(10, 4);
;       }
;     }
.Lgdf_body:
	ds_read_b32 v92, v101 offset:1024
	ds_read_b128 v[84:87], v102 offset:36864
	ds_read_b128 v[52:55], v100 offset:512
	ds_read_b128 v[36:39], v100 offset:0
	ds_read_b128 v[56:59], v100 offset:528
	ds_read_b128 v[40:43], v100 offset:16
	ds_read_b128 v[60:63], v100 offset:544
	ds_read_b128 v[44:47], v100 offset:32
	ds_read_b128 v[64:67], v100 offset:560
	ds_read_b128 v[48:51], v100 offset:48
	s_waitcnt lgkmcnt(6)
	v_pk_mul_f32 v[94:95], v[120:121], v[52:53]
	v_pk_mul_f32 v[96:97], v[120:121], v[36:37]
	v_pk_fma_f32 v[94:95], v[122:123], v[54:55], v[94:95]
	v_pk_fma_f32 v[96:97], v[122:123], v[38:39], v[96:97]
	v_pk_mul_f32 v[120:121], v[120:121], v[84:85] op_sel_hi:[1,0]
	ds_read_b128 v[68:71], v100 offset:1664
	s_waitcnt lgkmcnt(5)
	v_pk_fma_f32 v[94:95], v[124:125], v[56:57], v[94:95]
	v_pk_fma_f32 v[96:97], v[124:125], v[40:41], v[96:97]
	v_pk_mul_f32 v[122:123], v[122:123], v[84:85] op_sel_hi:[1,0]
	ds_read_b128 v[72:75], v100 offset:1680
	v_pk_fma_f32 v[94:95], v[126:127], v[58:59], v[94:95]
	v_pk_fma_f32 v[96:97], v[126:127], v[42:43], v[96:97]
	v_pk_mul_f32 v[124:125], v[124:125], v[84:85] op_sel_hi:[1,0]
	ds_read_b128 v[76:79], v100 offset:1696
	s_waitcnt lgkmcnt(5)
	v_pk_fma_f32 v[94:95], v[128:129], v[60:61], v[94:95]
	v_pk_fma_f32 v[96:97], v[128:129], v[44:45], v[96:97]
	v_pk_mul_f32 v[126:127], v[126:127], v[84:85] op_sel_hi:[1,0]
	ds_read_b128 v[80:83], v100 offset:1712
	v_pk_fma_f32 v[94:95], v[130:131], v[62:63], v[94:95]
	v_pk_fma_f32 v[96:97], v[130:131], v[46:47], v[96:97]
	v_pk_mul_f32 v[128:129], v[128:129], v[84:85] op_sel_hi:[1,0]
	ds_read_b32 v93, v101 offset:2176
	ds_read_b128 v[88:91], v102 offset:36880
	s_waitcnt lgkmcnt(6)
	v_pk_fma_f32 v[94:95], v[132:133], v[64:65], v[94:95]
	v_pk_fma_f32 v[96:97], v[132:133], v[48:49], v[96:97]
	v_pk_mul_f32 v[130:131], v[130:131], v[84:85] op_sel_hi:[1,0]
	v_pk_fma_f32 v[94:95], v[134:135], v[66:67], v[94:95]
	v_pk_fma_f32 v[96:97], v[134:135], v[50:51], v[96:97]
	v_pk_mul_f32 v[132:133], v[132:133], v[84:85] op_sel_hi:[1,0]
	v_pk_mul_f32 v[134:135], v[134:135], v[84:85] op_sel_hi:[1,0]
	v_add_f32_e32 v94, v94, v95
	v_add_f32_e32 v96, v96, v97
	ds_read_b128 v[36:39], v100 offset:1152
	v_add_f32_dpp v94, v94, v94 quad_perm:[1,0,3,2] row_mask:0xf bank_mask:0xf bound_ctrl:1
	v_add_f32_dpp v96, v96, v96 quad_perm:[1,0,3,2] row_mask:0xf bank_mask:0xf bound_ctrl:1
	ds_read_b128 v[40:43], v100 offset:1168
	v_add_f32_dpp v94, v94, v94 quad_perm:[2,3,0,1] row_mask:0xf bank_mask:0xf bound_ctrl:1
	v_add_f32_dpp v96, v96, v96 quad_perm:[2,3,0,1] row_mask:0xf bank_mask:0xf bound_ctrl:1
	ds_read_b128 v[44:47], v100 offset:1184
	v_add_f32_dpp v94, v94, v94 row_half_mirror row_mask:0xf bank_mask:0xf bound_ctrl:1
	v_add_f32_dpp v96, v96, v96 row_half_mirror row_mask:0xf bank_mask:0xf bound_ctrl:1
	v_fma_f32 v97, -v84, v94, v92
	v_pk_mul_f32 v[98:99], v[84:85], v[96:97]
	ds_read_b128 v[48:51], v100 offset:1200
	v_pk_fma_f32 v[120:121], v[52:53], v[98:99], v[120:121] op_sel:[0,1,0]
	v_pk_fma_f32 v[122:123], v[54:55], v[98:99], v[122:123] op_sel:[0,1,0]
	v_fmac_f32_e32 v98, v86, v99
	v_pk_fma_f32 v[124:125], v[56:57], v[98:99], v[124:125] op_sel:[0,1,0]
	v_pk_fma_f32 v[126:127], v[58:59], v[98:99], v[126:127] op_sel:[0,1,0]
	ds_write_b32 v103, v98 offset:0
	v_pk_fma_f32 v[128:129], v[60:61], v[98:99], v[128:129] op_sel:[0,1,0]
	v_pk_fma_f32 v[130:131], v[62:63], v[98:99], v[130:131] op_sel:[0,1,0]
	v_pk_fma_f32 v[132:133], v[64:65], v[98:99], v[132:133] op_sel:[0,1,0]
	v_pk_fma_f32 v[134:135], v[66:67], v[98:99], v[134:135] op_sel:[0,1,0]
	s_waitcnt lgkmcnt(4)
	v_pk_mul_f32 v[94:95], v[120:121], v[68:69]
	v_pk_mul_f32 v[96:97], v[120:121], v[36:37]
	v_pk_fma_f32 v[94:95], v[122:123], v[70:71], v[94:95]
	v_pk_fma_f32 v[96:97], v[122:123], v[38:39], v[96:97]
	v_pk_mul_f32 v[120:121], v[120:121], v[88:89] op_sel_hi:[1,0]
	ds_read_b128 v[52:55], v100 offset:2816
	s_waitcnt lgkmcnt(4)
	v_pk_fma_f32 v[94:95], v[124:125], v[72:73], v[94:95]
	v_pk_fma_f32 v[96:97], v[124:125], v[40:41], v[96:97]
	v_pk_mul_f32 v[122:123], v[122:123], v[88:89] op_sel_hi:[1,0]
	ds_read_b128 v[56:59], v100 offset:2832
	v_pk_fma_f32 v[94:95], v[126:127], v[74:75], v[94:95]
	v_pk_fma_f32 v[96:97], v[126:127], v[42:43], v[96:97]
	v_pk_mul_f32 v[124:125], v[124:125], v[88:89] op_sel_hi:[1,0]
	ds_read_b128 v[60:63], v100 offset:2848
	s_waitcnt lgkmcnt(5)
	v_pk_fma_f32 v[94:95], v[128:129], v[76:77], v[94:95]
	v_pk_fma_f32 v[96:97], v[128:129], v[44:45], v[96:97]
	v_pk_mul_f32 v[126:127], v[126:127], v[88:89] op_sel_hi:[1,0]
	ds_read_b128 v[64:67], v100 offset:2864
	v_pk_fma_f32 v[94:95], v[130:131], v[78:79], v[94:95]
	v_pk_fma_f32 v[96:97], v[130:131], v[46:47], v[96:97]
	v_pk_mul_f32 v[128:129], v[128:129], v[88:89] op_sel_hi:[1,0]
	ds_read_b32 v92, v101 offset:3328
	ds_read_b128 v[84:87], v102 offset:36896
	s_waitcnt lgkmcnt(7)
; __device__ __forceinline__ float red8(float v) { v = red4(v); v += dppf<0x141>(v); return v; }
; __device__ __forceinline__ f32x2 lo2(const f32x4& v) { return __builtin_shufflevector(v, v, 0, 1); }
; __device__ __forceinline__ f32x2 hi2(const f32x4& v) { return __builtin_shufflevector(v, v, 2, 3); }
; __device__ __forceinline__ f32x2 splat2(float x) { return (f32x2){x, x}; }
; __device__ __forceinline__ void gd_load(GdRegs& R, const float* vb, const float* sb, int t, int k0, int cl) {
;   const float* vt = vb + t * 288;
; #pragma unroll
;   for (int q = 0; q < 4; ++q) {
;     R.q[q] = *(const f32x4*)(vt + k0 + q * 4);
;     R.k[q] = *(const f32x4*)(vt + 128 + k0 + q * 4);
;   }
;   R.v = vt[256 + cl];
;   R.sc = *(const f32x4*)(sb + t * 4);
; }
; __device__ __forceinline__ float gd_step(f32x2 (&S)[8], const GdRegs& R) {
;   f32x2 k0a = splat2(0.f), k1a = splat2(0.f), q0a = splat2(0.f), q1a = splat2(0.f);
; #pragma unroll
;   for (int q = 0; q < 4; ++q) {
;     k0a += S[2 * q] * lo2(R.k[q]);
;     k1a += S[2 * q + 1] * hi2(R.k[q]);
;     q0a += S[2 * q] * lo2(R.q[q]);
;     q1a += S[2 * q + 1] * hi2(R.q[q]);
;   }
;   k0a += k1a; q0a += q1a;
;   const float dK = red8(k0a.x + k0a.y), dQ = red8(q0a.x + q0a.y);
;   const float vn = R.sc.y * (R.v - R.sc.x * dK);
;   const float o = R.sc.x * dQ + R.sc.z * vn;
;   const f32x2 al2 = splat2(R.sc.x), vn2 = splat2(vn);
; #pragma unroll
;   for (int q = 0; q < 4; ++q) {
;     S[2 * q] = S[2 * q] * al2 + lo2(R.k[q]) * vn2;
;     S[2 * q + 1] = S[2 * q + 1] * al2 + hi2(R.k[q]) * vn2;
;   }
;   return o;
; }
; __device__ __forceinline__ void scan_gdn(const Params& p, int l, int seq, int h, int qt, char* smem, const unsigned* wflags, unsigned wexpect) {
;     ...
;     for (int t = 0; t < nsteps; t += 2) {
;       gd_load(RB, vb, sb, min(t + 1, 15), k0, cl);
;       const float o0v = gd_step(S, RA);
;       *((part == 0) ? (yb + t * 32 + cl) : ydummy) = o0v;
;       SCAN_INTERLEAVE(10, 4);
;       if (t + 1 < nsteps) {
;         gd_load(RA, vb, sb, min(t + 2, 15), k0, cl);
;         const float o1v = gd_step(S, RB);
;         *((part == 0) ? (yb + (t + 1) * 32 + cl) : ydummy) = o1v;
;         SCAN_INTERLEAVE(10, 4);
;       }
;     }
	v_pk_fma_f32 v[94:95], v[132:133], v[80:81], v[94:95]
	v_pk_fma_f32 v[96:97], v[132:133], v[48:49], v[96:97]
	v_pk_mul_f32 v[130:131], v[130:131], v[88:89] op_sel_hi:[1,0]
	v_pk_fma_f32 v[94:95], v[134:135], v[82:83], v[94:95]
	v_pk_fma_f32 v[96:97], v[134:135], v[50:51], v[96:97]
	v_pk_mul_f32 v[132:133], v[132:133], v[88:89] op_sel_hi:[1,0]
	v_pk_mul_f32 v[134:135], v[134:135], v[88:89] op_sel_hi:[1,0]
	v_add_f32_e32 v94, v94, v95
	v_add_f32_e32 v96, v96, v97
	ds_read_b128 v[36:39], v100 offset:2304
	v_add_f32_dpp v94, v94, v94 quad_perm:[1,0,3,2] row_mask:0xf bank_mask:0xf bound_ctrl:1
	v_add_f32_dpp v96, v96, v96 quad_perm:[1,0,3,2] row_mask:0xf bank_mask:0xf bound_ctrl:1
	ds_read_b128 v[40:43], v100 offset:2320
	v_add_f32_dpp v94, v94, v94 quad_perm:[2,3,0,1] row_mask:0xf bank_mask:0xf bound_ctrl:1
	v_add_f32_dpp v96, v96, v96 quad_perm:[2,3,0,1] row_mask:0xf bank_mask:0xf bound_ctrl:1
	ds_read_b128 v[44:47], v100 offset:2336
	v_add_f32_dpp v94, v94, v94 row_half_mirror row_mask:0xf bank_mask:0xf bound_ctrl:1
	v_add_f32_dpp v96, v96, v96 row_half_mirror row_mask:0xf bank_mask:0xf bound_ctrl:1
	v_fma_f32 v97, -v88, v94, v93
	v_pk_mul_f32 v[98:99], v[88:89], v[96:97]
	ds_read_b128 v[48:51], v100 offset:2352
	v_pk_fma_f32 v[120:121], v[68:69], v[98:99], v[120:121] op_sel:[0,1,0]
	v_pk_fma_f32 v[122:123], v[70:71], v[98:99], v[122:123] op_sel:[0,1,0]
	v_fmac_f32_e32 v98, v90, v99
	v_pk_fma_f32 v[124:125], v[72:73], v[98:99], v[124:125] op_sel:[0,1,0]
	v_pk_fma_f32 v[126:127], v[74:75], v[98:99], v[126:127] op_sel:[0,1,0]
	ds_write_b32 v103, v98 offset:128
	v_pk_fma_f32 v[128:129], v[76:77], v[98:99], v[128:129] op_sel:[0,1,0]
	v_pk_fma_f32 v[130:131], v[78:79], v[98:99], v[130:131] op_sel:[0,1,0]
	v_pk_fma_f32 v[132:133], v[80:81], v[98:99], v[132:133] op_sel:[0,1,0]
	v_pk_fma_f32 v[134:135], v[82:83], v[98:99], v[134:135] op_sel:[0,1,0]
	s_waitcnt lgkmcnt(4)
	v_pk_mul_f32 v[94:95], v[120:121], v[52:53]
	v_pk_mul_f32 v[96:97], v[120:121], v[36:37]
	v_pk_fma_f32 v[94:95], v[122:123], v[54:55], v[94:95]
	v_pk_fma_f32 v[96:97], v[122:123], v[38:39], v[96:97]
	v_pk_mul_f32 v[120:121], v[120:121], v[84:85] op_sel_hi:[1,0]
	ds_read_b128 v[68:71], v100 offset:3968
	s_waitcnt lgkmcnt(4)
	v_pk_fma_f32 v[94:95], v[124:125], v[56:57], v[94:95]
	v_pk_fma_f32 v[96:97], v[124:125], v[40:41], v[96:97]
	v_pk_mul_f32 v[122:123], v[122:123], v[84:85] op_sel_hi:[1,0]
	ds_read_b128 v[72:75], v100 offset:3984
	v_pk_fma_f32 v[94:95], v[126:127], v[58:59], v[94:95]
	v_pk_fma_f32 v[96:97], v[126:127], v[42:43], v[96:97]
	v_pk_mul_f32 v[124:125], v[124:125], v[84:85] op_sel_hi:[1,0]
	ds_read_b128 v[76:79], v100 offset:4000
	s_waitcnt lgkmcnt(5)
	v_pk_fma_f32 v[94:95], v[128:129], v[60:61], v[94:95]
	v_pk_fma_f32 v[96:97], v[128:129], v[44:45], v[96:97]
	v_pk_mul_f32 v[126:127], v[126:127], v[84:85] op_sel_hi:[1,0]
	ds_read_b128 v[80:83], v100 offset:4016
	v_pk_fma_f32 v[94:95], v[130:131], v[62:63], v[94:95]
	v_pk_fma_f32 v[96:97], v[130:131], v[46:47], v[96:97]
	v_pk_mul_f32 v[128:129], v[128:129], v[84:85] op_sel_hi:[1,0]
	ds_read_b32 v93, v101 offset:4480
	ds_read_b128 v[88:91], v102 offset:36912
	s_waitcnt lgkmcnt(7)
	v_pk_fma_f32 v[94:95], v[132:133], v[64:65], v[94:95]
	v_pk_fma_f32 v[96:97], v[132:133], v[48:49], v[96:97]
	v_pk_mul_f32 v[130:131], v[130:131], v[84:85] op_sel_hi:[1,0]
	v_pk_fma_f32 v[94:95], v[134:135], v[66:67], v[94:95]
	v_pk_fma_f32 v[96:97], v[134:135], v[50:51], v[96:97]
	v_pk_mul_f32 v[132:133], v[132:133], v[84:85] op_sel_hi:[1,0]
	v_pk_mul_f32 v[134:135], v[134:135], v[84:85] op_sel_hi:[1,0]
	v_add_f32_e32 v94, v94, v95
	v_add_f32_e32 v96, v96, v97
	ds_read_b128 v[36:39], v100 offset:3456
	v_add_f32_dpp v94, v94, v94 quad_perm:[1,0,3,2] row_mask:0xf bank_mask:0xf bound_ctrl:1
	v_add_f32_dpp v96, v96, v96 quad_perm:[1,0,3,2] row_mask:0xf bank_mask:0xf bound_ctrl:1
	ds_read_b128 v[40:43], v100 offset:3472
	v_add_f32_dpp v94, v94, v94 quad_perm:[2,3,0,1] row_mask:0xf bank_mask:0xf bound_ctrl:1
	v_add_f32_dpp v96, v96, v96 quad_perm:[2,3,0,1] row_mask:0xf bank_mask:0xf bound_ctrl:1
	ds_read_b128 v[44:47], v100 offset:3488
	v_add_f32_dpp v94, v94, v94 row_half_mirror row_mask:0xf bank_mask:0xf bound_ctrl:1
	v_add_f32_dpp v96, v96, v96 row_half_mirror row_mask:0xf bank_mask:0xf bound_ctrl:1
	v_fma_f32 v97, -v84, v94, v92
	v_pk_mul_f32 v[98:99], v[84:85], v[96:97]
	ds_read_b128 v[48:51], v100 offset:3504
	v_pk_fma_f32 v[120:121], v[52:53], v[98:99], v[120:121] op_sel:[0,1,0]
	v_pk_fma_f32 v[122:123], v[54:55], v[98:99], v[122:123] op_sel:[0,1,0]
	v_fmac_f32_e32 v98, v86, v99
	v_pk_fma_f32 v[124:125], v[56:57], v[98:99], v[124:125] op_sel:[0,1,0]
	v_pk_fma_f32 v[126:127], v[58:59], v[98:99], v[126:127] op_sel:[0,1,0]
	ds_write_b32 v103, v98 offset:256
	v_pk_fma_f32 v[128:129], v[60:61], v[98:99], v[128:129] op_sel:[0,1,0]
	v_pk_fma_f32 v[130:131], v[62:63], v[98:99], v[130:131] op_sel:[0,1,0]
	v_pk_fma_f32 v[132:133], v[64:65], v[98:99], v[132:133] op_sel:[0,1,0]
	v_pk_fma_f32 v[134:135], v[66:67], v[98:99], v[134:135] op_sel:[0,1,0]
	s_waitcnt lgkmcnt(4)
	v_pk_mul_f32 v[94:95], v[120:121], v[68:69]
	v_pk_mul_f32 v[96:97], v[120:121], v[36:37]
	v_pk_fma_f32 v[94:95], v[122:123], v[70:71], v[94:95]
	v_pk_fma_f32 v[96:97], v[122:123], v[38:39], v[96:97]
	v_pk_mul_f32 v[120:121], v[120:121], v[88:89] op_sel_hi:[1,0]
	ds_read_b128 v[52:55], v100 offset:5120
	s_waitcnt lgkmcnt(4)
	v_pk_fma_f32 v[94:95], v[124:125], v[72:73], v[94:95]
	v_pk_fma_f32 v[96:97], v[124:125], v[40:41], v[96:97]
	v_pk_mul_f32 v[122:123], v[122:123], v[88:89] op_sel_hi:[1,0]
	ds_read_b128 v[56:59], v100 offset:5136
	v_pk_fma_f32 v[94:95], v[126:127], v[74:75], v[94:95]
	v_pk_fma_f32 v[96:97], v[126:127], v[42:43], v[96:97]
	v_pk_mul_f32 v[124:125], v[124:125], v[88:89] op_sel_hi:[1,0]
	ds_read_b128 v[60:63], v100 offset:5152
	s_waitcnt lgkmcnt(5)
; __device__ __forceinline__ float red8(float v) { v = red4(v); v += dppf<0x141>(v); return v; }
; __device__ __forceinline__ f32x2 lo2(const f32x4& v) { return __builtin_shufflevector(v, v, 0, 1); }
; __device__ __forceinline__ f32x2 hi2(const f32x4& v) { return __builtin_shufflevector(v, v, 2, 3); }
; __device__ __forceinline__ f32x2 splat2(float x) { return (f32x2){x, x}; }
; __device__ __forceinline__ void gd_load(GdRegs& R, const float* vb, const float* sb, int t, int k0, int cl) {
;   const float* vt = vb + t * 288;
; #pragma unroll
;   for (int q = 0; q < 4; ++q) {
;     R.q[q] = *(const f32x4*)(vt + k0 + q * 4);
;     R.k[q] = *(const f32x4*)(vt + 128 + k0 + q * 4);
;   }
;   R.v = vt[256 + cl];
;   R.sc = *(const f32x4*)(sb + t * 4);
; }
; __device__ __forceinline__ float gd_step(f32x2 (&S)[8], const GdRegs& R) {
;   f32x2 k0a = splat2(0.f), k1a = splat2(0.f), q0a = splat2(0.f), q1a = splat2(0.f);
; #pragma unroll
;   for (int q = 0; q < 4; ++q) {
;     k0a += S[2 * q] * lo2(R.k[q]);
;     k1a += S[2 * q + 1] * hi2(R.k[q]);
;     q0a += S[2 * q] * lo2(R.q[q]);
;     q1a += S[2 * q + 1] * hi2(R.q[q]);
;   }
;   k0a += k1a; q0a += q1a;
;   const float dK = red8(k0a.x + k0a.y), dQ = red8(q0a.x + q0a.y);
;   const float vn = R.sc.y * (R.v - R.sc.x * dK);
;   const float o = R.sc.x * dQ + R.sc.z * vn;
;   const f32x2 al2 = splat2(R.sc.x), vn2 = splat2(vn);
; #pragma unroll
;   for (int q = 0; q < 4; ++q) {
;     S[2 * q] = S[2 * q] * al2 + lo2(R.k[q]) * vn2;
;     S[2 * q + 1] = S[2 * q + 1] * al2 + hi2(R.k[q]) * vn2;
;   }
;   return o;
; }
; __device__ __forceinline__ void scan_gdn(const Params& p, int l, int seq, int h, int qt, char* smem, const unsigned* wflags, unsigned wexpect) {
;     ...
;     for (int t = 0; t < nsteps; t += 2) {
;       gd_load(RB, vb, sb, min(t + 1, 15), k0, cl);
;       const float o0v = gd_step(S, RA);
;       *((part == 0) ? (yb + t * 32 + cl) : ydummy) = o0v;
;       SCAN_INTERLEAVE(10, 4);
;       if (t + 1 < nsteps) {
;         gd_load(RA, vb, sb, min(t + 2, 15), k0, cl);
;         const float o1v = gd_step(S, RB);
;         *((part == 0) ? (yb + (t + 1) * 32 + cl) : ydummy) = o1v;
;         SCAN_INTERLEAVE(10, 4);
;       }
;     }
	v_pk_fma_f32 v[94:95], v[128:129], v[76:77], v[94:95]
	v_pk_fma_f32 v[96:97], v[128:129], v[44:45], v[96:97]
	v_pk_mul_f32 v[126:127], v[126:127], v[88:89] op_sel_hi:[1,0]
	ds_read_b128 v[64:67], v100 offset:5168
	v_pk_fma_f32 v[94:95], v[130:131], v[78:79], v[94:95]
	v_pk_fma_f32 v[96:97], v[130:131], v[46:47], v[96:97]
	v_pk_mul_f32 v[128:129], v[128:129], v[88:89] op_sel_hi:[1,0]
	ds_read_b32 v92, v101 offset:5632
	ds_read_b128 v[84:87], v102 offset:36928
	s_waitcnt lgkmcnt(7)
	v_pk_fma_f32 v[94:95], v[132:133], v[80:81], v[94:95]
	v_pk_fma_f32 v[96:97], v[132:133], v[48:49], v[96:97]
	v_pk_mul_f32 v[130:131], v[130:131], v[88:89] op_sel_hi:[1,0]
	v_pk_fma_f32 v[94:95], v[134:135], v[82:83], v[94:95]
	v_pk_fma_f32 v[96:97], v[134:135], v[50:51], v[96:97]
	v_pk_mul_f32 v[132:133], v[132:133], v[88:89] op_sel_hi:[1,0]
	v_pk_mul_f32 v[134:135], v[134:135], v[88:89] op_sel_hi:[1,0]
	v_add_f32_e32 v94, v94, v95
	v_add_f32_e32 v96, v96, v97
	ds_read_b128 v[36:39], v100 offset:4608
	v_add_f32_dpp v94, v94, v94 quad_perm:[1,0,3,2] row_mask:0xf bank_mask:0xf bound_ctrl:1
	v_add_f32_dpp v96, v96, v96 quad_perm:[1,0,3,2] row_mask:0xf bank_mask:0xf bound_ctrl:1
	ds_read_b128 v[40:43], v100 offset:4624
	v_add_f32_dpp v94, v94, v94 quad_perm:[2,3,0,1] row_mask:0xf bank_mask:0xf bound_ctrl:1
	v_add_f32_dpp v96, v96, v96 quad_perm:[2,3,0,1] row_mask:0xf bank_mask:0xf bound_ctrl:1
	ds_read_b128 v[44:47], v100 offset:4640
	v_add_f32_dpp v94, v94, v94 row_half_mirror row_mask:0xf bank_mask:0xf bound_ctrl:1
	v_add_f32_dpp v96, v96, v96 row_half_mirror row_mask:0xf bank_mask:0xf bound_ctrl:1
	v_fma_f32 v97, -v88, v94, v93
	v_pk_mul_f32 v[98:99], v[88:89], v[96:97]
	ds_read_b128 v[48:51], v100 offset:4656
	v_pk_fma_f32 v[120:121], v[68:69], v[98:99], v[120:121] op_sel:[0,1,0]
	v_pk_fma_f32 v[122:123], v[70:71], v[98:99], v[122:123] op_sel:[0,1,0]
	v_fmac_f32_e32 v98, v90, v99
	v_pk_fma_f32 v[124:125], v[72:73], v[98:99], v[124:125] op_sel:[0,1,0]
	v_pk_fma_f32 v[126:127], v[74:75], v[98:99], v[126:127] op_sel:[0,1,0]
	ds_write_b32 v103, v98 offset:384
	v_pk_fma_f32 v[128:129], v[76:77], v[98:99], v[128:129] op_sel:[0,1,0]
	v_pk_fma_f32 v[130:131], v[78:79], v[98:99], v[130:131] op_sel:[0,1,0]
	v_pk_fma_f32 v[132:133], v[80:81], v[98:99], v[132:133] op_sel:[0,1,0]
	v_pk_fma_f32 v[134:135], v[82:83], v[98:99], v[134:135] op_sel:[0,1,0]
	s_waitcnt lgkmcnt(4)
	v_pk_mul_f32 v[94:95], v[120:121], v[52:53]
	v_pk_mul_f32 v[96:97], v[120:121], v[36:37]
	v_pk_fma_f32 v[94:95], v[122:123], v[54:55], v[94:95]
	v_pk_fma_f32 v[96:97], v[122:123], v[38:39], v[96:97]
	v_pk_mul_f32 v[120:121], v[120:121], v[84:85] op_sel_hi:[1,0]
	ds_read_b128 v[68:71], v100 offset:6272
	s_waitcnt lgkmcnt(4)
	v_pk_fma_f32 v[94:95], v[124:125], v[56:57], v[94:95]
	v_pk_fma_f32 v[96:97], v[124:125], v[40:41], v[96:97]
	v_pk_mul_f32 v[122:123], v[122:123], v[84:85] op_sel_hi:[1,0]
	ds_read_b128 v[72:75], v100 offset:6288
	v_pk_fma_f32 v[94:95], v[126:127], v[58:59], v[94:95]
	v_pk_fma_f32 v[96:97], v[126:127], v[42:43], v[96:97]
	v_pk_mul_f32 v[124:125], v[124:125], v[84:85] op_sel_hi:[1,0]
	ds_read_b128 v[76:79], v100 offset:6304
	s_waitcnt lgkmcnt(5)
	v_pk_fma_f32 v[94:95], v[128:129], v[60:61], v[94:95]
	v_pk_fma_f32 v[96:97], v[128:129], v[44:45], v[96:97]
	v_pk_mul_f32 v[126:127], v[126:127], v[84:85] op_sel_hi:[1,0]
	ds_read_b128 v[80:83], v100 offset:6320
	v_pk_fma_f32 v[94:95], v[130:131], v[62:63], v[94:95]
	v_pk_fma_f32 v[96:97], v[130:131], v[46:47], v[96:97]
	v_pk_mul_f32 v[128:129], v[128:129], v[84:85] op_sel_hi:[1,0]
	ds_read_b32 v93, v101 offset:6784
	ds_read_b128 v[88:91], v102 offset:36944
	s_waitcnt lgkmcnt(7)
	v_pk_fma_f32 v[94:95], v[132:133], v[64:65], v[94:95]
	v_pk_fma_f32 v[96:97], v[132:133], v[48:49], v[96:97]
	v_pk_mul_f32 v[130:131], v[130:131], v[84:85] op_sel_hi:[1,0]
	v_pk_fma_f32 v[94:95], v[134:135], v[66:67], v[94:95]
	v_pk_fma_f32 v[96:97], v[134:135], v[50:51], v[96:97]
	v_pk_mul_f32 v[132:133], v[132:133], v[84:85] op_sel_hi:[1,0]
	v_pk_mul_f32 v[134:135], v[134:135], v[84:85] op_sel_hi:[1,0]
	v_add_f32_e32 v94, v94, v95
	v_add_f32_e32 v96, v96, v97
	ds_read_b128 v[36:39], v100 offset:5760
	v_add_f32_dpp v94, v94, v94 quad_perm:[1,0,3,2] row_mask:0xf bank_mask:0xf bound_ctrl:1
	v_add_f32_dpp v96, v96, v96 quad_perm:[1,0,3,2] row_mask:0xf bank_mask:0xf bound_ctrl:1
	ds_read_b128 v[40:43], v100 offset:5776
	v_add_f32_dpp v94, v94, v94 quad_perm:[2,3,0,1] row_mask:0xf bank_mask:0xf bound_ctrl:1
	v_add_f32_dpp v96, v96, v96 quad_perm:[2,3,0,1] row_mask:0xf bank_mask:0xf bound_ctrl:1
	ds_read_b128 v[44:47], v100 offset:5792
	v_add_f32_dpp v94, v94, v94 row_half_mirror row_mask:0xf bank_mask:0xf bound_ctrl:1
	v_add_f32_dpp v96, v96, v96 row_half_mirror row_mask:0xf bank_mask:0xf bound_ctrl:1
	v_fma_f32 v97, -v84, v94, v92
	v_pk_mul_f32 v[98:99], v[84:85], v[96:97]
	ds_read_b128 v[48:51], v100 offset:5808
	v_pk_fma_f32 v[120:121], v[52:53], v[98:99], v[120:121] op_sel:[0,1,0]
	v_pk_fma_f32 v[122:123], v[54:55], v[98:99], v[122:123] op_sel:[0,1,0]
	v_fmac_f32_e32 v98, v86, v99
	v_pk_fma_f32 v[124:125], v[56:57], v[98:99], v[124:125] op_sel:[0,1,0]
	v_pk_fma_f32 v[126:127], v[58:59], v[98:99], v[126:127] op_sel:[0,1,0]
	ds_write_b32 v103, v98 offset:512
	v_pk_fma_f32 v[128:129], v[60:61], v[98:99], v[128:129] op_sel:[0,1,0]
	v_pk_fma_f32 v[130:131], v[62:63], v[98:99], v[130:131] op_sel:[0,1,0]
	v_pk_fma_f32 v[132:133], v[64:65], v[98:99], v[132:133] op_sel:[0,1,0]
	v_pk_fma_f32 v[134:135], v[66:67], v[98:99], v[134:135] op_sel:[0,1,0]
	s_waitcnt lgkmcnt(4)
; __device__ __forceinline__ float red8(float v) { v = red4(v); v += dppf<0x141>(v); return v; }
; __device__ __forceinline__ f32x2 lo2(const f32x4& v) { return __builtin_shufflevector(v, v, 0, 1); }
; __device__ __forceinline__ f32x2 hi2(const f32x4& v) { return __builtin_shufflevector(v, v, 2, 3); }
; __device__ __forceinline__ f32x2 splat2(float x) { return (f32x2){x, x}; }
; __device__ __forceinline__ void gd_load(GdRegs& R, const float* vb, const float* sb, int t, int k0, int cl) {
;   const float* vt = vb + t * 288;
; #pragma unroll
;   for (int q = 0; q < 4; ++q) {
;     R.q[q] = *(const f32x4*)(vt + k0 + q * 4);
;     R.k[q] = *(const f32x4*)(vt + 128 + k0 + q * 4);
;   }
;   R.v = vt[256 + cl];
;   R.sc = *(const f32x4*)(sb + t * 4);
; }
; __device__ __forceinline__ float gd_step(f32x2 (&S)[8], const GdRegs& R) {
;   f32x2 k0a = splat2(0.f), k1a = splat2(0.f), q0a = splat2(0.f), q1a = splat2(0.f);
; #pragma unroll
;   for (int q = 0; q < 4; ++q) {
;     k0a += S[2 * q] * lo2(R.k[q]);
;     k1a += S[2 * q + 1] * hi2(R.k[q]);
;     q0a += S[2 * q] * lo2(R.q[q]);
;     q1a += S[2 * q + 1] * hi2(R.q[q]);
;   }
;   k0a += k1a; q0a += q1a;
;   const float dK = red8(k0a.x + k0a.y), dQ = red8(q0a.x + q0a.y);
;   const float vn = R.sc.y * (R.v - R.sc.x * dK);
;   const float o = R.sc.x * dQ + R.sc.z * vn;
;   const f32x2 al2 = splat2(R.sc.x), vn2 = splat2(vn);
; #pragma unroll
;   for (int q = 0; q < 4; ++q) {
;     S[2 * q] = S[2 * q] * al2 + lo2(R.k[q]) * vn2;
;     S[2 * q + 1] = S[2 * q + 1] * al2 + hi2(R.k[q]) * vn2;
;   }
;   return o;
; }
; __device__ __forceinline__ void scan_gdn(const Params& p, int l, int seq, int h, int qt, char* smem, const unsigned* wflags, unsigned wexpect) {
;     ...
;     for (int t = 0; t < nsteps; t += 2) {
;       gd_load(RB, vb, sb, min(t + 1, 15), k0, cl);
;       const float o0v = gd_step(S, RA);
;       *((part == 0) ? (yb + t * 32 + cl) : ydummy) = o0v;
;       SCAN_INTERLEAVE(10, 4);
;       if (t + 1 < nsteps) {
;         gd_load(RA, vb, sb, min(t + 2, 15), k0, cl);
;         const float o1v = gd_step(S, RB);
;         *((part == 0) ? (yb + (t + 1) * 32 + cl) : ydummy) = o1v;
;         SCAN_INTERLEAVE(10, 4);
;       }
;     }
	v_pk_mul_f32 v[94:95], v[120:121], v[68:69]
	v_pk_mul_f32 v[96:97], v[120:121], v[36:37]
	v_pk_fma_f32 v[94:95], v[122:123], v[70:71], v[94:95]
	v_pk_fma_f32 v[96:97], v[122:123], v[38:39], v[96:97]
	v_pk_mul_f32 v[120:121], v[120:121], v[88:89] op_sel_hi:[1,0]
	ds_read_b128 v[52:55], v100 offset:7424
	s_waitcnt lgkmcnt(4)
	v_pk_fma_f32 v[94:95], v[124:125], v[72:73], v[94:95]
	v_pk_fma_f32 v[96:97], v[124:125], v[40:41], v[96:97]
	v_pk_mul_f32 v[122:123], v[122:123], v[88:89] op_sel_hi:[1,0]
	ds_read_b128 v[56:59], v100 offset:7440
	v_pk_fma_f32 v[94:95], v[126:127], v[74:75], v[94:95]
	v_pk_fma_f32 v[96:97], v[126:127], v[42:43], v[96:97]
	v_pk_mul_f32 v[124:125], v[124:125], v[88:89] op_sel_hi:[1,0]
	ds_read_b128 v[60:63], v100 offset:7456
	s_waitcnt lgkmcnt(5)
	v_pk_fma_f32 v[94:95], v[128:129], v[76:77], v[94:95]
	v_pk_fma_f32 v[96:97], v[128:129], v[44:45], v[96:97]
	v_pk_mul_f32 v[126:127], v[126:127], v[88:89] op_sel_hi:[1,0]
	ds_read_b128 v[64:67], v100 offset:7472
	v_pk_fma_f32 v[94:95], v[130:131], v[78:79], v[94:95]
	v_pk_fma_f32 v[96:97], v[130:131], v[46:47], v[96:97]
	v_pk_mul_f32 v[128:129], v[128:129], v[88:89] op_sel_hi:[1,0]
	ds_read_b32 v92, v101 offset:7936
	ds_read_b128 v[84:87], v102 offset:36960
	s_waitcnt lgkmcnt(7)
	v_pk_fma_f32 v[94:95], v[132:133], v[80:81], v[94:95]
	v_pk_fma_f32 v[96:97], v[132:133], v[48:49], v[96:97]
	v_pk_mul_f32 v[130:131], v[130:131], v[88:89] op_sel_hi:[1,0]
	v_pk_fma_f32 v[94:95], v[134:135], v[82:83], v[94:95]
	v_pk_fma_f32 v[96:97], v[134:135], v[50:51], v[96:97]
	v_pk_mul_f32 v[132:133], v[132:133], v[88:89] op_sel_hi:[1,0]
	v_pk_mul_f32 v[134:135], v[134:135], v[88:89] op_sel_hi:[1,0]
	v_add_f32_e32 v94, v94, v95
	v_add_f32_e32 v96, v96, v97
	ds_read_b128 v[36:39], v100 offset:6912
	v_add_f32_dpp v94, v94, v94 quad_perm:[1,0,3,2] row_mask:0xf bank_mask:0xf bound_ctrl:1
	v_add_f32_dpp v96, v96, v96 quad_perm:[1,0,3,2] row_mask:0xf bank_mask:0xf bound_ctrl:1
	ds_read_b128 v[40:43], v100 offset:6928
	v_add_f32_dpp v94, v94, v94 quad_perm:[2,3,0,1] row_mask:0xf bank_mask:0xf bound_ctrl:1
	v_add_f32_dpp v96, v96, v96 quad_perm:[2,3,0,1] row_mask:0xf bank_mask:0xf bound_ctrl:1
	ds_read_b128 v[44:47], v100 offset:6944
	v_add_f32_dpp v94, v94, v94 row_half_mirror row_mask:0xf bank_mask:0xf bound_ctrl:1
	v_add_f32_dpp v96, v96, v96 row_half_mirror row_mask:0xf bank_mask:0xf bound_ctrl:1
	v_fma_f32 v97, -v88, v94, v93
	v_pk_mul_f32 v[98:99], v[88:89], v[96:97]
	ds_read_b128 v[48:51], v100 offset:6960
	v_pk_fma_f32 v[120:121], v[68:69], v[98:99], v[120:121] op_sel:[0,1,0]
	v_pk_fma_f32 v[122:123], v[70:71], v[98:99], v[122:123] op_sel:[0,1,0]
	v_fmac_f32_e32 v98, v90, v99
	v_pk_fma_f32 v[124:125], v[72:73], v[98:99], v[124:125] op_sel:[0,1,0]
	v_pk_fma_f32 v[126:127], v[74:75], v[98:99], v[126:127] op_sel:[0,1,0]
	ds_write_b32 v103, v98 offset:640
	v_pk_fma_f32 v[128:129], v[76:77], v[98:99], v[128:129] op_sel:[0,1,0]
	v_pk_fma_f32 v[130:131], v[78:79], v[98:99], v[130:131] op_sel:[0,1,0]
	v_pk_fma_f32 v[132:133], v[80:81], v[98:99], v[132:133] op_sel:[0,1,0]
	v_pk_fma_f32 v[134:135], v[82:83], v[98:99], v[134:135] op_sel:[0,1,0]
	s_waitcnt lgkmcnt(4)
	v_pk_mul_f32 v[94:95], v[120:121], v[52:53]
	v_pk_mul_f32 v[96:97], v[120:121], v[36:37]
	v_pk_fma_f32 v[94:95], v[122:123], v[54:55], v[94:95]
	v_pk_fma_f32 v[96:97], v[122:123], v[38:39], v[96:97]
	v_pk_mul_f32 v[120:121], v[120:121], v[84:85] op_sel_hi:[1,0]
	ds_read_b128 v[68:71], v100 offset:8576
	s_waitcnt lgkmcnt(4)
	v_pk_fma_f32 v[94:95], v[124:125], v[56:57], v[94:95]
	v_pk_fma_f32 v[96:97], v[124:125], v[40:41], v[96:97]
	v_pk_mul_f32 v[122:123], v[122:123], v[84:85] op_sel_hi:[1,0]
	ds_read_b128 v[72:75], v100 offset:8592
	v_pk_fma_f32 v[94:95], v[126:127], v[58:59], v[94:95]
	v_pk_fma_f32 v[96:97], v[126:127], v[42:43], v[96:97]
	v_pk_mul_f32 v[124:125], v[124:125], v[84:85] op_sel_hi:[1,0]
	ds_read_b128 v[76:79], v100 offset:8608
	s_waitcnt lgkmcnt(5)
	v_pk_fma_f32 v[94:95], v[128:129], v[60:61], v[94:95]
	v_pk_fma_f32 v[96:97], v[128:129], v[44:45], v[96:97]
	v_pk_mul_f32 v[126:127], v[126:127], v[84:85] op_sel_hi:[1,0]
	ds_read_b128 v[80:83], v100 offset:8624
	v_pk_fma_f32 v[94:95], v[130:131], v[62:63], v[94:95]
	v_pk_fma_f32 v[96:97], v[130:131], v[46:47], v[96:97]
	v_pk_mul_f32 v[128:129], v[128:129], v[84:85] op_sel_hi:[1,0]
	ds_read_b32 v93, v101 offset:9088
	ds_read_b128 v[88:91], v102 offset:36976
	s_waitcnt lgkmcnt(7)
	v_pk_fma_f32 v[94:95], v[132:133], v[64:65], v[94:95]
	v_pk_fma_f32 v[96:97], v[132:133], v[48:49], v[96:97]
	v_pk_mul_f32 v[130:131], v[130:131], v[84:85] op_sel_hi:[1,0]
	v_pk_fma_f32 v[94:95], v[134:135], v[66:67], v[94:95]
	v_pk_fma_f32 v[96:97], v[134:135], v[50:51], v[96:97]
	v_pk_mul_f32 v[132:133], v[132:133], v[84:85] op_sel_hi:[1,0]
	v_pk_mul_f32 v[134:135], v[134:135], v[84:85] op_sel_hi:[1,0]
	v_add_f32_e32 v94, v94, v95
	v_add_f32_e32 v96, v96, v97
	ds_read_b128 v[36:39], v100 offset:8064
	v_add_f32_dpp v94, v94, v94 quad_perm:[1,0,3,2] row_mask:0xf bank_mask:0xf bound_ctrl:1
	v_add_f32_dpp v96, v96, v96 quad_perm:[1,0,3,2] row_mask:0xf bank_mask:0xf bound_ctrl:1
	ds_read_b128 v[40:43], v100 offset:8080
	v_add_f32_dpp v94, v94, v94 quad_perm:[2,3,0,1] row_mask:0xf bank_mask:0xf bound_ctrl:1
	v_add_f32_dpp v96, v96, v96 quad_perm:[2,3,0,1] row_mask:0xf bank_mask:0xf bound_ctrl:1
	ds_read_b128 v[44:47], v100 offset:8096
	v_add_f32_dpp v94, v94, v94 row_half_mirror row_mask:0xf bank_mask:0xf bound_ctrl:1
	v_add_f32_dpp v96, v96, v96 row_half_mirror row_mask:0xf bank_mask:0xf bound_ctrl:1
	v_fma_f32 v97, -v84, v94, v92
	v_pk_mul_f32 v[98:99], v[84:85], v[96:97]
	ds_read_b128 v[48:51], v100 offset:8112
	v_pk_fma_f32 v[120:121], v[52:53], v[98:99], v[120:121] op_sel:[0,1,0]
	v_pk_fma_f32 v[122:123], v[54:55], v[98:99], v[122:123] op_sel:[0,1,0]
	v_fmac_f32_e32 v98, v86, v99
	v_pk_fma_f32 v[124:125], v[56:57], v[98:99], v[124:125] op_sel:[0,1,0]
	v_pk_fma_f32 v[126:127], v[58:59], v[98:99], v[126:127] op_sel:[0,1,0]
	ds_write_b32 v103, v98 offset:768
	v_pk_fma_f32 v[128:129], v[60:61], v[98:99], v[128:129] op_sel:[0,1,0]
	v_pk_fma_f32 v[130:131], v[62:63], v[98:99], v[130:131] op_sel:[0,1,0]
	v_pk_fma_f32 v[132:133], v[64:65], v[98:99], v[132:133] op_sel:[0,1,0]
	v_pk_fma_f32 v[134:135], v[66:67], v[98:99], v[134:135] op_sel:[0,1,0]
	s_waitcnt lgkmcnt(4)
; __device__ __forceinline__ float red8(float v) { v = red4(v); v += dppf<0x141>(v); return v; }
; __device__ __forceinline__ f32x2 lo2(const f32x4& v) { return __builtin_shufflevector(v, v, 0, 1); }
; __device__ __forceinline__ f32x2 hi2(const f32x4& v) { return __builtin_shufflevector(v, v, 2, 3); }
; __device__ __forceinline__ f32x2 splat2(float x) { return (f32x2){x, x}; }
; __device__ __forceinline__ void gd_load(GdRegs& R, const float* vb, const float* sb, int t, int k0, int cl) {
;   const float* vt = vb + t * 288;
; #pragma unroll
;   for (int q = 0; q < 4; ++q) {
;     R.q[q] = *(const f32x4*)(vt + k0 + q * 4);
;     R.k[q] = *(const f32x4*)(vt + 128 + k0 + q * 4);
;   }
;   R.v = vt[256 + cl];
;   R.sc = *(const f32x4*)(sb + t * 4);
; }
; __device__ __forceinline__ float gd_step(f32x2 (&S)[8], const GdRegs& R) {
;   f32x2 k0a = splat2(0.f), k1a = splat2(0.f), q0a = splat2(0.f), q1a = splat2(0.f);
; #pragma unroll
;   for (int q = 0; q < 4; ++q) {
;     k0a += S[2 * q] * lo2(R.k[q]);
;     k1a += S[2 * q + 1] * hi2(R.k[q]);
;     q0a += S[2 * q] * lo2(R.q[q]);
;     q1a += S[2 * q + 1] * hi2(R.q[q]);
;   }
;   k0a += k1a; q0a += q1a;
;   const float dK = red8(k0a.x + k0a.y), dQ = red8(q0a.x + q0a.y);
;   const float vn = R.sc.y * (R.v - R.sc.x * dK);
;   const float o = R.sc.x * dQ + R.sc.z * vn;
;   const f32x2 al2 = splat2(R.sc.x), vn2 = splat2(vn);
; #pragma unroll
;   for (int q = 0; q < 4; ++q) {
;     S[2 * q] = S[2 * q] * al2 + lo2(R.k[q]) * vn2;
;     S[2 * q + 1] = S[2 * q + 1] * al2 + hi2(R.k[q]) * vn2;
;   }
;   return o;
; }
; __device__ __forceinline__ void scan_gdn(const Params& p, int l, int seq, int h, int qt, char* smem, const unsigned* wflags, unsigned wexpect) {
;     ...
;     for (int t = 0; t < nsteps; t += 2) {
;       gd_load(RB, vb, sb, min(t + 1, 15), k0, cl);
;       const float o0v = gd_step(S, RA);
;       *((part == 0) ? (yb + t * 32 + cl) : ydummy) = o0v;
;       SCAN_INTERLEAVE(10, 4);
;       if (t + 1 < nsteps) {
;         gd_load(RA, vb, sb, min(t + 2, 15), k0, cl);
;         const float o1v = gd_step(S, RB);
;         *((part == 0) ? (yb + (t + 1) * 32 + cl) : ydummy) = o1v;
;         SCAN_INTERLEAVE(10, 4);
;       }
;     }
	v_pk_mul_f32 v[94:95], v[120:121], v[68:69]
	v_pk_mul_f32 v[96:97], v[120:121], v[36:37]
	v_pk_fma_f32 v[94:95], v[122:123], v[70:71], v[94:95]
	v_pk_fma_f32 v[96:97], v[122:123], v[38:39], v[96:97]
	v_pk_mul_f32 v[120:121], v[120:121], v[88:89] op_sel_hi:[1,0]
	ds_read_b128 v[52:55], v100 offset:9728
	s_waitcnt lgkmcnt(4)
	v_pk_fma_f32 v[94:95], v[124:125], v[72:73], v[94:95]
	v_pk_fma_f32 v[96:97], v[124:125], v[40:41], v[96:97]
	v_pk_mul_f32 v[122:123], v[122:123], v[88:89] op_sel_hi:[1,0]
	ds_read_b128 v[56:59], v100 offset:9744
	v_pk_fma_f32 v[94:95], v[126:127], v[74:75], v[94:95]
	v_pk_fma_f32 v[96:97], v[126:127], v[42:43], v[96:97]
	v_pk_mul_f32 v[124:125], v[124:125], v[88:89] op_sel_hi:[1,0]
	ds_read_b128 v[60:63], v100 offset:9760
	s_waitcnt lgkmcnt(5)
	v_pk_fma_f32 v[94:95], v[128:129], v[76:77], v[94:95]
	v_pk_fma_f32 v[96:97], v[128:129], v[44:45], v[96:97]
	v_pk_mul_f32 v[126:127], v[126:127], v[88:89] op_sel_hi:[1,0]
	ds_read_b128 v[64:67], v100 offset:9776
	v_pk_fma_f32 v[94:95], v[130:131], v[78:79], v[94:95]
	v_pk_fma_f32 v[96:97], v[130:131], v[46:47], v[96:97]
	v_pk_mul_f32 v[128:129], v[128:129], v[88:89] op_sel_hi:[1,0]
	ds_read_b32 v92, v101 offset:10240
	ds_read_b128 v[84:87], v102 offset:36992
	s_waitcnt lgkmcnt(7)
	v_pk_fma_f32 v[94:95], v[132:133], v[80:81], v[94:95]
	v_pk_fma_f32 v[96:97], v[132:133], v[48:49], v[96:97]
	v_pk_mul_f32 v[130:131], v[130:131], v[88:89] op_sel_hi:[1,0]
	v_pk_fma_f32 v[94:95], v[134:135], v[82:83], v[94:95]
	v_pk_fma_f32 v[96:97], v[134:135], v[50:51], v[96:97]
	v_pk_mul_f32 v[132:133], v[132:133], v[88:89] op_sel_hi:[1,0]
	v_pk_mul_f32 v[134:135], v[134:135], v[88:89] op_sel_hi:[1,0]
	v_add_f32_e32 v94, v94, v95
	v_add_f32_e32 v96, v96, v97
	ds_read_b128 v[36:39], v100 offset:9216
	v_add_f32_dpp v94, v94, v94 quad_perm:[1,0,3,2] row_mask:0xf bank_mask:0xf bound_ctrl:1
	v_add_f32_dpp v96, v96, v96 quad_perm:[1,0,3,2] row_mask:0xf bank_mask:0xf bound_ctrl:1
	ds_read_b128 v[40:43], v100 offset:9232
	v_add_f32_dpp v94, v94, v94 quad_perm:[2,3,0,1] row_mask:0xf bank_mask:0xf bound_ctrl:1
	v_add_f32_dpp v96, v96, v96 quad_perm:[2,3,0,1] row_mask:0xf bank_mask:0xf bound_ctrl:1
	ds_read_b128 v[44:47], v100 offset:9248
	v_add_f32_dpp v94, v94, v94 row_half_mirror row_mask:0xf bank_mask:0xf bound_ctrl:1
	v_add_f32_dpp v96, v96, v96 row_half_mirror row_mask:0xf bank_mask:0xf bound_ctrl:1
	v_fma_f32 v97, -v88, v94, v93
	v_pk_mul_f32 v[98:99], v[88:89], v[96:97]
	ds_read_b128 v[48:51], v100 offset:9264
	v_pk_fma_f32 v[120:121], v[68:69], v[98:99], v[120:121] op_sel:[0,1,0]
	v_pk_fma_f32 v[122:123], v[70:71], v[98:99], v[122:123] op_sel:[0,1,0]
	v_fmac_f32_e32 v98, v90, v99
	v_pk_fma_f32 v[124:125], v[72:73], v[98:99], v[124:125] op_sel:[0,1,0]
	v_pk_fma_f32 v[126:127], v[74:75], v[98:99], v[126:127] op_sel:[0,1,0]
	ds_write_b32 v103, v98 offset:896
	v_pk_fma_f32 v[128:129], v[76:77], v[98:99], v[128:129] op_sel:[0,1,0]
	v_pk_fma_f32 v[130:131], v[78:79], v[98:99], v[130:131] op_sel:[0,1,0]
	v_pk_fma_f32 v[132:133], v[80:81], v[98:99], v[132:133] op_sel:[0,1,0]
	v_pk_fma_f32 v[134:135], v[82:83], v[98:99], v[134:135] op_sel:[0,1,0]
	s_waitcnt lgkmcnt(4)
	v_pk_mul_f32 v[94:95], v[120:121], v[52:53]
	v_pk_mul_f32 v[96:97], v[120:121], v[36:37]
	v_pk_fma_f32 v[94:95], v[122:123], v[54:55], v[94:95]
	v_pk_fma_f32 v[96:97], v[122:123], v[38:39], v[96:97]
	v_pk_mul_f32 v[120:121], v[120:121], v[84:85] op_sel_hi:[1,0]
	ds_read_b128 v[68:71], v100 offset:10880
	s_waitcnt lgkmcnt(4)
	v_pk_fma_f32 v[94:95], v[124:125], v[56:57], v[94:95]
	v_pk_fma_f32 v[96:97], v[124:125], v[40:41], v[96:97]
	v_pk_mul_f32 v[122:123], v[122:123], v[84:85] op_sel_hi:[1,0]
	ds_read_b128 v[72:75], v100 offset:10896
	v_pk_fma_f32 v[94:95], v[126:127], v[58:59], v[94:95]
	v_pk_fma_f32 v[96:97], v[126:127], v[42:43], v[96:97]
	v_pk_mul_f32 v[124:125], v[124:125], v[84:85] op_sel_hi:[1,0]
	ds_read_b128 v[76:79], v100 offset:10912
	s_waitcnt lgkmcnt(5)
	v_pk_fma_f32 v[94:95], v[128:129], v[60:61], v[94:95]
	v_pk_fma_f32 v[96:97], v[128:129], v[44:45], v[96:97]
	v_pk_mul_f32 v[126:127], v[126:127], v[84:85] op_sel_hi:[1,0]
	ds_read_b128 v[80:83], v100 offset:10928
	v_pk_fma_f32 v[94:95], v[130:131], v[62:63], v[94:95]
	v_pk_fma_f32 v[96:97], v[130:131], v[46:47], v[96:97]
	v_pk_mul_f32 v[128:129], v[128:129], v[84:85] op_sel_hi:[1,0]
	ds_read_b32 v93, v101 offset:11392
	ds_read_b128 v[88:91], v102 offset:37008
	s_waitcnt lgkmcnt(7)
	v_pk_fma_f32 v[94:95], v[132:133], v[64:65], v[94:95]
	v_pk_fma_f32 v[96:97], v[132:133], v[48:49], v[96:97]
	v_pk_mul_f32 v[130:131], v[130:131], v[84:85] op_sel_hi:[1,0]
	v_pk_fma_f32 v[94:95], v[134:135], v[66:67], v[94:95]
	v_pk_fma_f32 v[96:97], v[134:135], v[50:51], v[96:97]
	v_pk_mul_f32 v[132:133], v[132:133], v[84:85] op_sel_hi:[1,0]
	v_pk_mul_f32 v[134:135], v[134:135], v[84:85] op_sel_hi:[1,0]
	v_add_f32_e32 v94, v94, v95
	v_add_f32_e32 v96, v96, v97
	ds_read_b128 v[36:39], v100 offset:10368
	v_add_f32_dpp v94, v94, v94 quad_perm:[1,0,3,2] row_mask:0xf bank_mask:0xf bound_ctrl:1
	v_add_f32_dpp v96, v96, v96 quad_perm:[1,0,3,2] row_mask:0xf bank_mask:0xf bound_ctrl:1
	ds_read_b128 v[40:43], v100 offset:10384
	v_add_f32_dpp v94, v94, v94 quad_perm:[2,3,0,1] row_mask:0xf bank_mask:0xf bound_ctrl:1
	v_add_f32_dpp v96, v96, v96 quad_perm:[2,3,0,1] row_mask:0xf bank_mask:0xf bound_ctrl:1
	ds_read_b128 v[44:47], v100 offset:10400
	v_add_f32_dpp v94, v94, v94 row_half_mirror row_mask:0xf bank_mask:0xf bound_ctrl:1
	v_add_f32_dpp v96, v96, v96 row_half_mirror row_mask:0xf bank_mask:0xf bound_ctrl:1
	v_fma_f32 v97, -v84, v94, v92
	v_pk_mul_f32 v[98:99], v[84:85], v[96:97]
	ds_read_b128 v[48:51], v100 offset:10416
	v_pk_fma_f32 v[120:121], v[52:53], v[98:99], v[120:121] op_sel:[0,1,0]
	v_pk_fma_f32 v[122:123], v[54:55], v[98:99], v[122:123] op_sel:[0,1,0]
	v_fmac_f32_e32 v98, v86, v99
	v_pk_fma_f32 v[124:125], v[56:57], v[98:99], v[124:125] op_sel:[0,1,0]
	v_pk_fma_f32 v[126:127], v[58:59], v[98:99], v[126:127] op_sel:[0,1,0]
	ds_write_b32 v103, v98 offset:1024
	v_pk_fma_f32 v[128:129], v[60:61], v[98:99], v[128:129] op_sel:[0,1,0]
	v_pk_fma_f32 v[130:131], v[62:63], v[98:99], v[130:131] op_sel:[0,1,0]
	v_pk_fma_f32 v[132:133], v[64:65], v[98:99], v[132:133] op_sel:[0,1,0]
	v_pk_fma_f32 v[134:135], v[66:67], v[98:99], v[134:135] op_sel:[0,1,0]
	s_waitcnt lgkmcnt(4)
; __device__ __forceinline__ float red8(float v) { v = red4(v); v += dppf<0x141>(v); return v; }
; __device__ __forceinline__ f32x2 lo2(const f32x4& v) { return __builtin_shufflevector(v, v, 0, 1); }
; __device__ __forceinline__ f32x2 hi2(const f32x4& v) { return __builtin_shufflevector(v, v, 2, 3); }
; __device__ __forceinline__ f32x2 splat2(float x) { return (f32x2){x, x}; }
; __device__ __forceinline__ void gd_load(GdRegs& R, const float* vb, const float* sb, int t, int k0, int cl) {
;   const float* vt = vb + t * 288;
; #pragma unroll
;   for (int q = 0; q < 4; ++q) {
;     R.q[q] = *(const f32x4*)(vt + k0 + q * 4);
;     R.k[q] = *(const f32x4*)(vt + 128 + k0 + q * 4);
;   }
;   R.v = vt[256 + cl];
;   R.sc = *(const f32x4*)(sb + t * 4);
; }
; __device__ __forceinline__ float gd_step(f32x2 (&S)[8], const GdRegs& R) {
;   f32x2 k0a = splat2(0.f), k1a = splat2(0.f), q0a = splat2(0.f), q1a = splat2(0.f);
; #pragma unroll
;   for (int q = 0; q < 4; ++q) {
;     k0a += S[2 * q] * lo2(R.k[q]);
;     k1a += S[2 * q + 1] * hi2(R.k[q]);
;     q0a += S[2 * q] * lo2(R.q[q]);
;     q1a += S[2 * q + 1] * hi2(R.q[q]);
;   }
;   k0a += k1a; q0a += q1a;
;   const float dK = red8(k0a.x + k0a.y), dQ = red8(q0a.x + q0a.y);
;   const float vn = R.sc.y * (R.v - R.sc.x * dK);
;   const float o = R.sc.x * dQ + R.sc.z * vn;
;   const f32x2 al2 = splat2(R.sc.x), vn2 = splat2(vn);
; #pragma unroll
;   for (int q = 0; q < 4; ++q) {
;     S[2 * q] = S[2 * q] * al2 + lo2(R.k[q]) * vn2;
;     S[2 * q + 1] = S[2 * q + 1] * al2 + hi2(R.k[q]) * vn2;
;   }
;   return o;
; }
; __device__ __forceinline__ void scan_gdn(const Params& p, int l, int seq, int h, int qt, char* smem, const unsigned* wflags, unsigned wexpect) {
;     ...
;     for (int t = 0; t < nsteps; t += 2) {
;       gd_load(RB, vb, sb, min(t + 1, 15), k0, cl);
;       const float o0v = gd_step(S, RA);
;       *((part == 0) ? (yb + t * 32 + cl) : ydummy) = o0v;
;       SCAN_INTERLEAVE(10, 4);
;       if (t + 1 < nsteps) {
;         gd_load(RA, vb, sb, min(t + 2, 15), k0, cl);
;         const float o1v = gd_step(S, RB);
;         *((part == 0) ? (yb + (t + 1) * 32 + cl) : ydummy) = o1v;
;         SCAN_INTERLEAVE(10, 4);
;       }
;     }
	v_pk_mul_f32 v[94:95], v[120:121], v[68:69]
	v_pk_mul_f32 v[96:97], v[120:121], v[36:37]
	v_pk_fma_f32 v[94:95], v[122:123], v[70:71], v[94:95]
	v_pk_fma_f32 v[96:97], v[122:123], v[38:39], v[96:97]
	v_pk_mul_f32 v[120:121], v[120:121], v[88:89] op_sel_hi:[1,0]
	ds_read_b128 v[52:55], v100 offset:12032
	s_waitcnt lgkmcnt(4)
	v_pk_fma_f32 v[94:95], v[124:125], v[72:73], v[94:95]
	v_pk_fma_f32 v[96:97], v[124:125], v[40:41], v[96:97]
	v_pk_mul_f32 v[122:123], v[122:123], v[88:89] op_sel_hi:[1,0]
	ds_read_b128 v[56:59], v100 offset:12048
	v_pk_fma_f32 v[94:95], v[126:127], v[74:75], v[94:95]
	v_pk_fma_f32 v[96:97], v[126:127], v[42:43], v[96:97]
	v_pk_mul_f32 v[124:125], v[124:125], v[88:89] op_sel_hi:[1,0]
	ds_read_b128 v[60:63], v100 offset:12064
	s_waitcnt lgkmcnt(5)
	v_pk_fma_f32 v[94:95], v[128:129], v[76:77], v[94:95]
	v_pk_fma_f32 v[96:97], v[128:129], v[44:45], v[96:97]
	v_pk_mul_f32 v[126:127], v[126:127], v[88:89] op_sel_hi:[1,0]
	ds_read_b128 v[64:67], v100 offset:12080
	v_pk_fma_f32 v[94:95], v[130:131], v[78:79], v[94:95]
	v_pk_fma_f32 v[96:97], v[130:131], v[46:47], v[96:97]
	v_pk_mul_f32 v[128:129], v[128:129], v[88:89] op_sel_hi:[1,0]
	ds_read_b32 v92, v101 offset:12544
	ds_read_b128 v[84:87], v102 offset:37024
	s_waitcnt lgkmcnt(7)
	v_pk_fma_f32 v[94:95], v[132:133], v[80:81], v[94:95]
	v_pk_fma_f32 v[96:97], v[132:133], v[48:49], v[96:97]
	v_pk_mul_f32 v[130:131], v[130:131], v[88:89] op_sel_hi:[1,0]
	v_pk_fma_f32 v[94:95], v[134:135], v[82:83], v[94:95]
	v_pk_fma_f32 v[96:97], v[134:135], v[50:51], v[96:97]
	v_pk_mul_f32 v[132:133], v[132:133], v[88:89] op_sel_hi:[1,0]
	v_pk_mul_f32 v[134:135], v[134:135], v[88:89] op_sel_hi:[1,0]
	v_add_f32_e32 v94, v94, v95
	v_add_f32_e32 v96, v96, v97
	ds_read_b128 v[36:39], v100 offset:11520
	v_add_f32_dpp v94, v94, v94 quad_perm:[1,0,3,2] row_mask:0xf bank_mask:0xf bound_ctrl:1
	v_add_f32_dpp v96, v96, v96 quad_perm:[1,0,3,2] row_mask:0xf bank_mask:0xf bound_ctrl:1
	ds_read_b128 v[40:43], v100 offset:11536
	v_add_f32_dpp v94, v94, v94 quad_perm:[2,3,0,1] row_mask:0xf bank_mask:0xf bound_ctrl:1
	v_add_f32_dpp v96, v96, v96 quad_perm:[2,3,0,1] row_mask:0xf bank_mask:0xf bound_ctrl:1
	ds_read_b128 v[44:47], v100 offset:11552
	v_add_f32_dpp v94, v94, v94 row_half_mirror row_mask:0xf bank_mask:0xf bound_ctrl:1
	v_add_f32_dpp v96, v96, v96 row_half_mirror row_mask:0xf bank_mask:0xf bound_ctrl:1
	v_fma_f32 v97, -v88, v94, v93
	v_pk_mul_f32 v[98:99], v[88:89], v[96:97]
	ds_read_b128 v[48:51], v100 offset:11568
	v_pk_fma_f32 v[120:121], v[68:69], v[98:99], v[120:121] op_sel:[0,1,0]
	v_pk_fma_f32 v[122:123], v[70:71], v[98:99], v[122:123] op_sel:[0,1,0]
	v_fmac_f32_e32 v98, v90, v99
	v_pk_fma_f32 v[124:125], v[72:73], v[98:99], v[124:125] op_sel:[0,1,0]
	v_pk_fma_f32 v[126:127], v[74:75], v[98:99], v[126:127] op_sel:[0,1,0]
	ds_write_b32 v103, v98 offset:1152
	v_pk_fma_f32 v[128:129], v[76:77], v[98:99], v[128:129] op_sel:[0,1,0]
	v_pk_fma_f32 v[130:131], v[78:79], v[98:99], v[130:131] op_sel:[0,1,0]
	v_pk_fma_f32 v[132:133], v[80:81], v[98:99], v[132:133] op_sel:[0,1,0]
	v_pk_fma_f32 v[134:135], v[82:83], v[98:99], v[134:135] op_sel:[0,1,0]
	s_waitcnt lgkmcnt(4)
	v_pk_mul_f32 v[94:95], v[120:121], v[52:53]
	v_pk_mul_f32 v[96:97], v[120:121], v[36:37]
	v_pk_fma_f32 v[94:95], v[122:123], v[54:55], v[94:95]
	v_pk_fma_f32 v[96:97], v[122:123], v[38:39], v[96:97]
	v_pk_mul_f32 v[120:121], v[120:121], v[84:85] op_sel_hi:[1,0]
	ds_read_b128 v[68:71], v100 offset:13184
	s_waitcnt lgkmcnt(4)
	v_pk_fma_f32 v[94:95], v[124:125], v[56:57], v[94:95]
	v_pk_fma_f32 v[96:97], v[124:125], v[40:41], v[96:97]
	v_pk_mul_f32 v[122:123], v[122:123], v[84:85] op_sel_hi:[1,0]
	ds_read_b128 v[72:75], v100 offset:13200
	v_pk_fma_f32 v[94:95], v[126:127], v[58:59], v[94:95]
	v_pk_fma_f32 v[96:97], v[126:127], v[42:43], v[96:97]
	v_pk_mul_f32 v[124:125], v[124:125], v[84:85] op_sel_hi:[1,0]
	ds_read_b128 v[76:79], v100 offset:13216
	s_waitcnt lgkmcnt(5)
	v_pk_fma_f32 v[94:95], v[128:129], v[60:61], v[94:95]
	v_pk_fma_f32 v[96:97], v[128:129], v[44:45], v[96:97]
	v_pk_mul_f32 v[126:127], v[126:127], v[84:85] op_sel_hi:[1,0]
	ds_read_b128 v[80:83], v100 offset:13232
	v_pk_fma_f32 v[94:95], v[130:131], v[62:63], v[94:95]
	v_pk_fma_f32 v[96:97], v[130:131], v[46:47], v[96:97]
	v_pk_mul_f32 v[128:129], v[128:129], v[84:85] op_sel_hi:[1,0]
	ds_read_b32 v93, v101 offset:13696
	ds_read_b128 v[88:91], v102 offset:37040
	s_waitcnt lgkmcnt(7)
	v_pk_fma_f32 v[94:95], v[132:133], v[64:65], v[94:95]
	v_pk_fma_f32 v[96:97], v[132:133], v[48:49], v[96:97]
	v_pk_mul_f32 v[130:131], v[130:131], v[84:85] op_sel_hi:[1,0]
	v_pk_fma_f32 v[94:95], v[134:135], v[66:67], v[94:95]
	v_pk_fma_f32 v[96:97], v[134:135], v[50:51], v[96:97]
	v_pk_mul_f32 v[132:133], v[132:133], v[84:85] op_sel_hi:[1,0]
	v_pk_mul_f32 v[134:135], v[134:135], v[84:85] op_sel_hi:[1,0]
	v_add_f32_e32 v94, v94, v95
	v_add_f32_e32 v96, v96, v97
	ds_read_b128 v[36:39], v100 offset:12672
	v_add_f32_dpp v94, v94, v94 quad_perm:[1,0,3,2] row_mask:0xf bank_mask:0xf bound_ctrl:1
	v_add_f32_dpp v96, v96, v96 quad_perm:[1,0,3,2] row_mask:0xf bank_mask:0xf bound_ctrl:1
	ds_read_b128 v[40:43], v100 offset:12688
	v_add_f32_dpp v94, v94, v94 quad_perm:[2,3,0,1] row_mask:0xf bank_mask:0xf bound_ctrl:1
	v_add_f32_dpp v96, v96, v96 quad_perm:[2,3,0,1] row_mask:0xf bank_mask:0xf bound_ctrl:1
	ds_read_b128 v[44:47], v100 offset:12704
	v_add_f32_dpp v94, v94, v94 row_half_mirror row_mask:0xf bank_mask:0xf bound_ctrl:1
	v_add_f32_dpp v96, v96, v96 row_half_mirror row_mask:0xf bank_mask:0xf bound_ctrl:1
	v_fma_f32 v97, -v84, v94, v92
	v_pk_mul_f32 v[98:99], v[84:85], v[96:97]
	ds_read_b128 v[48:51], v100 offset:12720
	v_pk_fma_f32 v[120:121], v[52:53], v[98:99], v[120:121] op_sel:[0,1,0]
	v_pk_fma_f32 v[122:123], v[54:55], v[98:99], v[122:123] op_sel:[0,1,0]
	v_fmac_f32_e32 v98, v86, v99
	v_pk_fma_f32 v[124:125], v[56:57], v[98:99], v[124:125] op_sel:[0,1,0]
	v_pk_fma_f32 v[126:127], v[58:59], v[98:99], v[126:127] op_sel:[0,1,0]
	ds_write_b32 v103, v98 offset:1280
	v_pk_fma_f32 v[128:129], v[60:61], v[98:99], v[128:129] op_sel:[0,1,0]
	v_pk_fma_f32 v[130:131], v[62:63], v[98:99], v[130:131] op_sel:[0,1,0]
	v_pk_fma_f32 v[132:133], v[64:65], v[98:99], v[132:133] op_sel:[0,1,0]
	v_pk_fma_f32 v[134:135], v[66:67], v[98:99], v[134:135] op_sel:[0,1,0]
	s_waitcnt lgkmcnt(4)
; __device__ __forceinline__ float red8(float v) { v = red4(v); v += dppf<0x141>(v); return v; }
; __device__ __forceinline__ f32x2 lo2(const f32x4& v) { return __builtin_shufflevector(v, v, 0, 1); }
; __device__ __forceinline__ f32x2 hi2(const f32x4& v) { return __builtin_shufflevector(v, v, 2, 3); }
; __device__ __forceinline__ f32x2 splat2(float x) { return (f32x2){x, x}; }
; __device__ __forceinline__ void gd_load(GdRegs& R, const float* vb, const float* sb, int t, int k0, int cl) {
;   const float* vt = vb + t * 288;
; #pragma unroll
;   for (int q = 0; q < 4; ++q) {
;     R.q[q] = *(const f32x4*)(vt + k0 + q * 4);
;     R.k[q] = *(const f32x4*)(vt + 128 + k0 + q * 4);
;   }
;   R.v = vt[256 + cl];
;   R.sc = *(const f32x4*)(sb + t * 4);
; }
; __device__ __forceinline__ float gd_step(f32x2 (&S)[8], const GdRegs& R) {
;   f32x2 k0a = splat2(0.f), k1a = splat2(0.f), q0a = splat2(0.f), q1a = splat2(0.f);
; #pragma unroll
;   for (int q = 0; q < 4; ++q) {
;     k0a += S[2 * q] * lo2(R.k[q]);
;     k1a += S[2 * q + 1] * hi2(R.k[q]);
;     q0a += S[2 * q] * lo2(R.q[q]);
;     q1a += S[2 * q + 1] * hi2(R.q[q]);
;   }
;   k0a += k1a; q0a += q1a;
;   const float dK = red8(k0a.x + k0a.y), dQ = red8(q0a.x + q0a.y);
;   const float vn = R.sc.y * (R.v - R.sc.x * dK);
;   const float o = R.sc.x * dQ + R.sc.z * vn;
;   const f32x2 al2 = splat2(R.sc.x), vn2 = splat2(vn);
; #pragma unroll
;   for (int q = 0; q < 4; ++q) {
;     S[2 * q] = S[2 * q] * al2 + lo2(R.k[q]) * vn2;
;     S[2 * q + 1] = S[2 * q + 1] * al2 + hi2(R.k[q]) * vn2;
;   }
;   return o;
; }
; __device__ __forceinline__ void scan_gdn(const Params& p, int l, int seq, int h, int qt, char* smem, const unsigned* wflags, unsigned wexpect) {
;     ...
;     for (int t = 0; t < nsteps; t += 2) {
;       gd_load(RB, vb, sb, min(t + 1, 15), k0, cl);
;       const float o0v = gd_step(S, RA);
;       *((part == 0) ? (yb + t * 32 + cl) : ydummy) = o0v;
;       SCAN_INTERLEAVE(10, 4);
;       if (t + 1 < nsteps) {
;         gd_load(RA, vb, sb, min(t + 2, 15), k0, cl);
;         const float o1v = gd_step(S, RB);
;         *((part == 0) ? (yb + (t + 1) * 32 + cl) : ydummy) = o1v;
;         SCAN_INTERLEAVE(10, 4);
;       }
;     }
	v_pk_mul_f32 v[94:95], v[120:121], v[68:69]
	v_pk_mul_f32 v[96:97], v[120:121], v[36:37]
	v_pk_fma_f32 v[94:95], v[122:123], v[70:71], v[94:95]
	v_pk_fma_f32 v[96:97], v[122:123], v[38:39], v[96:97]
	v_pk_mul_f32 v[120:121], v[120:121], v[88:89] op_sel_hi:[1,0]
	ds_read_b128 v[52:55], v100 offset:14336
	s_waitcnt lgkmcnt(4)
	v_pk_fma_f32 v[94:95], v[124:125], v[72:73], v[94:95]
	v_pk_fma_f32 v[96:97], v[124:125], v[40:41], v[96:97]
	v_pk_mul_f32 v[122:123], v[122:123], v[88:89] op_sel_hi:[1,0]
	ds_read_b128 v[56:59], v100 offset:14352
	v_pk_fma_f32 v[94:95], v[126:127], v[74:75], v[94:95]
	v_pk_fma_f32 v[96:97], v[126:127], v[42:43], v[96:97]
	v_pk_mul_f32 v[124:125], v[124:125], v[88:89] op_sel_hi:[1,0]
	ds_read_b128 v[60:63], v100 offset:14368
	s_waitcnt lgkmcnt(5)
	v_pk_fma_f32 v[94:95], v[128:129], v[76:77], v[94:95]
	v_pk_fma_f32 v[96:97], v[128:129], v[44:45], v[96:97]
	v_pk_mul_f32 v[126:127], v[126:127], v[88:89] op_sel_hi:[1,0]
	ds_read_b128 v[64:67], v100 offset:14384
	v_pk_fma_f32 v[94:95], v[130:131], v[78:79], v[94:95]
	v_pk_fma_f32 v[96:97], v[130:131], v[46:47], v[96:97]
	v_pk_mul_f32 v[128:129], v[128:129], v[88:89] op_sel_hi:[1,0]
	ds_read_b32 v92, v101 offset:14848
	ds_read_b128 v[84:87], v102 offset:37056
	s_waitcnt lgkmcnt(7)
	v_pk_fma_f32 v[94:95], v[132:133], v[80:81], v[94:95]
	v_pk_fma_f32 v[96:97], v[132:133], v[48:49], v[96:97]
	v_pk_mul_f32 v[130:131], v[130:131], v[88:89] op_sel_hi:[1,0]
	v_pk_fma_f32 v[94:95], v[134:135], v[82:83], v[94:95]
	v_pk_fma_f32 v[96:97], v[134:135], v[50:51], v[96:97]
	v_pk_mul_f32 v[132:133], v[132:133], v[88:89] op_sel_hi:[1,0]
	v_pk_mul_f32 v[134:135], v[134:135], v[88:89] op_sel_hi:[1,0]
	v_add_f32_e32 v94, v94, v95
	v_add_f32_e32 v96, v96, v97
	ds_read_b128 v[36:39], v100 offset:13824
	v_add_f32_dpp v94, v94, v94 quad_perm:[1,0,3,2] row_mask:0xf bank_mask:0xf bound_ctrl:1
	v_add_f32_dpp v96, v96, v96 quad_perm:[1,0,3,2] row_mask:0xf bank_mask:0xf bound_ctrl:1
	ds_read_b128 v[40:43], v100 offset:13840
	v_add_f32_dpp v94, v94, v94 quad_perm:[2,3,0,1] row_mask:0xf bank_mask:0xf bound_ctrl:1
	v_add_f32_dpp v96, v96, v96 quad_perm:[2,3,0,1] row_mask:0xf bank_mask:0xf bound_ctrl:1
	ds_read_b128 v[44:47], v100 offset:13856
	v_add_f32_dpp v94, v94, v94 row_half_mirror row_mask:0xf bank_mask:0xf bound_ctrl:1
	v_add_f32_dpp v96, v96, v96 row_half_mirror row_mask:0xf bank_mask:0xf bound_ctrl:1
	v_fma_f32 v97, -v88, v94, v93
	v_pk_mul_f32 v[98:99], v[88:89], v[96:97]
	ds_read_b128 v[48:51], v100 offset:13872
	v_pk_fma_f32 v[120:121], v[68:69], v[98:99], v[120:121] op_sel:[0,1,0]
	v_pk_fma_f32 v[122:123], v[70:71], v[98:99], v[122:123] op_sel:[0,1,0]
	v_fmac_f32_e32 v98, v90, v99
	v_pk_fma_f32 v[124:125], v[72:73], v[98:99], v[124:125] op_sel:[0,1,0]
	v_pk_fma_f32 v[126:127], v[74:75], v[98:99], v[126:127] op_sel:[0,1,0]
	ds_write_b32 v103, v98 offset:1408
	v_pk_fma_f32 v[128:129], v[76:77], v[98:99], v[128:129] op_sel:[0,1,0]
	v_pk_fma_f32 v[130:131], v[78:79], v[98:99], v[130:131] op_sel:[0,1,0]
	v_pk_fma_f32 v[132:133], v[80:81], v[98:99], v[132:133] op_sel:[0,1,0]
	v_pk_fma_f32 v[134:135], v[82:83], v[98:99], v[134:135] op_sel:[0,1,0]
	s_waitcnt lgkmcnt(4)
	v_pk_mul_f32 v[94:95], v[120:121], v[52:53]
	v_pk_mul_f32 v[96:97], v[120:121], v[36:37]
	v_pk_fma_f32 v[94:95], v[122:123], v[54:55], v[94:95]
	v_pk_fma_f32 v[96:97], v[122:123], v[38:39], v[96:97]
	v_pk_mul_f32 v[120:121], v[120:121], v[84:85] op_sel_hi:[1,0]
	ds_read_b128 v[68:71], v100 offset:15488
	s_waitcnt lgkmcnt(4)
	v_pk_fma_f32 v[94:95], v[124:125], v[56:57], v[94:95]
	v_pk_fma_f32 v[96:97], v[124:125], v[40:41], v[96:97]
	v_pk_mul_f32 v[122:123], v[122:123], v[84:85] op_sel_hi:[1,0]
	ds_read_b128 v[72:75], v100 offset:15504
	v_pk_fma_f32 v[94:95], v[126:127], v[58:59], v[94:95]
	v_pk_fma_f32 v[96:97], v[126:127], v[42:43], v[96:97]
	v_pk_mul_f32 v[124:125], v[124:125], v[84:85] op_sel_hi:[1,0]
	ds_read_b128 v[76:79], v100 offset:15520
	s_waitcnt lgkmcnt(5)
	v_pk_fma_f32 v[94:95], v[128:129], v[60:61], v[94:95]
	v_pk_fma_f32 v[96:97], v[128:129], v[44:45], v[96:97]
	v_pk_mul_f32 v[126:127], v[126:127], v[84:85] op_sel_hi:[1,0]
	ds_read_b128 v[80:83], v100 offset:15536
	v_pk_fma_f32 v[94:95], v[130:131], v[62:63], v[94:95]
	v_pk_fma_f32 v[96:97], v[130:131], v[46:47], v[96:97]
	v_pk_mul_f32 v[128:129], v[128:129], v[84:85] op_sel_hi:[1,0]
	ds_read_b32 v93, v101 offset:16000
	ds_read_b128 v[88:91], v102 offset:37072
	s_waitcnt lgkmcnt(7)
	v_pk_fma_f32 v[94:95], v[132:133], v[64:65], v[94:95]
	v_pk_fma_f32 v[96:97], v[132:133], v[48:49], v[96:97]
	v_pk_mul_f32 v[130:131], v[130:131], v[84:85] op_sel_hi:[1,0]
	v_pk_fma_f32 v[94:95], v[134:135], v[66:67], v[94:95]
	v_pk_fma_f32 v[96:97], v[134:135], v[50:51], v[96:97]
	v_pk_mul_f32 v[132:133], v[132:133], v[84:85] op_sel_hi:[1,0]
	v_pk_mul_f32 v[134:135], v[134:135], v[84:85] op_sel_hi:[1,0]
	v_add_f32_e32 v94, v94, v95
	v_add_f32_e32 v96, v96, v97
	ds_read_b128 v[36:39], v100 offset:14976
	v_add_f32_dpp v94, v94, v94 quad_perm:[1,0,3,2] row_mask:0xf bank_mask:0xf bound_ctrl:1
	v_add_f32_dpp v96, v96, v96 quad_perm:[1,0,3,2] row_mask:0xf bank_mask:0xf bound_ctrl:1
	ds_read_b128 v[40:43], v100 offset:14992
	v_add_f32_dpp v94, v94, v94 quad_perm:[2,3,0,1] row_mask:0xf bank_mask:0xf bound_ctrl:1
	v_add_f32_dpp v96, v96, v96 quad_perm:[2,3,0,1] row_mask:0xf bank_mask:0xf bound_ctrl:1
	ds_read_b128 v[44:47], v100 offset:15008
	v_add_f32_dpp v94, v94, v94 row_half_mirror row_mask:0xf bank_mask:0xf bound_ctrl:1
	v_add_f32_dpp v96, v96, v96 row_half_mirror row_mask:0xf bank_mask:0xf bound_ctrl:1
	v_fma_f32 v97, -v84, v94, v92
	v_pk_mul_f32 v[98:99], v[84:85], v[96:97]
	ds_read_b128 v[48:51], v100 offset:15024
	v_pk_fma_f32 v[120:121], v[52:53], v[98:99], v[120:121] op_sel:[0,1,0]
	v_pk_fma_f32 v[122:123], v[54:55], v[98:99], v[122:123] op_sel:[0,1,0]
	v_fmac_f32_e32 v98, v86, v99
	v_pk_fma_f32 v[124:125], v[56:57], v[98:99], v[124:125] op_sel:[0,1,0]
	v_pk_fma_f32 v[126:127], v[58:59], v[98:99], v[126:127] op_sel:[0,1,0]
	ds_write_b32 v103, v98 offset:1536
	v_pk_fma_f32 v[128:129], v[60:61], v[98:99], v[128:129] op_sel:[0,1,0]
	v_pk_fma_f32 v[130:131], v[62:63], v[98:99], v[130:131] op_sel:[0,1,0]
	v_pk_fma_f32 v[132:133], v[64:65], v[98:99], v[132:133] op_sel:[0,1,0]
	v_pk_fma_f32 v[134:135], v[66:67], v[98:99], v[134:135] op_sel:[0,1,0]
	s_waitcnt lgkmcnt(4)
; __device__ __forceinline__ float red8(float v) { v = red4(v); v += dppf<0x141>(v); return v; }
; __device__ __forceinline__ f32x2 lo2(const f32x4& v) { return __builtin_shufflevector(v, v, 0, 1); }
; __device__ __forceinline__ f32x2 hi2(const f32x4& v) { return __builtin_shufflevector(v, v, 2, 3); }
; __device__ __forceinline__ f32x2 splat2(float x) { return (f32x2){x, x}; }
; __device__ __forceinline__ void gd_load(GdRegs& R, const float* vb, const float* sb, int t, int k0, int cl) {
;   const float* vt = vb + t * 288;
; #pragma unroll
;   for (int q = 0; q < 4; ++q) {
;     R.q[q] = *(const f32x4*)(vt + k0 + q * 4);
;     R.k[q] = *(const f32x4*)(vt + 128 + k0 + q * 4);
;   }
;   R.v = vt[256 + cl];
;   R.sc = *(const f32x4*)(sb + t * 4);
; }
; __device__ __forceinline__ float gd_step(f32x2 (&S)[8], const GdRegs& R) {
;   f32x2 k0a = splat2(0.f), k1a = splat2(0.f), q0a = splat2(0.f), q1a = splat2(0.f);
; #pragma unroll
;   for (int q = 0; q < 4; ++q) {
;     k0a += S[2 * q] * lo2(R.k[q]);
;     k1a += S[2 * q + 1] * hi2(R.k[q]);
;     q0a += S[2 * q] * lo2(R.q[q]);
;     q1a += S[2 * q + 1] * hi2(R.q[q]);
;   }
;   k0a += k1a; q0a += q1a;
;   const float dK = red8(k0a.x + k0a.y), dQ = red8(q0a.x + q0a.y);
;   const float vn = R.sc.y * (R.v - R.sc.x * dK);
;   const float o = R.sc.x * dQ + R.sc.z * vn;
;   const f32x2 al2 = splat2(R.sc.x), vn2 = splat2(vn);
; #pragma unroll
;   for (int q = 0; q < 4; ++q) {
;     S[2 * q] = S[2 * q] * al2 + lo2(R.k[q]) * vn2;
;     S[2 * q + 1] = S[2 * q + 1] * al2 + hi2(R.k[q]) * vn2;
;   }
;   return o;
; }
; __device__ __forceinline__ void scan_gdn(const Params& p, int l, int seq, int h, int qt, char* smem, const unsigned* wflags, unsigned wexpect) {
;     ...
;     for (int t = 0; t < nsteps; t += 2) {
;       gd_load(RB, vb, sb, min(t + 1, 15), k0, cl);
;       const float o0v = gd_step(S, RA);
;       *((part == 0) ? (yb + t * 32 + cl) : ydummy) = o0v;
;       SCAN_INTERLEAVE(10, 4);
;       if (t + 1 < nsteps) {
;         gd_load(RA, vb, sb, min(t + 2, 15), k0, cl);
;         const float o1v = gd_step(S, RB);
;         *((part == 0) ? (yb + (t + 1) * 32 + cl) : ydummy) = o1v;
;         SCAN_INTERLEAVE(10, 4);
;       }
;     }
	v_pk_mul_f32 v[94:95], v[120:121], v[68:69]
	v_pk_mul_f32 v[96:97], v[120:121], v[36:37]
	v_pk_fma_f32 v[94:95], v[122:123], v[70:71], v[94:95]
	v_pk_fma_f32 v[96:97], v[122:123], v[38:39], v[96:97]
	v_pk_mul_f32 v[120:121], v[120:121], v[88:89] op_sel_hi:[1,0]
	ds_read_b128 v[52:55], v100 offset:16640
	s_waitcnt lgkmcnt(4)
	v_pk_fma_f32 v[94:95], v[124:125], v[72:73], v[94:95]
	v_pk_fma_f32 v[96:97], v[124:125], v[40:41], v[96:97]
	v_pk_mul_f32 v[122:123], v[122:123], v[88:89] op_sel_hi:[1,0]
	ds_read_b128 v[56:59], v100 offset:16656
	v_pk_fma_f32 v[94:95], v[126:127], v[74:75], v[94:95]
	v_pk_fma_f32 v[96:97], v[126:127], v[42:43], v[96:97]
	v_pk_mul_f32 v[124:125], v[124:125], v[88:89] op_sel_hi:[1,0]
	ds_read_b128 v[60:63], v100 offset:16672
	s_waitcnt lgkmcnt(5)
	v_pk_fma_f32 v[94:95], v[128:129], v[76:77], v[94:95]
	v_pk_fma_f32 v[96:97], v[128:129], v[44:45], v[96:97]
	v_pk_mul_f32 v[126:127], v[126:127], v[88:89] op_sel_hi:[1,0]
	ds_read_b128 v[64:67], v100 offset:16688
	v_pk_fma_f32 v[94:95], v[130:131], v[78:79], v[94:95]
	v_pk_fma_f32 v[96:97], v[130:131], v[46:47], v[96:97]
	v_pk_mul_f32 v[128:129], v[128:129], v[88:89] op_sel_hi:[1,0]
	ds_read_b32 v92, v101 offset:17152
	ds_read_b128 v[84:87], v102 offset:37088
	s_waitcnt lgkmcnt(7)
	v_pk_fma_f32 v[94:95], v[132:133], v[80:81], v[94:95]
	v_pk_fma_f32 v[96:97], v[132:133], v[48:49], v[96:97]
	v_pk_mul_f32 v[130:131], v[130:131], v[88:89] op_sel_hi:[1,0]
	v_pk_fma_f32 v[94:95], v[134:135], v[82:83], v[94:95]
	v_pk_fma_f32 v[96:97], v[134:135], v[50:51], v[96:97]
	v_pk_mul_f32 v[132:133], v[132:133], v[88:89] op_sel_hi:[1,0]
	v_pk_mul_f32 v[134:135], v[134:135], v[88:89] op_sel_hi:[1,0]
	v_add_f32_e32 v94, v94, v95
	v_add_f32_e32 v96, v96, v97
	ds_read_b128 v[36:39], v100 offset:16128
	v_add_f32_dpp v94, v94, v94 quad_perm:[1,0,3,2] row_mask:0xf bank_mask:0xf bound_ctrl:1
	v_add_f32_dpp v96, v96, v96 quad_perm:[1,0,3,2] row_mask:0xf bank_mask:0xf bound_ctrl:1
	ds_read_b128 v[40:43], v100 offset:16144
	v_add_f32_dpp v94, v94, v94 quad_perm:[2,3,0,1] row_mask:0xf bank_mask:0xf bound_ctrl:1
	v_add_f32_dpp v96, v96, v96 quad_perm:[2,3,0,1] row_mask:0xf bank_mask:0xf bound_ctrl:1
	ds_read_b128 v[44:47], v100 offset:16160
	v_add_f32_dpp v94, v94, v94 row_half_mirror row_mask:0xf bank_mask:0xf bound_ctrl:1
	v_add_f32_dpp v96, v96, v96 row_half_mirror row_mask:0xf bank_mask:0xf bound_ctrl:1
	v_fma_f32 v97, -v88, v94, v93
	v_pk_mul_f32 v[98:99], v[88:89], v[96:97]
	ds_read_b128 v[48:51], v100 offset:16176
	v_pk_fma_f32 v[120:121], v[68:69], v[98:99], v[120:121] op_sel:[0,1,0]
	v_pk_fma_f32 v[122:123], v[70:71], v[98:99], v[122:123] op_sel:[0,1,0]
	v_fmac_f32_e32 v98, v90, v99
	v_pk_fma_f32 v[124:125], v[72:73], v[98:99], v[124:125] op_sel:[0,1,0]
	v_pk_fma_f32 v[126:127], v[74:75], v[98:99], v[126:127] op_sel:[0,1,0]
	ds_write_b32 v103, v98 offset:1664
	v_pk_fma_f32 v[128:129], v[76:77], v[98:99], v[128:129] op_sel:[0,1,0]
	v_pk_fma_f32 v[130:131], v[78:79], v[98:99], v[130:131] op_sel:[0,1,0]
	v_pk_fma_f32 v[132:133], v[80:81], v[98:99], v[132:133] op_sel:[0,1,0]
	v_pk_fma_f32 v[134:135], v[82:83], v[98:99], v[134:135] op_sel:[0,1,0]
	s_waitcnt lgkmcnt(4)
	v_pk_mul_f32 v[94:95], v[120:121], v[52:53]
	v_pk_mul_f32 v[96:97], v[120:121], v[36:37]
	v_pk_fma_f32 v[94:95], v[122:123], v[54:55], v[94:95]
	v_pk_fma_f32 v[96:97], v[122:123], v[38:39], v[96:97]
	v_pk_mul_f32 v[120:121], v[120:121], v[84:85] op_sel_hi:[1,0]
	ds_read_b128 v[68:71], v100 offset:17792
	s_waitcnt lgkmcnt(4)
	v_pk_fma_f32 v[94:95], v[124:125], v[56:57], v[94:95]
	v_pk_fma_f32 v[96:97], v[124:125], v[40:41], v[96:97]
	v_pk_mul_f32 v[122:123], v[122:123], v[84:85] op_sel_hi:[1,0]
	ds_read_b128 v[72:75], v100 offset:17808
	v_pk_fma_f32 v[94:95], v[126:127], v[58:59], v[94:95]
	v_pk_fma_f32 v[96:97], v[126:127], v[42:43], v[96:97]
	v_pk_mul_f32 v[124:125], v[124:125], v[84:85] op_sel_hi:[1,0]
	ds_read_b128 v[76:79], v100 offset:17824
	s_waitcnt lgkmcnt(5)
	v_pk_fma_f32 v[94:95], v[128:129], v[60:61], v[94:95]
	v_pk_fma_f32 v[96:97], v[128:129], v[44:45], v[96:97]
	v_pk_mul_f32 v[126:127], v[126:127], v[84:85] op_sel_hi:[1,0]
	ds_read_b128 v[80:83], v100 offset:17840
	v_pk_fma_f32 v[94:95], v[130:131], v[62:63], v[94:95]
	v_pk_fma_f32 v[96:97], v[130:131], v[46:47], v[96:97]
	v_pk_mul_f32 v[128:129], v[128:129], v[84:85] op_sel_hi:[1,0]
	ds_read_b32 v93, v101 offset:18304
	ds_read_b128 v[88:91], v102 offset:37104
	s_waitcnt lgkmcnt(7)
; __device__ __forceinline__ float red8(float v) { v = red4(v); v += dppf<0x141>(v); return v; }
; __device__ __forceinline__ f32x2 lo2(const f32x4& v) { return __builtin_shufflevector(v, v, 0, 1); }
; __device__ __forceinline__ f32x2 hi2(const f32x4& v) { return __builtin_shufflevector(v, v, 2, 3); }
; __device__ __forceinline__ f32x2 splat2(float x) { return (f32x2){x, x}; }
; __device__ __forceinline__ void gd_load(GdRegs& R, const float* vb, const float* sb, int t, int k0, int cl) {
;   const float* vt = vb + t * 288;
; #pragma unroll
;   for (int q = 0; q < 4; ++q) {
;     R.q[q] = *(const f32x4*)(vt + k0 + q * 4);
;     R.k[q] = *(const f32x4*)(vt + 128 + k0 + q * 4);
;   }
;   R.v = vt[256 + cl];
;   R.sc = *(const f32x4*)(sb + t * 4);
; }
; __device__ __forceinline__ float gd_step(f32x2 (&S)[8], const GdRegs& R) {
;   f32x2 k0a = splat2(0.f), k1a = splat2(0.f), q0a = splat2(0.f), q1a = splat2(0.f);
; #pragma unroll
;   for (int q = 0; q < 4; ++q) {
;     k0a += S[2 * q] * lo2(R.k[q]);
;     k1a += S[2 * q + 1] * hi2(R.k[q]);
;     q0a += S[2 * q] * lo2(R.q[q]);
;     q1a += S[2 * q + 1] * hi2(R.q[q]);
;   }
;   k0a += k1a; q0a += q1a;
;   const float dK = red8(k0a.x + k0a.y), dQ = red8(q0a.x + q0a.y);
;   const float vn = R.sc.y * (R.v - R.sc.x * dK);
;   const float o = R.sc.x * dQ + R.sc.z * vn;
;   const f32x2 al2 = splat2(R.sc.x), vn2 = splat2(vn);
; #pragma unroll
;   for (int q = 0; q < 4; ++q) {
;     S[2 * q] = S[2 * q] * al2 + lo2(R.k[q]) * vn2;
;     S[2 * q + 1] = S[2 * q + 1] * al2 + hi2(R.k[q]) * vn2;
;   }
;   return o;
; }
	v_pk_fma_f32 v[94:95], v[132:133], v[64:65], v[94:95]
	v_pk_fma_f32 v[96:97], v[132:133], v[48:49], v[96:97]
	v_pk_mul_f32 v[130:131], v[130:131], v[84:85] op_sel_hi:[1,0]
	v_pk_fma_f32 v[94:95], v[134:135], v[66:67], v[94:95]
	v_pk_fma_f32 v[96:97], v[134:135], v[50:51], v[96:97]
	v_pk_mul_f32 v[132:133], v[132:133], v[84:85] op_sel_hi:[1,0]
	v_pk_mul_f32 v[134:135], v[134:135], v[84:85] op_sel_hi:[1,0]
	v_add_f32_e32 v94, v94, v95
	v_add_f32_e32 v96, v96, v97
	ds_read_b128 v[36:39], v100 offset:17280
	v_add_f32_dpp v94, v94, v94 quad_perm:[1,0,3,2] row_mask:0xf bank_mask:0xf bound_ctrl:1
	v_add_f32_dpp v96, v96, v96 quad_perm:[1,0,3,2] row_mask:0xf bank_mask:0xf bound_ctrl:1
	ds_read_b128 v[40:43], v100 offset:17296
	v_add_f32_dpp v94, v94, v94 quad_perm:[2,3,0,1] row_mask:0xf bank_mask:0xf bound_ctrl:1
	v_add_f32_dpp v96, v96, v96 quad_perm:[2,3,0,1] row_mask:0xf bank_mask:0xf bound_ctrl:1
	ds_read_b128 v[44:47], v100 offset:17312
	v_add_f32_dpp v94, v94, v94 row_half_mirror row_mask:0xf bank_mask:0xf bound_ctrl:1
	v_add_f32_dpp v96, v96, v96 row_half_mirror row_mask:0xf bank_mask:0xf bound_ctrl:1
	v_fma_f32 v97, -v84, v94, v92
	v_pk_mul_f32 v[98:99], v[84:85], v[96:97]
	ds_read_b128 v[48:51], v100 offset:17328
	v_pk_fma_f32 v[120:121], v[52:53], v[98:99], v[120:121] op_sel:[0,1,0]
	v_pk_fma_f32 v[122:123], v[54:55], v[98:99], v[122:123] op_sel:[0,1,0]
	v_fmac_f32_e32 v98, v86, v99
	v_pk_fma_f32 v[124:125], v[56:57], v[98:99], v[124:125] op_sel:[0,1,0]
	v_pk_fma_f32 v[126:127], v[58:59], v[98:99], v[126:127] op_sel:[0,1,0]
	ds_write_b32 v103, v98 offset:1792
	v_pk_fma_f32 v[128:129], v[60:61], v[98:99], v[128:129] op_sel:[0,1,0]
	v_pk_fma_f32 v[130:131], v[62:63], v[98:99], v[130:131] op_sel:[0,1,0]
	v_pk_fma_f32 v[132:133], v[64:65], v[98:99], v[132:133] op_sel:[0,1,0]
	v_pk_fma_f32 v[134:135], v[66:67], v[98:99], v[134:135] op_sel:[0,1,0]
	s_waitcnt lgkmcnt(4)
	v_pk_mul_f32 v[94:95], v[120:121], v[68:69]
	v_pk_mul_f32 v[96:97], v[120:121], v[36:37]
	v_pk_fma_f32 v[94:95], v[122:123], v[70:71], v[94:95]
	v_pk_fma_f32 v[96:97], v[122:123], v[38:39], v[96:97]
	v_pk_mul_f32 v[120:121], v[120:121], v[88:89] op_sel_hi:[1,0]
	s_waitcnt lgkmcnt(3)
	v_pk_fma_f32 v[94:95], v[124:125], v[72:73], v[94:95]
	v_pk_fma_f32 v[96:97], v[124:125], v[40:41], v[96:97]
	v_pk_mul_f32 v[122:123], v[122:123], v[88:89] op_sel_hi:[1,0]
	v_pk_fma_f32 v[94:95], v[126:127], v[74:75], v[94:95]
	v_pk_fma_f32 v[96:97], v[126:127], v[42:43], v[96:97]
	v_pk_mul_f32 v[124:125], v[124:125], v[88:89] op_sel_hi:[1,0]
	s_waitcnt lgkmcnt(2)
	v_pk_fma_f32 v[94:95], v[128:129], v[76:77], v[94:95]
	v_pk_fma_f32 v[96:97], v[128:129], v[44:45], v[96:97]
	v_pk_mul_f32 v[126:127], v[126:127], v[88:89] op_sel_hi:[1,0]
	v_pk_fma_f32 v[94:95], v[130:131], v[78:79], v[94:95]
	v_pk_fma_f32 v[96:97], v[130:131], v[46:47], v[96:97]
	v_pk_mul_f32 v[128:129], v[128:129], v[88:89] op_sel_hi:[1,0]
	s_waitcnt lgkmcnt(1)
	v_pk_fma_f32 v[94:95], v[132:133], v[80:81], v[94:95]
	v_pk_fma_f32 v[96:97], v[132:133], v[48:49], v[96:97]
	v_pk_mul_f32 v[130:131], v[130:131], v[88:89] op_sel_hi:[1,0]
	v_pk_fma_f32 v[94:95], v[134:135], v[82:83], v[94:95]
	v_pk_fma_f32 v[96:97], v[134:135], v[50:51], v[96:97]
	v_pk_mul_f32 v[132:133], v[132:133], v[88:89] op_sel_hi:[1,0]
	v_pk_mul_f32 v[134:135], v[134:135], v[88:89] op_sel_hi:[1,0]
	v_add_f32_e32 v94, v94, v95
	v_add_f32_e32 v96, v96, v97
	s_nop 0
	v_add_f32_dpp v94, v94, v94 quad_perm:[1,0,3,2] row_mask:0xf bank_mask:0xf bound_ctrl:1
	v_add_f32_dpp v96, v96, v96 quad_perm:[1,0,3,2] row_mask:0xf bank_mask:0xf bound_ctrl:1
	s_nop 0
	v_add_f32_dpp v94, v94, v94 quad_perm:[2,3,0,1] row_mask:0xf bank_mask:0xf bound_ctrl:1
	v_add_f32_dpp v96, v96, v96 quad_perm:[2,3,0,1] row_mask:0xf bank_mask:0xf bound_ctrl:1
	s_nop 0
	v_add_f32_dpp v94, v94, v94 row_half_mirror row_mask:0xf bank_mask:0xf bound_ctrl:1
	v_add_f32_dpp v96, v96, v96 row_half_mirror row_mask:0xf bank_mask:0xf bound_ctrl:1
	v_fma_f32 v97, -v88, v94, v93
	v_pk_mul_f32 v[98:99], v[88:89], v[96:97]
	s_nop 0
	v_pk_fma_f32 v[120:121], v[68:69], v[98:99], v[120:121] op_sel:[0,1,0]
	v_pk_fma_f32 v[122:123], v[70:71], v[98:99], v[122:123] op_sel:[0,1,0]
	v_fmac_f32_e32 v98, v90, v99
	v_pk_fma_f32 v[124:125], v[72:73], v[98:99], v[124:125] op_sel:[0,1,0]
	v_pk_fma_f32 v[126:127], v[74:75], v[98:99], v[126:127] op_sel:[0,1,0]
	ds_write_b32 v103, v98 offset:1920
	v_pk_fma_f32 v[128:129], v[76:77], v[98:99], v[128:129] op_sel:[0,1,0]
	v_pk_fma_f32 v[130:131], v[78:79], v[98:99], v[130:131] op_sel:[0,1,0]
	v_pk_fma_f32 v[132:133], v[80:81], v[98:99], v[132:133] op_sel:[0,1,0]
	v_pk_fma_f32 v[134:135], v[82:83], v[98:99], v[134:135] op_sel:[0,1,0]
	s_cmp_eq_u32 s51, 0
	s_cbranch_scc1 .LBB0_193
	s_branch .LBB0_229

; __device__ __forceinline__ float red8(float v) { v = red4(v); v += dppf<0x141>(v); return v; }
; __device__ __forceinline__ f32x2 lo2(const f32x4& v) { return __builtin_shufflevector(v, v, 0, 1); }
; __device__ __forceinline__ f32x2 hi2(const f32x4& v) { return __builtin_shufflevector(v, v, 2, 3); }
; __device__ __forceinline__ f32x2 splat2(float x) { return (f32x2){x, x}; }
; __device__ __forceinline__ void ss_load(SsRegs& R, const float* vb, const float* sb, int t, int n0, int prow0) {
;   const float* vt = vb + t * 320;
; #pragma unroll
;   for (int q = 0; q < 4; ++q) {
;     R.B[q] = *(const f32x4*)(vt + n0 + q * 4);
;     R.C[q] = *(const f32x4*)(vt + 128 + n0 + q * 4);
;   }
;   R.x = *(const f32x2*)(vt + 256 + prow0);
;   R.sc = *(const f32x2*)(sb + t * 2);
; }
; __device__ __forceinline__ f32x2 ss_step(f32x2 (&S)[2][8], const SsRegs& R) {
;   const f32x2 dA2 = splat2(R.sc.y);
;   f32x2 out;
; #pragma unroll
;   for (int r = 0; r < 2; ++r) {
;     const f32x2 xdt2 = splat2((r ? R.x.y : R.x.x) * R.sc.x);
;     f32x2 y0 = splat2(0.f), y1 = splat2(0.f);
; #pragma unroll
;     for (int q = 0; q < 4; ++q) {
;       S[r][2 * q] = S[r][2 * q] * dA2 + xdt2 * lo2(R.B[q]);
;       S[r][2 * q + 1] = S[r][2 * q + 1] * dA2 + xdt2 * hi2(R.B[q]);
;       y0 += S[r][2 * q] * lo2(R.C[q]);
;       y1 += S[r][2 * q + 1] * hi2(R.C[q]);
;     }
;     y0 += y1;
;     const float y = red8(y0.x + y0.y);
;     if (r) out.y = y; else out.x = y;
;   }
;   return out;
; }
.Lssf_body:
	ds_read_b64 v[92:93], v117 offset:1024
	ds_read_b64 v[94:95], v118 offset:40960
	ds_read_b128 v[60:63], v116 offset:0
	ds_read_b128 v[76:79], v116 offset:512
	ds_read_b128 v[64:67], v116 offset:16
	ds_read_b128 v[80:83], v116 offset:528
	ds_read_b128 v[68:71], v116 offset:32
	ds_read_b128 v[84:87], v116 offset:544
	ds_read_b128 v[72:75], v116 offset:48
	ds_read_b128 v[88:91], v116 offset:560
	ds_read_b64 v[96:97], v117 offset:2304
	ds_read_b64 v[98:99], v118 offset:40968
	s_waitcnt lgkmcnt(4)
	v_pk_mul_f32 v[100:101], v[92:93], v[94:95] op_sel_hi:[1,0]
	v_pk_mul_f32 v[102:103], v[100:101], v[60:61] op_sel_hi:[0,1]
	v_pk_mul_f32 v[104:105], v[100:101], v[60:61] op_sel:[1,0]
	v_pk_fma_f32 v[28:29], v[28:29], v[94:95], v[102:103] op_sel:[0,1,0]
	v_pk_fma_f32 v[24:25], v[24:25], v[94:95], v[104:105] op_sel:[0,1,0]
	v_pk_mul_f32 v[110:111], v[28:29], v[76:77]
	v_pk_mul_f32 v[112:113], v[24:25], v[76:77]
	v_pk_mul_f32 v[106:107], v[100:101], v[62:63] op_sel_hi:[0,1]
	v_pk_mul_f32 v[108:109], v[100:101], v[62:63] op_sel:[1,0]
	v_pk_fma_f32 v[30:31], v[30:31], v[94:95], v[106:107] op_sel:[0,1,0]
	v_pk_fma_f32 v[26:27], v[26:27], v[94:95], v[108:109] op_sel:[0,1,0]
	v_pk_fma_f32 v[110:111], v[30:31], v[78:79], v[110:111]
	v_pk_fma_f32 v[112:113], v[26:27], v[78:79], v[112:113]
	ds_read_b128 v[60:63], v116 offset:1280
	ds_read_b128 v[76:79], v116 offset:1792
	v_pk_mul_f32 v[102:103], v[100:101], v[64:65] op_sel_hi:[0,1]
	v_pk_mul_f32 v[104:105], v[100:101], v[64:65] op_sel:[1,0]
	v_pk_fma_f32 v[12:13], v[12:13], v[94:95], v[102:103] op_sel:[0,1,0]
	v_pk_fma_f32 v[32:33], v[32:33], v[94:95], v[104:105] op_sel:[0,1,0]
	v_pk_fma_f32 v[110:111], v[12:13], v[80:81], v[110:111]
	v_pk_fma_f32 v[112:113], v[32:33], v[80:81], v[112:113]
	v_pk_mul_f32 v[106:107], v[100:101], v[66:67] op_sel_hi:[0,1]
	v_pk_mul_f32 v[108:109], v[100:101], v[66:67] op_sel:[1,0]
	v_pk_fma_f32 v[14:15], v[14:15], v[94:95], v[106:107] op_sel:[0,1,0]
	v_pk_fma_f32 v[34:35], v[34:35], v[94:95], v[108:109] op_sel:[0,1,0]
	v_pk_fma_f32 v[110:111], v[14:15], v[82:83], v[110:111]
	v_pk_fma_f32 v[112:113], v[34:35], v[82:83], v[112:113]
	ds_read_b128 v[64:67], v116 offset:1296
	ds_read_b128 v[80:83], v116 offset:1808
	v_pk_mul_f32 v[102:103], v[100:101], v[68:69] op_sel_hi:[0,1]
	v_pk_mul_f32 v[104:105], v[100:101], v[68:69] op_sel:[1,0]
	v_pk_fma_f32 v[8:9], v[8:9], v[94:95], v[102:103] op_sel:[0,1,0]
	v_pk_fma_f32 v[20:21], v[20:21], v[94:95], v[104:105] op_sel:[0,1,0]
	v_pk_fma_f32 v[110:111], v[8:9], v[84:85], v[110:111]
	v_pk_fma_f32 v[112:113], v[20:21], v[84:85], v[112:113]
	v_pk_mul_f32 v[106:107], v[100:101], v[70:71] op_sel_hi:[0,1]
	v_pk_mul_f32 v[108:109], v[100:101], v[70:71] op_sel:[1,0]
	v_pk_fma_f32 v[10:11], v[10:11], v[94:95], v[106:107] op_sel:[0,1,0]
	v_pk_fma_f32 v[22:23], v[22:23], v[94:95], v[108:109] op_sel:[0,1,0]
	v_pk_fma_f32 v[110:111], v[10:11], v[86:87], v[110:111]
	v_pk_fma_f32 v[112:113], v[22:23], v[86:87], v[112:113]
	ds_read_b128 v[68:71], v116 offset:1312
	ds_read_b128 v[84:87], v116 offset:1824
	s_waitcnt lgkmcnt(8)
	v_pk_mul_f32 v[102:103], v[100:101], v[72:73] op_sel_hi:[0,1]
	v_pk_mul_f32 v[104:105], v[100:101], v[72:73] op_sel:[1,0]
	v_pk_fma_f32 v[4:5], v[4:5], v[94:95], v[102:103] op_sel:[0,1,0]
	v_pk_fma_f32 v[16:17], v[16:17], v[94:95], v[104:105] op_sel:[0,1,0]
	v_pk_fma_f32 v[110:111], v[4:5], v[88:89], v[110:111]
	v_pk_fma_f32 v[112:113], v[16:17], v[88:89], v[112:113]
	v_pk_mul_f32 v[106:107], v[100:101], v[74:75] op_sel_hi:[0,1]
	v_pk_mul_f32 v[108:109], v[100:101], v[74:75] op_sel:[1,0]
	v_pk_fma_f32 v[6:7], v[6:7], v[94:95], v[106:107] op_sel:[0,1,0]
	v_pk_fma_f32 v[18:19], v[18:19], v[94:95], v[108:109] op_sel:[0,1,0]
	v_pk_fma_f32 v[110:111], v[6:7], v[90:91], v[110:111]
	v_pk_fma_f32 v[112:113], v[18:19], v[90:91], v[112:113]
	ds_read_b128 v[72:75], v116 offset:1328
	ds_read_b128 v[88:91], v116 offset:1840
	v_add_f32_e32 v114, v110, v111
	v_add_f32_e32 v115, v112, v113
	ds_read_b64 v[92:93], v117 offset:3584
	ds_read_b64 v[94:95], v118 offset:40976
	s_waitcnt lgkmcnt(4)
	v_pk_mul_f32 v[100:101], v[96:97], v[98:99] op_sel_hi:[1,0]
	v_pk_mul_f32 v[102:103], v[100:101], v[60:61] op_sel_hi:[0,1]
	v_pk_mul_f32 v[104:105], v[100:101], v[60:61] op_sel:[1,0]
	v_pk_fma_f32 v[28:29], v[28:29], v[98:99], v[102:103] op_sel:[0,1,0]
	v_pk_fma_f32 v[24:25], v[24:25], v[98:99], v[104:105] op_sel:[0,1,0]
	v_pk_mul_f32 v[110:111], v[28:29], v[76:77]
	v_pk_mul_f32 v[112:113], v[24:25], v[76:77]
	v_add_f32_dpp v114, v114, v114 quad_perm:[1,0,3,2] row_mask:0xf bank_mask:0xf bound_ctrl:1
	v_add_f32_dpp v115, v115, v115 quad_perm:[1,0,3,2] row_mask:0xf bank_mask:0xf bound_ctrl:1
	v_pk_mul_f32 v[106:107], v[100:101], v[62:63] op_sel_hi:[0,1]
	v_pk_mul_f32 v[108:109], v[100:101], v[62:63] op_sel:[1,0]
	v_pk_fma_f32 v[30:31], v[30:31], v[98:99], v[106:107] op_sel:[0,1,0]
	v_pk_fma_f32 v[26:27], v[26:27], v[98:99], v[108:109] op_sel:[0,1,0]
	v_pk_fma_f32 v[110:111], v[30:31], v[78:79], v[110:111]
	v_pk_fma_f32 v[112:113], v[26:27], v[78:79], v[112:113]
	ds_read_b128 v[60:63], v116 offset:2560
	ds_read_b128 v[76:79], v116 offset:3072
	v_add_f32_dpp v114, v114, v114 quad_perm:[2,3,0,1] row_mask:0xf bank_mask:0xf bound_ctrl:1
	v_add_f32_dpp v115, v115, v115 quad_perm:[2,3,0,1] row_mask:0xf bank_mask:0xf bound_ctrl:1
	v_pk_mul_f32 v[102:103], v[100:101], v[64:65] op_sel_hi:[0,1]
	v_pk_mul_f32 v[104:105], v[100:101], v[64:65] op_sel:[1,0]
	v_pk_fma_f32 v[12:13], v[12:13], v[98:99], v[102:103] op_sel:[0,1,0]
	v_pk_fma_f32 v[32:33], v[32:33], v[98:99], v[104:105] op_sel:[0,1,0]
	v_pk_fma_f32 v[110:111], v[12:13], v[80:81], v[110:111]
; __device__ __forceinline__ float red8(float v) { v = red4(v); v += dppf<0x141>(v); return v; }
; __device__ __forceinline__ f32x2 lo2(const f32x4& v) { return __builtin_shufflevector(v, v, 0, 1); }
; __device__ __forceinline__ f32x2 hi2(const f32x4& v) { return __builtin_shufflevector(v, v, 2, 3); }
; __device__ __forceinline__ f32x2 splat2(float x) { return (f32x2){x, x}; }
; __device__ __forceinline__ void ss_load(SsRegs& R, const float* vb, const float* sb, int t, int n0, int prow0) {
;   const float* vt = vb + t * 320;
; #pragma unroll
;   for (int q = 0; q < 4; ++q) {
;     R.B[q] = *(const f32x4*)(vt + n0 + q * 4);
;     R.C[q] = *(const f32x4*)(vt + 128 + n0 + q * 4);
;   }
;   R.x = *(const f32x2*)(vt + 256 + prow0);
;   R.sc = *(const f32x2*)(sb + t * 2);
; }
; __device__ __forceinline__ f32x2 ss_step(f32x2 (&S)[2][8], const SsRegs& R) {
;   const f32x2 dA2 = splat2(R.sc.y);
;   f32x2 out;
; #pragma unroll
;   for (int r = 0; r < 2; ++r) {
;     const f32x2 xdt2 = splat2((r ? R.x.y : R.x.x) * R.sc.x);
;     f32x2 y0 = splat2(0.f), y1 = splat2(0.f);
; #pragma unroll
;     for (int q = 0; q < 4; ++q) {
;       S[r][2 * q] = S[r][2 * q] * dA2 + xdt2 * lo2(R.B[q]);
;       S[r][2 * q + 1] = S[r][2 * q + 1] * dA2 + xdt2 * hi2(R.B[q]);
;       y0 += S[r][2 * q] * lo2(R.C[q]);
;       y1 += S[r][2 * q + 1] * hi2(R.C[q]);
;     }
;     y0 += y1;
;     const float y = red8(y0.x + y0.y);
;     if (r) out.y = y; else out.x = y;
;   }
;   return out;
; }
	v_pk_fma_f32 v[112:113], v[32:33], v[80:81], v[112:113]
	v_add_f32_dpp v114, v114, v114 row_half_mirror row_mask:0xf bank_mask:0xf bound_ctrl:1
	v_add_f32_dpp v115, v115, v115 row_half_mirror row_mask:0xf bank_mask:0xf bound_ctrl:1
	v_pk_mul_f32 v[106:107], v[100:101], v[66:67] op_sel_hi:[0,1]
	v_pk_mul_f32 v[108:109], v[100:101], v[66:67] op_sel:[1,0]
	v_pk_fma_f32 v[14:15], v[14:15], v[98:99], v[106:107] op_sel:[0,1,0]
	v_pk_fma_f32 v[34:35], v[34:35], v[98:99], v[108:109] op_sel:[0,1,0]
	v_pk_fma_f32 v[110:111], v[14:15], v[82:83], v[110:111]
	v_pk_fma_f32 v[112:113], v[34:35], v[82:83], v[112:113]
	ds_read_b128 v[64:67], v116 offset:2576
	ds_read_b128 v[80:83], v116 offset:3088
	ds_write_b64 v119, v[114:115] offset:0
	v_pk_mul_f32 v[102:103], v[100:101], v[68:69] op_sel_hi:[0,1]
	v_pk_mul_f32 v[104:105], v[100:101], v[68:69] op_sel:[1,0]
	v_pk_fma_f32 v[8:9], v[8:9], v[98:99], v[102:103] op_sel:[0,1,0]
	v_pk_fma_f32 v[20:21], v[20:21], v[98:99], v[104:105] op_sel:[0,1,0]
	v_pk_fma_f32 v[110:111], v[8:9], v[84:85], v[110:111]
	v_pk_fma_f32 v[112:113], v[20:21], v[84:85], v[112:113]
	v_pk_mul_f32 v[106:107], v[100:101], v[70:71] op_sel_hi:[0,1]
	v_pk_mul_f32 v[108:109], v[100:101], v[70:71] op_sel:[1,0]
	v_pk_fma_f32 v[10:11], v[10:11], v[98:99], v[106:107] op_sel:[0,1,0]
	v_pk_fma_f32 v[22:23], v[22:23], v[98:99], v[108:109] op_sel:[0,1,0]
	v_pk_fma_f32 v[110:111], v[10:11], v[86:87], v[110:111]
	v_pk_fma_f32 v[112:113], v[22:23], v[86:87], v[112:113]
	ds_read_b128 v[68:71], v116 offset:2592
	ds_read_b128 v[84:87], v116 offset:3104
	s_waitcnt lgkmcnt(9)
	v_pk_mul_f32 v[102:103], v[100:101], v[72:73] op_sel_hi:[0,1]
	v_pk_mul_f32 v[104:105], v[100:101], v[72:73] op_sel:[1,0]
	v_pk_fma_f32 v[4:5], v[4:5], v[98:99], v[102:103] op_sel:[0,1,0]
	v_pk_fma_f32 v[16:17], v[16:17], v[98:99], v[104:105] op_sel:[0,1,0]
	v_pk_fma_f32 v[110:111], v[4:5], v[88:89], v[110:111]
	v_pk_fma_f32 v[112:113], v[16:17], v[88:89], v[112:113]
	v_pk_mul_f32 v[106:107], v[100:101], v[74:75] op_sel_hi:[0,1]
	v_pk_mul_f32 v[108:109], v[100:101], v[74:75] op_sel:[1,0]
	v_pk_fma_f32 v[6:7], v[6:7], v[98:99], v[106:107] op_sel:[0,1,0]
	v_pk_fma_f32 v[18:19], v[18:19], v[98:99], v[108:109] op_sel:[0,1,0]
	v_pk_fma_f32 v[110:111], v[6:7], v[90:91], v[110:111]
	v_pk_fma_f32 v[112:113], v[18:19], v[90:91], v[112:113]
	ds_read_b128 v[72:75], v116 offset:2608
	ds_read_b128 v[88:91], v116 offset:3120
	v_add_f32_e32 v114, v110, v111
	v_add_f32_e32 v115, v112, v113
	ds_read_b64 v[96:97], v117 offset:4864
	ds_read_b64 v[98:99], v118 offset:40984
	s_waitcnt lgkmcnt(4)
	v_pk_mul_f32 v[100:101], v[92:93], v[94:95] op_sel_hi:[1,0]
	v_pk_mul_f32 v[102:103], v[100:101], v[60:61] op_sel_hi:[0,1]
	v_pk_mul_f32 v[104:105], v[100:101], v[60:61] op_sel:[1,0]
	v_pk_fma_f32 v[28:29], v[28:29], v[94:95], v[102:103] op_sel:[0,1,0]
	v_pk_fma_f32 v[24:25], v[24:25], v[94:95], v[104:105] op_sel:[0,1,0]
	v_pk_mul_f32 v[110:111], v[28:29], v[76:77]
	v_pk_mul_f32 v[112:113], v[24:25], v[76:77]
	v_add_f32_dpp v114, v114, v114 quad_perm:[1,0,3,2] row_mask:0xf bank_mask:0xf bound_ctrl:1
	v_add_f32_dpp v115, v115, v115 quad_perm:[1,0,3,2] row_mask:0xf bank_mask:0xf bound_ctrl:1
	v_pk_mul_f32 v[106:107], v[100:101], v[62:63] op_sel_hi:[0,1]
	v_pk_mul_f32 v[108:109], v[100:101], v[62:63] op_sel:[1,0]
	v_pk_fma_f32 v[30:31], v[30:31], v[94:95], v[106:107] op_sel:[0,1,0]
	v_pk_fma_f32 v[26:27], v[26:27], v[94:95], v[108:109] op_sel:[0,1,0]
	v_pk_fma_f32 v[110:111], v[30:31], v[78:79], v[110:111]
	v_pk_fma_f32 v[112:113], v[26:27], v[78:79], v[112:113]
	ds_read_b128 v[60:63], v116 offset:3840
	ds_read_b128 v[76:79], v116 offset:4352
	v_add_f32_dpp v114, v114, v114 quad_perm:[2,3,0,1] row_mask:0xf bank_mask:0xf bound_ctrl:1
	v_add_f32_dpp v115, v115, v115 quad_perm:[2,3,0,1] row_mask:0xf bank_mask:0xf bound_ctrl:1
	v_pk_mul_f32 v[102:103], v[100:101], v[64:65] op_sel_hi:[0,1]
	v_pk_mul_f32 v[104:105], v[100:101], v[64:65] op_sel:[1,0]
	v_pk_fma_f32 v[12:13], v[12:13], v[94:95], v[102:103] op_sel:[0,1,0]
	v_pk_fma_f32 v[32:33], v[32:33], v[94:95], v[104:105] op_sel:[0,1,0]
	v_pk_fma_f32 v[110:111], v[12:13], v[80:81], v[110:111]
	v_pk_fma_f32 v[112:113], v[32:33], v[80:81], v[112:113]
	v_add_f32_dpp v114, v114, v114 row_half_mirror row_mask:0xf bank_mask:0xf bound_ctrl:1
	v_add_f32_dpp v115, v115, v115 row_half_mirror row_mask:0xf bank_mask:0xf bound_ctrl:1
	v_pk_mul_f32 v[106:107], v[100:101], v[66:67] op_sel_hi:[0,1]
	v_pk_mul_f32 v[108:109], v[100:101], v[66:67] op_sel:[1,0]
	v_pk_fma_f32 v[14:15], v[14:15], v[94:95], v[106:107] op_sel:[0,1,0]
	v_pk_fma_f32 v[34:35], v[34:35], v[94:95], v[108:109] op_sel:[0,1,0]
	v_pk_fma_f32 v[110:111], v[14:15], v[82:83], v[110:111]
	v_pk_fma_f32 v[112:113], v[34:35], v[82:83], v[112:113]
	ds_read_b128 v[64:67], v116 offset:3856
	ds_read_b128 v[80:83], v116 offset:4368
	ds_write_b64 v119, v[114:115] offset:256
	v_pk_mul_f32 v[102:103], v[100:101], v[68:69] op_sel_hi:[0,1]
	v_pk_mul_f32 v[104:105], v[100:101], v[68:69] op_sel:[1,0]
	v_pk_fma_f32 v[8:9], v[8:9], v[94:95], v[102:103] op_sel:[0,1,0]
	v_pk_fma_f32 v[20:21], v[20:21], v[94:95], v[104:105] op_sel:[0,1,0]
	v_pk_fma_f32 v[110:111], v[8:9], v[84:85], v[110:111]
	v_pk_fma_f32 v[112:113], v[20:21], v[84:85], v[112:113]
	v_pk_mul_f32 v[106:107], v[100:101], v[70:71] op_sel_hi:[0,1]
	v_pk_mul_f32 v[108:109], v[100:101], v[70:71] op_sel:[1,0]
	v_pk_fma_f32 v[10:11], v[10:11], v[94:95], v[106:107] op_sel:[0,1,0]
	v_pk_fma_f32 v[22:23], v[22:23], v[94:95], v[108:109] op_sel:[0,1,0]
	v_pk_fma_f32 v[110:111], v[10:11], v[86:87], v[110:111]
	v_pk_fma_f32 v[112:113], v[22:23], v[86:87], v[112:113]
	ds_read_b128 v[68:71], v116 offset:3872
	ds_read_b128 v[84:87], v116 offset:4384
	s_waitcnt lgkmcnt(9)
; __device__ __forceinline__ float red8(float v) { v = red4(v); v += dppf<0x141>(v); return v; }
; __device__ __forceinline__ f32x2 lo2(const f32x4& v) { return __builtin_shufflevector(v, v, 0, 1); }
; __device__ __forceinline__ f32x2 hi2(const f32x4& v) { return __builtin_shufflevector(v, v, 2, 3); }
; __device__ __forceinline__ f32x2 splat2(float x) { return (f32x2){x, x}; }
; __device__ __forceinline__ void ss_load(SsRegs& R, const float* vb, const float* sb, int t, int n0, int prow0) {
;   const float* vt = vb + t * 320;
; #pragma unroll
;   for (int q = 0; q < 4; ++q) {
;     R.B[q] = *(const f32x4*)(vt + n0 + q * 4);
;     R.C[q] = *(const f32x4*)(vt + 128 + n0 + q * 4);
;   }
;   R.x = *(const f32x2*)(vt + 256 + prow0);
;   R.sc = *(const f32x2*)(sb + t * 2);
; }
; __device__ __forceinline__ f32x2 ss_step(f32x2 (&S)[2][8], const SsRegs& R) {
;   const f32x2 dA2 = splat2(R.sc.y);
;   f32x2 out;
; #pragma unroll
;   for (int r = 0; r < 2; ++r) {
;     const f32x2 xdt2 = splat2((r ? R.x.y : R.x.x) * R.sc.x);
;     f32x2 y0 = splat2(0.f), y1 = splat2(0.f);
; #pragma unroll
;     for (int q = 0; q < 4; ++q) {
;       S[r][2 * q] = S[r][2 * q] * dA2 + xdt2 * lo2(R.B[q]);
;       S[r][2 * q + 1] = S[r][2 * q + 1] * dA2 + xdt2 * hi2(R.B[q]);
;       y0 += S[r][2 * q] * lo2(R.C[q]);
;       y1 += S[r][2 * q + 1] * hi2(R.C[q]);
;     }
;     y0 += y1;
;     const float y = red8(y0.x + y0.y);
;     if (r) out.y = y; else out.x = y;
;   }
;   return out;
; }
	v_pk_mul_f32 v[102:103], v[100:101], v[72:73] op_sel_hi:[0,1]
	v_pk_mul_f32 v[104:105], v[100:101], v[72:73] op_sel:[1,0]
	v_pk_fma_f32 v[4:5], v[4:5], v[94:95], v[102:103] op_sel:[0,1,0]
	v_pk_fma_f32 v[16:17], v[16:17], v[94:95], v[104:105] op_sel:[0,1,0]
	v_pk_fma_f32 v[110:111], v[4:5], v[88:89], v[110:111]
	v_pk_fma_f32 v[112:113], v[16:17], v[88:89], v[112:113]
	v_pk_mul_f32 v[106:107], v[100:101], v[74:75] op_sel_hi:[0,1]
	v_pk_mul_f32 v[108:109], v[100:101], v[74:75] op_sel:[1,0]
	v_pk_fma_f32 v[6:7], v[6:7], v[94:95], v[106:107] op_sel:[0,1,0]
	v_pk_fma_f32 v[18:19], v[18:19], v[94:95], v[108:109] op_sel:[0,1,0]
	v_pk_fma_f32 v[110:111], v[6:7], v[90:91], v[110:111]
	v_pk_fma_f32 v[112:113], v[18:19], v[90:91], v[112:113]
	ds_read_b128 v[72:75], v116 offset:3888
	ds_read_b128 v[88:91], v116 offset:4400
	v_add_f32_e32 v114, v110, v111
	v_add_f32_e32 v115, v112, v113
	ds_read_b64 v[92:93], v117 offset:6144
	ds_read_b64 v[94:95], v118 offset:40992
	s_waitcnt lgkmcnt(4)
	v_pk_mul_f32 v[100:101], v[96:97], v[98:99] op_sel_hi:[1,0]
	v_pk_mul_f32 v[102:103], v[100:101], v[60:61] op_sel_hi:[0,1]
	v_pk_mul_f32 v[104:105], v[100:101], v[60:61] op_sel:[1,0]
	v_pk_fma_f32 v[28:29], v[28:29], v[98:99], v[102:103] op_sel:[0,1,0]
	v_pk_fma_f32 v[24:25], v[24:25], v[98:99], v[104:105] op_sel:[0,1,0]
	v_pk_mul_f32 v[110:111], v[28:29], v[76:77]
	v_pk_mul_f32 v[112:113], v[24:25], v[76:77]
	v_add_f32_dpp v114, v114, v114 quad_perm:[1,0,3,2] row_mask:0xf bank_mask:0xf bound_ctrl:1
	v_add_f32_dpp v115, v115, v115 quad_perm:[1,0,3,2] row_mask:0xf bank_mask:0xf bound_ctrl:1
	v_pk_mul_f32 v[106:107], v[100:101], v[62:63] op_sel_hi:[0,1]
	v_pk_mul_f32 v[108:109], v[100:101], v[62:63] op_sel:[1,0]
	v_pk_fma_f32 v[30:31], v[30:31], v[98:99], v[106:107] op_sel:[0,1,0]
	v_pk_fma_f32 v[26:27], v[26:27], v[98:99], v[108:109] op_sel:[0,1,0]
	v_pk_fma_f32 v[110:111], v[30:31], v[78:79], v[110:111]
	v_pk_fma_f32 v[112:113], v[26:27], v[78:79], v[112:113]
	ds_read_b128 v[60:63], v116 offset:5120
	ds_read_b128 v[76:79], v116 offset:5632
	v_add_f32_dpp v114, v114, v114 quad_perm:[2,3,0,1] row_mask:0xf bank_mask:0xf bound_ctrl:1
	v_add_f32_dpp v115, v115, v115 quad_perm:[2,3,0,1] row_mask:0xf bank_mask:0xf bound_ctrl:1
	v_pk_mul_f32 v[102:103], v[100:101], v[64:65] op_sel_hi:[0,1]
	v_pk_mul_f32 v[104:105], v[100:101], v[64:65] op_sel:[1,0]
	v_pk_fma_f32 v[12:13], v[12:13], v[98:99], v[102:103] op_sel:[0,1,0]
	v_pk_fma_f32 v[32:33], v[32:33], v[98:99], v[104:105] op_sel:[0,1,0]
	v_pk_fma_f32 v[110:111], v[12:13], v[80:81], v[110:111]
	v_pk_fma_f32 v[112:113], v[32:33], v[80:81], v[112:113]
	v_add_f32_dpp v114, v114, v114 row_half_mirror row_mask:0xf bank_mask:0xf bound_ctrl:1
	v_add_f32_dpp v115, v115, v115 row_half_mirror row_mask:0xf bank_mask:0xf bound_ctrl:1
	v_pk_mul_f32 v[106:107], v[100:101], v[66:67] op_sel_hi:[0,1]
	v_pk_mul_f32 v[108:109], v[100:101], v[66:67] op_sel:[1,0]
	v_pk_fma_f32 v[14:15], v[14:15], v[98:99], v[106:107] op_sel:[0,1,0]
	v_pk_fma_f32 v[34:35], v[34:35], v[98:99], v[108:109] op_sel:[0,1,0]
	v_pk_fma_f32 v[110:111], v[14:15], v[82:83], v[110:111]
	v_pk_fma_f32 v[112:113], v[34:35], v[82:83], v[112:113]
	ds_read_b128 v[64:67], v116 offset:5136
	ds_read_b128 v[80:83], v116 offset:5648
	ds_write_b64 v119, v[114:115] offset:512
	v_pk_mul_f32 v[102:103], v[100:101], v[68:69] op_sel_hi:[0,1]
	v_pk_mul_f32 v[104:105], v[100:101], v[68:69] op_sel:[1,0]
	v_pk_fma_f32 v[8:9], v[8:9], v[98:99], v[102:103] op_sel:[0,1,0]
	v_pk_fma_f32 v[20:21], v[20:21], v[98:99], v[104:105] op_sel:[0,1,0]
	v_pk_fma_f32 v[110:111], v[8:9], v[84:85], v[110:111]
	v_pk_fma_f32 v[112:113], v[20:21], v[84:85], v[112:113]
	v_pk_mul_f32 v[106:107], v[100:101], v[70:71] op_sel_hi:[0,1]
	v_pk_mul_f32 v[108:109], v[100:101], v[70:71] op_sel:[1,0]
	v_pk_fma_f32 v[10:11], v[10:11], v[98:99], v[106:107] op_sel:[0,1,0]
	v_pk_fma_f32 v[22:23], v[22:23], v[98:99], v[108:109] op_sel:[0,1,0]
	v_pk_fma_f32 v[110:111], v[10:11], v[86:87], v[110:111]
	v_pk_fma_f32 v[112:113], v[22:23], v[86:87], v[112:113]
	ds_read_b128 v[68:71], v116 offset:5152
	ds_read_b128 v[84:87], v116 offset:5664
	s_waitcnt lgkmcnt(9)
	v_pk_mul_f32 v[102:103], v[100:101], v[72:73] op_sel_hi:[0,1]
	v_pk_mul_f32 v[104:105], v[100:101], v[72:73] op_sel:[1,0]
	v_pk_fma_f32 v[4:5], v[4:5], v[98:99], v[102:103] op_sel:[0,1,0]
	v_pk_fma_f32 v[16:17], v[16:17], v[98:99], v[104:105] op_sel:[0,1,0]
	v_pk_fma_f32 v[110:111], v[4:5], v[88:89], v[110:111]
	v_pk_fma_f32 v[112:113], v[16:17], v[88:89], v[112:113]
	v_pk_mul_f32 v[106:107], v[100:101], v[74:75] op_sel_hi:[0,1]
	v_pk_mul_f32 v[108:109], v[100:101], v[74:75] op_sel:[1,0]
	v_pk_fma_f32 v[6:7], v[6:7], v[98:99], v[106:107] op_sel:[0,1,0]
	v_pk_fma_f32 v[18:19], v[18:19], v[98:99], v[108:109] op_sel:[0,1,0]
	v_pk_fma_f32 v[110:111], v[6:7], v[90:91], v[110:111]
	v_pk_fma_f32 v[112:113], v[18:19], v[90:91], v[112:113]
	ds_read_b128 v[72:75], v116 offset:5168
	ds_read_b128 v[88:91], v116 offset:5680
	v_add_f32_e32 v114, v110, v111
	v_add_f32_e32 v115, v112, v113
	ds_read_b64 v[96:97], v117 offset:7424
	ds_read_b64 v[98:99], v118 offset:41000
	s_waitcnt lgkmcnt(4)
; __device__ __forceinline__ float red8(float v) { v = red4(v); v += dppf<0x141>(v); return v; }
; __device__ __forceinline__ f32x2 lo2(const f32x4& v) { return __builtin_shufflevector(v, v, 0, 1); }
; __device__ __forceinline__ f32x2 hi2(const f32x4& v) { return __builtin_shufflevector(v, v, 2, 3); }
; __device__ __forceinline__ f32x2 splat2(float x) { return (f32x2){x, x}; }
; __device__ __forceinline__ void ss_load(SsRegs& R, const float* vb, const float* sb, int t, int n0, int prow0) {
;   const float* vt = vb + t * 320;
; #pragma unroll
;   for (int q = 0; q < 4; ++q) {
;     R.B[q] = *(const f32x4*)(vt + n0 + q * 4);
;     R.C[q] = *(const f32x4*)(vt + 128 + n0 + q * 4);
;   }
;   R.x = *(const f32x2*)(vt + 256 + prow0);
;   R.sc = *(const f32x2*)(sb + t * 2);
; }
; __device__ __forceinline__ f32x2 ss_step(f32x2 (&S)[2][8], const SsRegs& R) {
;   const f32x2 dA2 = splat2(R.sc.y);
;   f32x2 out;
; #pragma unroll
;   for (int r = 0; r < 2; ++r) {
;     const f32x2 xdt2 = splat2((r ? R.x.y : R.x.x) * R.sc.x);
;     f32x2 y0 = splat2(0.f), y1 = splat2(0.f);
; #pragma unroll
;     for (int q = 0; q < 4; ++q) {
;       S[r][2 * q] = S[r][2 * q] * dA2 + xdt2 * lo2(R.B[q]);
;       S[r][2 * q + 1] = S[r][2 * q + 1] * dA2 + xdt2 * hi2(R.B[q]);
;       y0 += S[r][2 * q] * lo2(R.C[q]);
;       y1 += S[r][2 * q + 1] * hi2(R.C[q]);
;     }
;     y0 += y1;
;     const float y = red8(y0.x + y0.y);
;     if (r) out.y = y; else out.x = y;
;   }
;   return out;
; }
	v_pk_mul_f32 v[100:101], v[92:93], v[94:95] op_sel_hi:[1,0]
	v_pk_mul_f32 v[102:103], v[100:101], v[60:61] op_sel_hi:[0,1]
	v_pk_mul_f32 v[104:105], v[100:101], v[60:61] op_sel:[1,0]
	v_pk_fma_f32 v[28:29], v[28:29], v[94:95], v[102:103] op_sel:[0,1,0]
	v_pk_fma_f32 v[24:25], v[24:25], v[94:95], v[104:105] op_sel:[0,1,0]
	v_pk_mul_f32 v[110:111], v[28:29], v[76:77]
	v_pk_mul_f32 v[112:113], v[24:25], v[76:77]
	v_add_f32_dpp v114, v114, v114 quad_perm:[1,0,3,2] row_mask:0xf bank_mask:0xf bound_ctrl:1
	v_add_f32_dpp v115, v115, v115 quad_perm:[1,0,3,2] row_mask:0xf bank_mask:0xf bound_ctrl:1
	v_pk_mul_f32 v[106:107], v[100:101], v[62:63] op_sel_hi:[0,1]
	v_pk_mul_f32 v[108:109], v[100:101], v[62:63] op_sel:[1,0]
	v_pk_fma_f32 v[30:31], v[30:31], v[94:95], v[106:107] op_sel:[0,1,0]
	v_pk_fma_f32 v[26:27], v[26:27], v[94:95], v[108:109] op_sel:[0,1,0]
	v_pk_fma_f32 v[110:111], v[30:31], v[78:79], v[110:111]
	v_pk_fma_f32 v[112:113], v[26:27], v[78:79], v[112:113]
	ds_read_b128 v[60:63], v116 offset:6400
	ds_read_b128 v[76:79], v116 offset:6912
	v_add_f32_dpp v114, v114, v114 quad_perm:[2,3,0,1] row_mask:0xf bank_mask:0xf bound_ctrl:1
	v_add_f32_dpp v115, v115, v115 quad_perm:[2,3,0,1] row_mask:0xf bank_mask:0xf bound_ctrl:1
	v_pk_mul_f32 v[102:103], v[100:101], v[64:65] op_sel_hi:[0,1]
	v_pk_mul_f32 v[104:105], v[100:101], v[64:65] op_sel:[1,0]
	v_pk_fma_f32 v[12:13], v[12:13], v[94:95], v[102:103] op_sel:[0,1,0]
	v_pk_fma_f32 v[32:33], v[32:33], v[94:95], v[104:105] op_sel:[0,1,0]
	v_pk_fma_f32 v[110:111], v[12:13], v[80:81], v[110:111]
	v_pk_fma_f32 v[112:113], v[32:33], v[80:81], v[112:113]
	v_add_f32_dpp v114, v114, v114 row_half_mirror row_mask:0xf bank_mask:0xf bound_ctrl:1
	v_add_f32_dpp v115, v115, v115 row_half_mirror row_mask:0xf bank_mask:0xf bound_ctrl:1
	v_pk_mul_f32 v[106:107], v[100:101], v[66:67] op_sel_hi:[0,1]
	v_pk_mul_f32 v[108:109], v[100:101], v[66:67] op_sel:[1,0]
	v_pk_fma_f32 v[14:15], v[14:15], v[94:95], v[106:107] op_sel:[0,1,0]
	v_pk_fma_f32 v[34:35], v[34:35], v[94:95], v[108:109] op_sel:[0,1,0]
	v_pk_fma_f32 v[110:111], v[14:15], v[82:83], v[110:111]
	v_pk_fma_f32 v[112:113], v[34:35], v[82:83], v[112:113]
	ds_read_b128 v[64:67], v116 offset:6416
	ds_read_b128 v[80:83], v116 offset:6928
	ds_write_b64 v119, v[114:115] offset:768
	v_pk_mul_f32 v[102:103], v[100:101], v[68:69] op_sel_hi:[0,1]
	v_pk_mul_f32 v[104:105], v[100:101], v[68:69] op_sel:[1,0]
	v_pk_fma_f32 v[8:9], v[8:9], v[94:95], v[102:103] op_sel:[0,1,0]
	v_pk_fma_f32 v[20:21], v[20:21], v[94:95], v[104:105] op_sel:[0,1,0]
	v_pk_fma_f32 v[110:111], v[8:9], v[84:85], v[110:111]
	v_pk_fma_f32 v[112:113], v[20:21], v[84:85], v[112:113]
	v_pk_mul_f32 v[106:107], v[100:101], v[70:71] op_sel_hi:[0,1]
	v_pk_mul_f32 v[108:109], v[100:101], v[70:71] op_sel:[1,0]
	v_pk_fma_f32 v[10:11], v[10:11], v[94:95], v[106:107] op_sel:[0,1,0]
	v_pk_fma_f32 v[22:23], v[22:23], v[94:95], v[108:109] op_sel:[0,1,0]
	v_pk_fma_f32 v[110:111], v[10:11], v[86:87], v[110:111]
	v_pk_fma_f32 v[112:113], v[22:23], v[86:87], v[112:113]
	ds_read_b128 v[68:71], v116 offset:6432
	ds_read_b128 v[84:87], v116 offset:6944
	s_waitcnt lgkmcnt(9)
	v_pk_mul_f32 v[102:103], v[100:101], v[72:73] op_sel_hi:[0,1]
	v_pk_mul_f32 v[104:105], v[100:101], v[72:73] op_sel:[1,0]
	v_pk_fma_f32 v[4:5], v[4:5], v[94:95], v[102:103] op_sel:[0,1,0]
	v_pk_fma_f32 v[16:17], v[16:17], v[94:95], v[104:105] op_sel:[0,1,0]
	v_pk_fma_f32 v[110:111], v[4:5], v[88:89], v[110:111]
	v_pk_fma_f32 v[112:113], v[16:17], v[88:89], v[112:113]
	v_pk_mul_f32 v[106:107], v[100:101], v[74:75] op_sel_hi:[0,1]
	v_pk_mul_f32 v[108:109], v[100:101], v[74:75] op_sel:[1,0]
	v_pk_fma_f32 v[6:7], v[6:7], v[94:95], v[106:107] op_sel:[0,1,0]
	v_pk_fma_f32 v[18:19], v[18:19], v[94:95], v[108:109] op_sel:[0,1,0]
	v_pk_fma_f32 v[110:111], v[6:7], v[90:91], v[110:111]
	v_pk_fma_f32 v[112:113], v[18:19], v[90:91], v[112:113]
	ds_read_b128 v[72:75], v116 offset:6448
	ds_read_b128 v[88:91], v116 offset:6960
	v_add_f32_e32 v114, v110, v111
	v_add_f32_e32 v115, v112, v113
	ds_read_b64 v[92:93], v117 offset:8704
	ds_read_b64 v[94:95], v118 offset:41008
	s_waitcnt lgkmcnt(4)
	v_pk_mul_f32 v[100:101], v[96:97], v[98:99] op_sel_hi:[1,0]
	v_pk_mul_f32 v[102:103], v[100:101], v[60:61] op_sel_hi:[0,1]
	v_pk_mul_f32 v[104:105], v[100:101], v[60:61] op_sel:[1,0]
	v_pk_fma_f32 v[28:29], v[28:29], v[98:99], v[102:103] op_sel:[0,1,0]
	v_pk_fma_f32 v[24:25], v[24:25], v[98:99], v[104:105] op_sel:[0,1,0]
	v_pk_mul_f32 v[110:111], v[28:29], v[76:77]
	v_pk_mul_f32 v[112:113], v[24:25], v[76:77]
	v_add_f32_dpp v114, v114, v114 quad_perm:[1,0,3,2] row_mask:0xf bank_mask:0xf bound_ctrl:1
	v_add_f32_dpp v115, v115, v115 quad_perm:[1,0,3,2] row_mask:0xf bank_mask:0xf bound_ctrl:1
	v_pk_mul_f32 v[106:107], v[100:101], v[62:63] op_sel_hi:[0,1]
	v_pk_mul_f32 v[108:109], v[100:101], v[62:63] op_sel:[1,0]
	v_pk_fma_f32 v[30:31], v[30:31], v[98:99], v[106:107] op_sel:[0,1,0]
	v_pk_fma_f32 v[26:27], v[26:27], v[98:99], v[108:109] op_sel:[0,1,0]
	v_pk_fma_f32 v[110:111], v[30:31], v[78:79], v[110:111]
	v_pk_fma_f32 v[112:113], v[26:27], v[78:79], v[112:113]
	ds_read_b128 v[60:63], v116 offset:7680
	ds_read_b128 v[76:79], v116 offset:8192
	v_add_f32_dpp v114, v114, v114 quad_perm:[2,3,0,1] row_mask:0xf bank_mask:0xf bound_ctrl:1
	v_add_f32_dpp v115, v115, v115 quad_perm:[2,3,0,1] row_mask:0xf bank_mask:0xf bound_ctrl:1
	v_pk_mul_f32 v[102:103], v[100:101], v[64:65] op_sel_hi:[0,1]
	v_pk_mul_f32 v[104:105], v[100:101], v[64:65] op_sel:[1,0]
	v_pk_fma_f32 v[12:13], v[12:13], v[98:99], v[102:103] op_sel:[0,1,0]
	v_pk_fma_f32 v[32:33], v[32:33], v[98:99], v[104:105] op_sel:[0,1,0]
; __device__ __forceinline__ float red8(float v) { v = red4(v); v += dppf<0x141>(v); return v; }
; __device__ __forceinline__ f32x2 lo2(const f32x4& v) { return __builtin_shufflevector(v, v, 0, 1); }
; __device__ __forceinline__ f32x2 hi2(const f32x4& v) { return __builtin_shufflevector(v, v, 2, 3); }
; __device__ __forceinline__ f32x2 splat2(float x) { return (f32x2){x, x}; }
; __device__ __forceinline__ void ss_load(SsRegs& R, const float* vb, const float* sb, int t, int n0, int prow0) {
;   const float* vt = vb + t * 320;
; #pragma unroll
;   for (int q = 0; q < 4; ++q) {
;     R.B[q] = *(const f32x4*)(vt + n0 + q * 4);
;     R.C[q] = *(const f32x4*)(vt + 128 + n0 + q * 4);
;   }
;   R.x = *(const f32x2*)(vt + 256 + prow0);
;   R.sc = *(const f32x2*)(sb + t * 2);
; }
; __device__ __forceinline__ f32x2 ss_step(f32x2 (&S)[2][8], const SsRegs& R) {
;   const f32x2 dA2 = splat2(R.sc.y);
;   f32x2 out;
; #pragma unroll
;   for (int r = 0; r < 2; ++r) {
;     const f32x2 xdt2 = splat2((r ? R.x.y : R.x.x) * R.sc.x);
;     f32x2 y0 = splat2(0.f), y1 = splat2(0.f);
; #pragma unroll
;     for (int q = 0; q < 4; ++q) {
;       S[r][2 * q] = S[r][2 * q] * dA2 + xdt2 * lo2(R.B[q]);
;       S[r][2 * q + 1] = S[r][2 * q + 1] * dA2 + xdt2 * hi2(R.B[q]);
;       y0 += S[r][2 * q] * lo2(R.C[q]);
;       y1 += S[r][2 * q + 1] * hi2(R.C[q]);
;     }
;     y0 += y1;
;     const float y = red8(y0.x + y0.y);
;     if (r) out.y = y; else out.x = y;
;   }
;   return out;
; }
	v_pk_fma_f32 v[110:111], v[12:13], v[80:81], v[110:111]
	v_pk_fma_f32 v[112:113], v[32:33], v[80:81], v[112:113]
	v_add_f32_dpp v114, v114, v114 row_half_mirror row_mask:0xf bank_mask:0xf bound_ctrl:1
	v_add_f32_dpp v115, v115, v115 row_half_mirror row_mask:0xf bank_mask:0xf bound_ctrl:1
	v_pk_mul_f32 v[106:107], v[100:101], v[66:67] op_sel_hi:[0,1]
	v_pk_mul_f32 v[108:109], v[100:101], v[66:67] op_sel:[1,0]
	v_pk_fma_f32 v[14:15], v[14:15], v[98:99], v[106:107] op_sel:[0,1,0]
	v_pk_fma_f32 v[34:35], v[34:35], v[98:99], v[108:109] op_sel:[0,1,0]
	v_pk_fma_f32 v[110:111], v[14:15], v[82:83], v[110:111]
	v_pk_fma_f32 v[112:113], v[34:35], v[82:83], v[112:113]
	ds_read_b128 v[64:67], v116 offset:7696
	ds_read_b128 v[80:83], v116 offset:8208
	ds_write_b64 v119, v[114:115] offset:1024
	v_pk_mul_f32 v[102:103], v[100:101], v[68:69] op_sel_hi:[0,1]
	v_pk_mul_f32 v[104:105], v[100:101], v[68:69] op_sel:[1,0]
	v_pk_fma_f32 v[8:9], v[8:9], v[98:99], v[102:103] op_sel:[0,1,0]
	v_pk_fma_f32 v[20:21], v[20:21], v[98:99], v[104:105] op_sel:[0,1,0]
	v_pk_fma_f32 v[110:111], v[8:9], v[84:85], v[110:111]
	v_pk_fma_f32 v[112:113], v[20:21], v[84:85], v[112:113]
	v_pk_mul_f32 v[106:107], v[100:101], v[70:71] op_sel_hi:[0,1]
	v_pk_mul_f32 v[108:109], v[100:101], v[70:71] op_sel:[1,0]
	v_pk_fma_f32 v[10:11], v[10:11], v[98:99], v[106:107] op_sel:[0,1,0]
	v_pk_fma_f32 v[22:23], v[22:23], v[98:99], v[108:109] op_sel:[0,1,0]
	v_pk_fma_f32 v[110:111], v[10:11], v[86:87], v[110:111]
	v_pk_fma_f32 v[112:113], v[22:23], v[86:87], v[112:113]
	ds_read_b128 v[68:71], v116 offset:7712
	ds_read_b128 v[84:87], v116 offset:8224
	s_waitcnt lgkmcnt(9)
	v_pk_mul_f32 v[102:103], v[100:101], v[72:73] op_sel_hi:[0,1]
	v_pk_mul_f32 v[104:105], v[100:101], v[72:73] op_sel:[1,0]
	v_pk_fma_f32 v[4:5], v[4:5], v[98:99], v[102:103] op_sel:[0,1,0]
	v_pk_fma_f32 v[16:17], v[16:17], v[98:99], v[104:105] op_sel:[0,1,0]
	v_pk_fma_f32 v[110:111], v[4:5], v[88:89], v[110:111]
	v_pk_fma_f32 v[112:113], v[16:17], v[88:89], v[112:113]
	v_pk_mul_f32 v[106:107], v[100:101], v[74:75] op_sel_hi:[0,1]
	v_pk_mul_f32 v[108:109], v[100:101], v[74:75] op_sel:[1,0]
	v_pk_fma_f32 v[6:7], v[6:7], v[98:99], v[106:107] op_sel:[0,1,0]
	v_pk_fma_f32 v[18:19], v[18:19], v[98:99], v[108:109] op_sel:[0,1,0]
	v_pk_fma_f32 v[110:111], v[6:7], v[90:91], v[110:111]
	v_pk_fma_f32 v[112:113], v[18:19], v[90:91], v[112:113]
	ds_read_b128 v[72:75], v116 offset:7728
	ds_read_b128 v[88:91], v116 offset:8240
	v_add_f32_e32 v114, v110, v111
	v_add_f32_e32 v115, v112, v113
	ds_read_b64 v[96:97], v117 offset:9984
	ds_read_b64 v[98:99], v118 offset:41016
	s_waitcnt lgkmcnt(4)
	v_pk_mul_f32 v[100:101], v[92:93], v[94:95] op_sel_hi:[1,0]
	v_pk_mul_f32 v[102:103], v[100:101], v[60:61] op_sel_hi:[0,1]
	v_pk_mul_f32 v[104:105], v[100:101], v[60:61] op_sel:[1,0]
	v_pk_fma_f32 v[28:29], v[28:29], v[94:95], v[102:103] op_sel:[0,1,0]
	v_pk_fma_f32 v[24:25], v[24:25], v[94:95], v[104:105] op_sel:[0,1,0]
	v_pk_mul_f32 v[110:111], v[28:29], v[76:77]
	v_pk_mul_f32 v[112:113], v[24:25], v[76:77]
	v_add_f32_dpp v114, v114, v114 quad_perm:[1,0,3,2] row_mask:0xf bank_mask:0xf bound_ctrl:1
	v_add_f32_dpp v115, v115, v115 quad_perm:[1,0,3,2] row_mask:0xf bank_mask:0xf bound_ctrl:1
	v_pk_mul_f32 v[106:107], v[100:101], v[62:63] op_sel_hi:[0,1]
	v_pk_mul_f32 v[108:109], v[100:101], v[62:63] op_sel:[1,0]
	v_pk_fma_f32 v[30:31], v[30:31], v[94:95], v[106:107] op_sel:[0,1,0]
	v_pk_fma_f32 v[26:27], v[26:27], v[94:95], v[108:109] op_sel:[0,1,0]
	v_pk_fma_f32 v[110:111], v[30:31], v[78:79], v[110:111]
	v_pk_fma_f32 v[112:113], v[26:27], v[78:79], v[112:113]
	ds_read_b128 v[60:63], v116 offset:8960
	ds_read_b128 v[76:79], v116 offset:9472
	v_add_f32_dpp v114, v114, v114 quad_perm:[2,3,0,1] row_mask:0xf bank_mask:0xf bound_ctrl:1
	v_add_f32_dpp v115, v115, v115 quad_perm:[2,3,0,1] row_mask:0xf bank_mask:0xf bound_ctrl:1
	v_pk_mul_f32 v[102:103], v[100:101], v[64:65] op_sel_hi:[0,1]
	v_pk_mul_f32 v[104:105], v[100:101], v[64:65] op_sel:[1,0]
	v_pk_fma_f32 v[12:13], v[12:13], v[94:95], v[102:103] op_sel:[0,1,0]
	v_pk_fma_f32 v[32:33], v[32:33], v[94:95], v[104:105] op_sel:[0,1,0]
	v_pk_fma_f32 v[110:111], v[12:13], v[80:81], v[110:111]
	v_pk_fma_f32 v[112:113], v[32:33], v[80:81], v[112:113]
	v_add_f32_dpp v114, v114, v114 row_half_mirror row_mask:0xf bank_mask:0xf bound_ctrl:1
	v_add_f32_dpp v115, v115, v115 row_half_mirror row_mask:0xf bank_mask:0xf bound_ctrl:1
	v_pk_mul_f32 v[106:107], v[100:101], v[66:67] op_sel_hi:[0,1]
	v_pk_mul_f32 v[108:109], v[100:101], v[66:67] op_sel:[1,0]
	v_pk_fma_f32 v[14:15], v[14:15], v[94:95], v[106:107] op_sel:[0,1,0]
	v_pk_fma_f32 v[34:35], v[34:35], v[94:95], v[108:109] op_sel:[0,1,0]
	v_pk_fma_f32 v[110:111], v[14:15], v[82:83], v[110:111]
	v_pk_fma_f32 v[112:113], v[34:35], v[82:83], v[112:113]
	ds_read_b128 v[64:67], v116 offset:8976
	ds_read_b128 v[80:83], v116 offset:9488
	ds_write_b64 v119, v[114:115] offset:1280
	v_pk_mul_f32 v[102:103], v[100:101], v[68:69] op_sel_hi:[0,1]
	v_pk_mul_f32 v[104:105], v[100:101], v[68:69] op_sel:[1,0]
	v_pk_fma_f32 v[8:9], v[8:9], v[94:95], v[102:103] op_sel:[0,1,0]
	v_pk_fma_f32 v[20:21], v[20:21], v[94:95], v[104:105] op_sel:[0,1,0]
	v_pk_fma_f32 v[110:111], v[8:9], v[84:85], v[110:111]
	v_pk_fma_f32 v[112:113], v[20:21], v[84:85], v[112:113]
	v_pk_mul_f32 v[106:107], v[100:101], v[70:71] op_sel_hi:[0,1]
	v_pk_mul_f32 v[108:109], v[100:101], v[70:71] op_sel:[1,0]
	v_pk_fma_f32 v[10:11], v[10:11], v[94:95], v[106:107] op_sel:[0,1,0]
	v_pk_fma_f32 v[22:23], v[22:23], v[94:95], v[108:109] op_sel:[0,1,0]
	v_pk_fma_f32 v[110:111], v[10:11], v[86:87], v[110:111]
	v_pk_fma_f32 v[112:113], v[22:23], v[86:87], v[112:113]
	ds_read_b128 v[68:71], v116 offset:8992
	ds_read_b128 v[84:87], v116 offset:9504
	s_waitcnt lgkmcnt(9)
; __device__ __forceinline__ float red8(float v) { v = red4(v); v += dppf<0x141>(v); return v; }
; __device__ __forceinline__ f32x2 lo2(const f32x4& v) { return __builtin_shufflevector(v, v, 0, 1); }
; __device__ __forceinline__ f32x2 hi2(const f32x4& v) { return __builtin_shufflevector(v, v, 2, 3); }
; __device__ __forceinline__ f32x2 splat2(float x) { return (f32x2){x, x}; }
; __device__ __forceinline__ void ss_load(SsRegs& R, const float* vb, const float* sb, int t, int n0, int prow0) {
;   const float* vt = vb + t * 320;
; #pragma unroll
;   for (int q = 0; q < 4; ++q) {
;     R.B[q] = *(const f32x4*)(vt + n0 + q * 4);
;     R.C[q] = *(const f32x4*)(vt + 128 + n0 + q * 4);
;   }
;   R.x = *(const f32x2*)(vt + 256 + prow0);
;   R.sc = *(const f32x2*)(sb + t * 2);
; }
; __device__ __forceinline__ f32x2 ss_step(f32x2 (&S)[2][8], const SsRegs& R) {
;   const f32x2 dA2 = splat2(R.sc.y);
;   f32x2 out;
; #pragma unroll
;   for (int r = 0; r < 2; ++r) {
;     const f32x2 xdt2 = splat2((r ? R.x.y : R.x.x) * R.sc.x);
;     f32x2 y0 = splat2(0.f), y1 = splat2(0.f);
; #pragma unroll
;     for (int q = 0; q < 4; ++q) {
;       S[r][2 * q] = S[r][2 * q] * dA2 + xdt2 * lo2(R.B[q]);
;       S[r][2 * q + 1] = S[r][2 * q + 1] * dA2 + xdt2 * hi2(R.B[q]);
;       y0 += S[r][2 * q] * lo2(R.C[q]);
;       y1 += S[r][2 * q + 1] * hi2(R.C[q]);
;     }
;     y0 += y1;
;     const float y = red8(y0.x + y0.y);
;     if (r) out.y = y; else out.x = y;
;   }
;   return out;
; }
	v_pk_mul_f32 v[102:103], v[100:101], v[72:73] op_sel_hi:[0,1]
	v_pk_mul_f32 v[104:105], v[100:101], v[72:73] op_sel:[1,0]
	v_pk_fma_f32 v[4:5], v[4:5], v[94:95], v[102:103] op_sel:[0,1,0]
	v_pk_fma_f32 v[16:17], v[16:17], v[94:95], v[104:105] op_sel:[0,1,0]
	v_pk_fma_f32 v[110:111], v[4:5], v[88:89], v[110:111]
	v_pk_fma_f32 v[112:113], v[16:17], v[88:89], v[112:113]
	v_pk_mul_f32 v[106:107], v[100:101], v[74:75] op_sel_hi:[0,1]
	v_pk_mul_f32 v[108:109], v[100:101], v[74:75] op_sel:[1,0]
	v_pk_fma_f32 v[6:7], v[6:7], v[94:95], v[106:107] op_sel:[0,1,0]
	v_pk_fma_f32 v[18:19], v[18:19], v[94:95], v[108:109] op_sel:[0,1,0]
	v_pk_fma_f32 v[110:111], v[6:7], v[90:91], v[110:111]
	v_pk_fma_f32 v[112:113], v[18:19], v[90:91], v[112:113]
	ds_read_b128 v[72:75], v116 offset:9008
	ds_read_b128 v[88:91], v116 offset:9520
	v_add_f32_e32 v114, v110, v111
	v_add_f32_e32 v115, v112, v113
	ds_read_b64 v[92:93], v117 offset:11264
	ds_read_b64 v[94:95], v118 offset:41024
	s_waitcnt lgkmcnt(4)
	v_pk_mul_f32 v[100:101], v[96:97], v[98:99] op_sel_hi:[1,0]
	v_pk_mul_f32 v[102:103], v[100:101], v[60:61] op_sel_hi:[0,1]
	v_pk_mul_f32 v[104:105], v[100:101], v[60:61] op_sel:[1,0]
	v_pk_fma_f32 v[28:29], v[28:29], v[98:99], v[102:103] op_sel:[0,1,0]
	v_pk_fma_f32 v[24:25], v[24:25], v[98:99], v[104:105] op_sel:[0,1,0]
	v_pk_mul_f32 v[110:111], v[28:29], v[76:77]
	v_pk_mul_f32 v[112:113], v[24:25], v[76:77]
	v_add_f32_dpp v114, v114, v114 quad_perm:[1,0,3,2] row_mask:0xf bank_mask:0xf bound_ctrl:1
	v_add_f32_dpp v115, v115, v115 quad_perm:[1,0,3,2] row_mask:0xf bank_mask:0xf bound_ctrl:1
	v_pk_mul_f32 v[106:107], v[100:101], v[62:63] op_sel_hi:[0,1]
	v_pk_mul_f32 v[108:109], v[100:101], v[62:63] op_sel:[1,0]
	v_pk_fma_f32 v[30:31], v[30:31], v[98:99], v[106:107] op_sel:[0,1,0]
	v_pk_fma_f32 v[26:27], v[26:27], v[98:99], v[108:109] op_sel:[0,1,0]
	v_pk_fma_f32 v[110:111], v[30:31], v[78:79], v[110:111]
	v_pk_fma_f32 v[112:113], v[26:27], v[78:79], v[112:113]
	ds_read_b128 v[60:63], v116 offset:10240
	ds_read_b128 v[76:79], v116 offset:10752
	v_add_f32_dpp v114, v114, v114 quad_perm:[2,3,0,1] row_mask:0xf bank_mask:0xf bound_ctrl:1
	v_add_f32_dpp v115, v115, v115 quad_perm:[2,3,0,1] row_mask:0xf bank_mask:0xf bound_ctrl:1
	v_pk_mul_f32 v[102:103], v[100:101], v[64:65] op_sel_hi:[0,1]
	v_pk_mul_f32 v[104:105], v[100:101], v[64:65] op_sel:[1,0]
	v_pk_fma_f32 v[12:13], v[12:13], v[98:99], v[102:103] op_sel:[0,1,0]
	v_pk_fma_f32 v[32:33], v[32:33], v[98:99], v[104:105] op_sel:[0,1,0]
	v_pk_fma_f32 v[110:111], v[12:13], v[80:81], v[110:111]
	v_pk_fma_f32 v[112:113], v[32:33], v[80:81], v[112:113]
	v_add_f32_dpp v114, v114, v114 row_half_mirror row_mask:0xf bank_mask:0xf bound_ctrl:1
	v_add_f32_dpp v115, v115, v115 row_half_mirror row_mask:0xf bank_mask:0xf bound_ctrl:1
	v_pk_mul_f32 v[106:107], v[100:101], v[66:67] op_sel_hi:[0,1]
	v_pk_mul_f32 v[108:109], v[100:101], v[66:67] op_sel:[1,0]
	v_pk_fma_f32 v[14:15], v[14:15], v[98:99], v[106:107] op_sel:[0,1,0]
	v_pk_fma_f32 v[34:35], v[34:35], v[98:99], v[108:109] op_sel:[0,1,0]
	v_pk_fma_f32 v[110:111], v[14:15], v[82:83], v[110:111]
	v_pk_fma_f32 v[112:113], v[34:35], v[82:83], v[112:113]
	ds_read_b128 v[64:67], v116 offset:10256
	ds_read_b128 v[80:83], v116 offset:10768
	ds_write_b64 v119, v[114:115] offset:1536
	v_pk_mul_f32 v[102:103], v[100:101], v[68:69] op_sel_hi:[0,1]
	v_pk_mul_f32 v[104:105], v[100:101], v[68:69] op_sel:[1,0]
	v_pk_fma_f32 v[8:9], v[8:9], v[98:99], v[102:103] op_sel:[0,1,0]
	v_pk_fma_f32 v[20:21], v[20:21], v[98:99], v[104:105] op_sel:[0,1,0]
	v_pk_fma_f32 v[110:111], v[8:9], v[84:85], v[110:111]
	v_pk_fma_f32 v[112:113], v[20:21], v[84:85], v[112:113]
	v_pk_mul_f32 v[106:107], v[100:101], v[70:71] op_sel_hi:[0,1]
	v_pk_mul_f32 v[108:109], v[100:101], v[70:71] op_sel:[1,0]
	v_pk_fma_f32 v[10:11], v[10:11], v[98:99], v[106:107] op_sel:[0,1,0]
	v_pk_fma_f32 v[22:23], v[22:23], v[98:99], v[108:109] op_sel:[0,1,0]
	v_pk_fma_f32 v[110:111], v[10:11], v[86:87], v[110:111]
	v_pk_fma_f32 v[112:113], v[22:23], v[86:87], v[112:113]
	ds_read_b128 v[68:71], v116 offset:10272
	ds_read_b128 v[84:87], v116 offset:10784
	s_waitcnt lgkmcnt(9)
	v_pk_mul_f32 v[102:103], v[100:101], v[72:73] op_sel_hi:[0,1]
	v_pk_mul_f32 v[104:105], v[100:101], v[72:73] op_sel:[1,0]
	v_pk_fma_f32 v[4:5], v[4:5], v[98:99], v[102:103] op_sel:[0,1,0]
	v_pk_fma_f32 v[16:17], v[16:17], v[98:99], v[104:105] op_sel:[0,1,0]
	v_pk_fma_f32 v[110:111], v[4:5], v[88:89], v[110:111]
	v_pk_fma_f32 v[112:113], v[16:17], v[88:89], v[112:113]
	v_pk_mul_f32 v[106:107], v[100:101], v[74:75] op_sel_hi:[0,1]
	v_pk_mul_f32 v[108:109], v[100:101], v[74:75] op_sel:[1,0]
	v_pk_fma_f32 v[6:7], v[6:7], v[98:99], v[106:107] op_sel:[0,1,0]
	v_pk_fma_f32 v[18:19], v[18:19], v[98:99], v[108:109] op_sel:[0,1,0]
	v_pk_fma_f32 v[110:111], v[6:7], v[90:91], v[110:111]
	v_pk_fma_f32 v[112:113], v[18:19], v[90:91], v[112:113]
	ds_read_b128 v[72:75], v116 offset:10288
	ds_read_b128 v[88:91], v116 offset:10800
	v_add_f32_e32 v114, v110, v111
	v_add_f32_e32 v115, v112, v113
	ds_read_b64 v[96:97], v117 offset:12544
	ds_read_b64 v[98:99], v118 offset:41032
	s_waitcnt lgkmcnt(4)
; __device__ __forceinline__ float red8(float v) { v = red4(v); v += dppf<0x141>(v); return v; }
; __device__ __forceinline__ f32x2 lo2(const f32x4& v) { return __builtin_shufflevector(v, v, 0, 1); }
; __device__ __forceinline__ f32x2 hi2(const f32x4& v) { return __builtin_shufflevector(v, v, 2, 3); }
; __device__ __forceinline__ f32x2 splat2(float x) { return (f32x2){x, x}; }
; __device__ __forceinline__ void ss_load(SsRegs& R, const float* vb, const float* sb, int t, int n0, int prow0) {
;   const float* vt = vb + t * 320;
; #pragma unroll
;   for (int q = 0; q < 4; ++q) {
;     R.B[q] = *(const f32x4*)(vt + n0 + q * 4);
;     R.C[q] = *(const f32x4*)(vt + 128 + n0 + q * 4);
;   }
;   R.x = *(const f32x2*)(vt + 256 + prow0);
;   R.sc = *(const f32x2*)(sb + t * 2);
; }
; __device__ __forceinline__ f32x2 ss_step(f32x2 (&S)[2][8], const SsRegs& R) {
;   const f32x2 dA2 = splat2(R.sc.y);
;   f32x2 out;
; #pragma unroll
;   for (int r = 0; r < 2; ++r) {
;     const f32x2 xdt2 = splat2((r ? R.x.y : R.x.x) * R.sc.x);
;     f32x2 y0 = splat2(0.f), y1 = splat2(0.f);
; #pragma unroll
;     for (int q = 0; q < 4; ++q) {
;       S[r][2 * q] = S[r][2 * q] * dA2 + xdt2 * lo2(R.B[q]);
;       S[r][2 * q + 1] = S[r][2 * q + 1] * dA2 + xdt2 * hi2(R.B[q]);
;       y0 += S[r][2 * q] * lo2(R.C[q]);
;       y1 += S[r][2 * q + 1] * hi2(R.C[q]);
;     }
;     y0 += y1;
;     const float y = red8(y0.x + y0.y);
;     if (r) out.y = y; else out.x = y;
;   }
;   return out;
; }
	v_pk_mul_f32 v[100:101], v[92:93], v[94:95] op_sel_hi:[1,0]
	v_pk_mul_f32 v[102:103], v[100:101], v[60:61] op_sel_hi:[0,1]
	v_pk_mul_f32 v[104:105], v[100:101], v[60:61] op_sel:[1,0]
	v_pk_fma_f32 v[28:29], v[28:29], v[94:95], v[102:103] op_sel:[0,1,0]
	v_pk_fma_f32 v[24:25], v[24:25], v[94:95], v[104:105] op_sel:[0,1,0]
	v_pk_mul_f32 v[110:111], v[28:29], v[76:77]
	v_pk_mul_f32 v[112:113], v[24:25], v[76:77]
	v_add_f32_dpp v114, v114, v114 quad_perm:[1,0,3,2] row_mask:0xf bank_mask:0xf bound_ctrl:1
	v_add_f32_dpp v115, v115, v115 quad_perm:[1,0,3,2] row_mask:0xf bank_mask:0xf bound_ctrl:1
	v_pk_mul_f32 v[106:107], v[100:101], v[62:63] op_sel_hi:[0,1]
	v_pk_mul_f32 v[108:109], v[100:101], v[62:63] op_sel:[1,0]
	v_pk_fma_f32 v[30:31], v[30:31], v[94:95], v[106:107] op_sel:[0,1,0]
	v_pk_fma_f32 v[26:27], v[26:27], v[94:95], v[108:109] op_sel:[0,1,0]
	v_pk_fma_f32 v[110:111], v[30:31], v[78:79], v[110:111]
	v_pk_fma_f32 v[112:113], v[26:27], v[78:79], v[112:113]
	ds_read_b128 v[60:63], v116 offset:11520
	ds_read_b128 v[76:79], v116 offset:12032
	v_add_f32_dpp v114, v114, v114 quad_perm:[2,3,0,1] row_mask:0xf bank_mask:0xf bound_ctrl:1
	v_add_f32_dpp v115, v115, v115 quad_perm:[2,3,0,1] row_mask:0xf bank_mask:0xf bound_ctrl:1
	v_pk_mul_f32 v[102:103], v[100:101], v[64:65] op_sel_hi:[0,1]
	v_pk_mul_f32 v[104:105], v[100:101], v[64:65] op_sel:[1,0]
	v_pk_fma_f32 v[12:13], v[12:13], v[94:95], v[102:103] op_sel:[0,1,0]
	v_pk_fma_f32 v[32:33], v[32:33], v[94:95], v[104:105] op_sel:[0,1,0]
	v_pk_fma_f32 v[110:111], v[12:13], v[80:81], v[110:111]
	v_pk_fma_f32 v[112:113], v[32:33], v[80:81], v[112:113]
	v_add_f32_dpp v114, v114, v114 row_half_mirror row_mask:0xf bank_mask:0xf bound_ctrl:1
	v_add_f32_dpp v115, v115, v115 row_half_mirror row_mask:0xf bank_mask:0xf bound_ctrl:1
	v_pk_mul_f32 v[106:107], v[100:101], v[66:67] op_sel_hi:[0,1]
	v_pk_mul_f32 v[108:109], v[100:101], v[66:67] op_sel:[1,0]
	v_pk_fma_f32 v[14:15], v[14:15], v[94:95], v[106:107] op_sel:[0,1,0]
	v_pk_fma_f32 v[34:35], v[34:35], v[94:95], v[108:109] op_sel:[0,1,0]
	v_pk_fma_f32 v[110:111], v[14:15], v[82:83], v[110:111]
	v_pk_fma_f32 v[112:113], v[34:35], v[82:83], v[112:113]
	ds_read_b128 v[64:67], v116 offset:11536
	ds_read_b128 v[80:83], v116 offset:12048
	ds_write_b64 v119, v[114:115] offset:1792
	v_pk_mul_f32 v[102:103], v[100:101], v[68:69] op_sel_hi:[0,1]
	v_pk_mul_f32 v[104:105], v[100:101], v[68:69] op_sel:[1,0]
	v_pk_fma_f32 v[8:9], v[8:9], v[94:95], v[102:103] op_sel:[0,1,0]
	v_pk_fma_f32 v[20:21], v[20:21], v[94:95], v[104:105] op_sel:[0,1,0]
	v_pk_fma_f32 v[110:111], v[8:9], v[84:85], v[110:111]
	v_pk_fma_f32 v[112:113], v[20:21], v[84:85], v[112:113]
	v_pk_mul_f32 v[106:107], v[100:101], v[70:71] op_sel_hi:[0,1]
	v_pk_mul_f32 v[108:109], v[100:101], v[70:71] op_sel:[1,0]
	v_pk_fma_f32 v[10:11], v[10:11], v[94:95], v[106:107] op_sel:[0,1,0]
	v_pk_fma_f32 v[22:23], v[22:23], v[94:95], v[108:109] op_sel:[0,1,0]
	v_pk_fma_f32 v[110:111], v[10:11], v[86:87], v[110:111]
	v_pk_fma_f32 v[112:113], v[22:23], v[86:87], v[112:113]
	ds_read_b128 v[68:71], v116 offset:11552
	ds_read_b128 v[84:87], v116 offset:12064
	s_waitcnt lgkmcnt(9)
	v_pk_mul_f32 v[102:103], v[100:101], v[72:73] op_sel_hi:[0,1]
	v_pk_mul_f32 v[104:105], v[100:101], v[72:73] op_sel:[1,0]
	v_pk_fma_f32 v[4:5], v[4:5], v[94:95], v[102:103] op_sel:[0,1,0]
	v_pk_fma_f32 v[16:17], v[16:17], v[94:95], v[104:105] op_sel:[0,1,0]
	v_pk_fma_f32 v[110:111], v[4:5], v[88:89], v[110:111]
	v_pk_fma_f32 v[112:113], v[16:17], v[88:89], v[112:113]
	v_pk_mul_f32 v[106:107], v[100:101], v[74:75] op_sel_hi:[0,1]
	v_pk_mul_f32 v[108:109], v[100:101], v[74:75] op_sel:[1,0]
	v_pk_fma_f32 v[6:7], v[6:7], v[94:95], v[106:107] op_sel:[0,1,0]
	v_pk_fma_f32 v[18:19], v[18:19], v[94:95], v[108:109] op_sel:[0,1,0]
	v_pk_fma_f32 v[110:111], v[6:7], v[90:91], v[110:111]
	v_pk_fma_f32 v[112:113], v[18:19], v[90:91], v[112:113]
	ds_read_b128 v[72:75], v116 offset:11568
	ds_read_b128 v[88:91], v116 offset:12080
	v_add_f32_e32 v114, v110, v111
	v_add_f32_e32 v115, v112, v113
	ds_read_b64 v[92:93], v117 offset:13824
	ds_read_b64 v[94:95], v118 offset:41040
	s_waitcnt lgkmcnt(4)
	v_pk_mul_f32 v[100:101], v[96:97], v[98:99] op_sel_hi:[1,0]
	v_pk_mul_f32 v[102:103], v[100:101], v[60:61] op_sel_hi:[0,1]
	v_pk_mul_f32 v[104:105], v[100:101], v[60:61] op_sel:[1,0]
	v_pk_fma_f32 v[28:29], v[28:29], v[98:99], v[102:103] op_sel:[0,1,0]
	v_pk_fma_f32 v[24:25], v[24:25], v[98:99], v[104:105] op_sel:[0,1,0]
	v_pk_mul_f32 v[110:111], v[28:29], v[76:77]
	v_pk_mul_f32 v[112:113], v[24:25], v[76:77]
	v_add_f32_dpp v114, v114, v114 quad_perm:[1,0,3,2] row_mask:0xf bank_mask:0xf bound_ctrl:1
	v_add_f32_dpp v115, v115, v115 quad_perm:[1,0,3,2] row_mask:0xf bank_mask:0xf bound_ctrl:1
	v_pk_mul_f32 v[106:107], v[100:101], v[62:63] op_sel_hi:[0,1]
	v_pk_mul_f32 v[108:109], v[100:101], v[62:63] op_sel:[1,0]
	v_pk_fma_f32 v[30:31], v[30:31], v[98:99], v[106:107] op_sel:[0,1,0]
	v_pk_fma_f32 v[26:27], v[26:27], v[98:99], v[108:109] op_sel:[0,1,0]
	v_pk_fma_f32 v[110:111], v[30:31], v[78:79], v[110:111]
	v_pk_fma_f32 v[112:113], v[26:27], v[78:79], v[112:113]
	ds_read_b128 v[60:63], v116 offset:12800
	ds_read_b128 v[76:79], v116 offset:13312
	v_add_f32_dpp v114, v114, v114 quad_perm:[2,3,0,1] row_mask:0xf bank_mask:0xf bound_ctrl:1
	v_add_f32_dpp v115, v115, v115 quad_perm:[2,3,0,1] row_mask:0xf bank_mask:0xf bound_ctrl:1
	v_pk_mul_f32 v[102:103], v[100:101], v[64:65] op_sel_hi:[0,1]
	v_pk_mul_f32 v[104:105], v[100:101], v[64:65] op_sel:[1,0]
	v_pk_fma_f32 v[12:13], v[12:13], v[98:99], v[102:103] op_sel:[0,1,0]
	v_pk_fma_f32 v[32:33], v[32:33], v[98:99], v[104:105] op_sel:[0,1,0]
; __device__ __forceinline__ float red8(float v) { v = red4(v); v += dppf<0x141>(v); return v; }
; __device__ __forceinline__ f32x2 lo2(const f32x4& v) { return __builtin_shufflevector(v, v, 0, 1); }
; __device__ __forceinline__ f32x2 hi2(const f32x4& v) { return __builtin_shufflevector(v, v, 2, 3); }
; __device__ __forceinline__ f32x2 splat2(float x) { return (f32x2){x, x}; }
; __device__ __forceinline__ void ss_load(SsRegs& R, const float* vb, const float* sb, int t, int n0, int prow0) {
;   const float* vt = vb + t * 320;
; #pragma unroll
;   for (int q = 0; q < 4; ++q) {
;     R.B[q] = *(const f32x4*)(vt + n0 + q * 4);
;     R.C[q] = *(const f32x4*)(vt + 128 + n0 + q * 4);
;   }
;   R.x = *(const f32x2*)(vt + 256 + prow0);
;   R.sc = *(const f32x2*)(sb + t * 2);
; }
; __device__ __forceinline__ f32x2 ss_step(f32x2 (&S)[2][8], const SsRegs& R) {
;   const f32x2 dA2 = splat2(R.sc.y);
;   f32x2 out;
; #pragma unroll
;   for (int r = 0; r < 2; ++r) {
;     const f32x2 xdt2 = splat2((r ? R.x.y : R.x.x) * R.sc.x);
;     f32x2 y0 = splat2(0.f), y1 = splat2(0.f);
; #pragma unroll
;     for (int q = 0; q < 4; ++q) {
;       S[r][2 * q] = S[r][2 * q] * dA2 + xdt2 * lo2(R.B[q]);
;       S[r][2 * q + 1] = S[r][2 * q + 1] * dA2 + xdt2 * hi2(R.B[q]);
;       y0 += S[r][2 * q] * lo2(R.C[q]);
;       y1 += S[r][2 * q + 1] * hi2(R.C[q]);
;     }
;     y0 += y1;
;     const float y = red8(y0.x + y0.y);
;     if (r) out.y = y; else out.x = y;
;   }
;   return out;
; }
	v_pk_fma_f32 v[110:111], v[12:13], v[80:81], v[110:111]
	v_pk_fma_f32 v[112:113], v[32:33], v[80:81], v[112:113]
	v_add_f32_dpp v114, v114, v114 row_half_mirror row_mask:0xf bank_mask:0xf bound_ctrl:1
	v_add_f32_dpp v115, v115, v115 row_half_mirror row_mask:0xf bank_mask:0xf bound_ctrl:1
	v_pk_mul_f32 v[106:107], v[100:101], v[66:67] op_sel_hi:[0,1]
	v_pk_mul_f32 v[108:109], v[100:101], v[66:67] op_sel:[1,0]
	v_pk_fma_f32 v[14:15], v[14:15], v[98:99], v[106:107] op_sel:[0,1,0]
	v_pk_fma_f32 v[34:35], v[34:35], v[98:99], v[108:109] op_sel:[0,1,0]
	v_pk_fma_f32 v[110:111], v[14:15], v[82:83], v[110:111]
	v_pk_fma_f32 v[112:113], v[34:35], v[82:83], v[112:113]
	ds_read_b128 v[64:67], v116 offset:12816
	ds_read_b128 v[80:83], v116 offset:13328
	ds_write_b64 v119, v[114:115] offset:2048
	v_pk_mul_f32 v[102:103], v[100:101], v[68:69] op_sel_hi:[0,1]
	v_pk_mul_f32 v[104:105], v[100:101], v[68:69] op_sel:[1,0]
	v_pk_fma_f32 v[8:9], v[8:9], v[98:99], v[102:103] op_sel:[0,1,0]
	v_pk_fma_f32 v[20:21], v[20:21], v[98:99], v[104:105] op_sel:[0,1,0]
	v_pk_fma_f32 v[110:111], v[8:9], v[84:85], v[110:111]
	v_pk_fma_f32 v[112:113], v[20:21], v[84:85], v[112:113]
	v_pk_mul_f32 v[106:107], v[100:101], v[70:71] op_sel_hi:[0,1]
	v_pk_mul_f32 v[108:109], v[100:101], v[70:71] op_sel:[1,0]
	v_pk_fma_f32 v[10:11], v[10:11], v[98:99], v[106:107] op_sel:[0,1,0]
	v_pk_fma_f32 v[22:23], v[22:23], v[98:99], v[108:109] op_sel:[0,1,0]
	v_pk_fma_f32 v[110:111], v[10:11], v[86:87], v[110:111]
	v_pk_fma_f32 v[112:113], v[22:23], v[86:87], v[112:113]
	ds_read_b128 v[68:71], v116 offset:12832
	ds_read_b128 v[84:87], v116 offset:13344
	s_waitcnt lgkmcnt(9)
	v_pk_mul_f32 v[102:103], v[100:101], v[72:73] op_sel_hi:[0,1]
	v_pk_mul_f32 v[104:105], v[100:101], v[72:73] op_sel:[1,0]
	v_pk_fma_f32 v[4:5], v[4:5], v[98:99], v[102:103] op_sel:[0,1,0]
	v_pk_fma_f32 v[16:17], v[16:17], v[98:99], v[104:105] op_sel:[0,1,0]
	v_pk_fma_f32 v[110:111], v[4:5], v[88:89], v[110:111]
	v_pk_fma_f32 v[112:113], v[16:17], v[88:89], v[112:113]
	v_pk_mul_f32 v[106:107], v[100:101], v[74:75] op_sel_hi:[0,1]
	v_pk_mul_f32 v[108:109], v[100:101], v[74:75] op_sel:[1,0]
	v_pk_fma_f32 v[6:7], v[6:7], v[98:99], v[106:107] op_sel:[0,1,0]
	v_pk_fma_f32 v[18:19], v[18:19], v[98:99], v[108:109] op_sel:[0,1,0]
	v_pk_fma_f32 v[110:111], v[6:7], v[90:91], v[110:111]
	v_pk_fma_f32 v[112:113], v[18:19], v[90:91], v[112:113]
	ds_read_b128 v[72:75], v116 offset:12848
	ds_read_b128 v[88:91], v116 offset:13360
	v_add_f32_e32 v114, v110, v111
	v_add_f32_e32 v115, v112, v113
	ds_read_b64 v[96:97], v117 offset:15104
	ds_read_b64 v[98:99], v118 offset:41048
	s_waitcnt lgkmcnt(4)
	v_pk_mul_f32 v[100:101], v[92:93], v[94:95] op_sel_hi:[1,0]
	v_pk_mul_f32 v[102:103], v[100:101], v[60:61] op_sel_hi:[0,1]
	v_pk_mul_f32 v[104:105], v[100:101], v[60:61] op_sel:[1,0]
	v_pk_fma_f32 v[28:29], v[28:29], v[94:95], v[102:103] op_sel:[0,1,0]
	v_pk_fma_f32 v[24:25], v[24:25], v[94:95], v[104:105] op_sel:[0,1,0]
	v_pk_mul_f32 v[110:111], v[28:29], v[76:77]
	v_pk_mul_f32 v[112:113], v[24:25], v[76:77]
	v_add_f32_dpp v114, v114, v114 quad_perm:[1,0,3,2] row_mask:0xf bank_mask:0xf bound_ctrl:1
	v_add_f32_dpp v115, v115, v115 quad_perm:[1,0,3,2] row_mask:0xf bank_mask:0xf bound_ctrl:1
	v_pk_mul_f32 v[106:107], v[100:101], v[62:63] op_sel_hi:[0,1]
	v_pk_mul_f32 v[108:109], v[100:101], v[62:63] op_sel:[1,0]
	v_pk_fma_f32 v[30:31], v[30:31], v[94:95], v[106:107] op_sel:[0,1,0]
	v_pk_fma_f32 v[26:27], v[26:27], v[94:95], v[108:109] op_sel:[0,1,0]
	v_pk_fma_f32 v[110:111], v[30:31], v[78:79], v[110:111]
	v_pk_fma_f32 v[112:113], v[26:27], v[78:79], v[112:113]
	ds_read_b128 v[60:63], v116 offset:14080
	ds_read_b128 v[76:79], v116 offset:14592
	v_add_f32_dpp v114, v114, v114 quad_perm:[2,3,0,1] row_mask:0xf bank_mask:0xf bound_ctrl:1
	v_add_f32_dpp v115, v115, v115 quad_perm:[2,3,0,1] row_mask:0xf bank_mask:0xf bound_ctrl:1
	v_pk_mul_f32 v[102:103], v[100:101], v[64:65] op_sel_hi:[0,1]
	v_pk_mul_f32 v[104:105], v[100:101], v[64:65] op_sel:[1,0]
	v_pk_fma_f32 v[12:13], v[12:13], v[94:95], v[102:103] op_sel:[0,1,0]
	v_pk_fma_f32 v[32:33], v[32:33], v[94:95], v[104:105] op_sel:[0,1,0]
	v_pk_fma_f32 v[110:111], v[12:13], v[80:81], v[110:111]
	v_pk_fma_f32 v[112:113], v[32:33], v[80:81], v[112:113]
	v_add_f32_dpp v114, v114, v114 row_half_mirror row_mask:0xf bank_mask:0xf bound_ctrl:1
	v_add_f32_dpp v115, v115, v115 row_half_mirror row_mask:0xf bank_mask:0xf bound_ctrl:1
	v_pk_mul_f32 v[106:107], v[100:101], v[66:67] op_sel_hi:[0,1]
	v_pk_mul_f32 v[108:109], v[100:101], v[66:67] op_sel:[1,0]
	v_pk_fma_f32 v[14:15], v[14:15], v[94:95], v[106:107] op_sel:[0,1,0]
	v_pk_fma_f32 v[34:35], v[34:35], v[94:95], v[108:109] op_sel:[0,1,0]
	v_pk_fma_f32 v[110:111], v[14:15], v[82:83], v[110:111]
	v_pk_fma_f32 v[112:113], v[34:35], v[82:83], v[112:113]
	ds_read_b128 v[64:67], v116 offset:14096
	ds_read_b128 v[80:83], v116 offset:14608
	ds_write_b64 v119, v[114:115] offset:2304
	v_pk_mul_f32 v[102:103], v[100:101], v[68:69] op_sel_hi:[0,1]
	v_pk_mul_f32 v[104:105], v[100:101], v[68:69] op_sel:[1,0]
	v_pk_fma_f32 v[8:9], v[8:9], v[94:95], v[102:103] op_sel:[0,1,0]
	v_pk_fma_f32 v[20:21], v[20:21], v[94:95], v[104:105] op_sel:[0,1,0]
	v_pk_fma_f32 v[110:111], v[8:9], v[84:85], v[110:111]
	v_pk_fma_f32 v[112:113], v[20:21], v[84:85], v[112:113]
	v_pk_mul_f32 v[106:107], v[100:101], v[70:71] op_sel_hi:[0,1]
	v_pk_mul_f32 v[108:109], v[100:101], v[70:71] op_sel:[1,0]
	v_pk_fma_f32 v[10:11], v[10:11], v[94:95], v[106:107] op_sel:[0,1,0]
	v_pk_fma_f32 v[22:23], v[22:23], v[94:95], v[108:109] op_sel:[0,1,0]
	v_pk_fma_f32 v[110:111], v[10:11], v[86:87], v[110:111]
	v_pk_fma_f32 v[112:113], v[22:23], v[86:87], v[112:113]
	ds_read_b128 v[68:71], v116 offset:14112
	ds_read_b128 v[84:87], v116 offset:14624
	s_waitcnt lgkmcnt(9)
; __device__ __forceinline__ float red8(float v) { v = red4(v); v += dppf<0x141>(v); return v; }
; __device__ __forceinline__ f32x2 lo2(const f32x4& v) { return __builtin_shufflevector(v, v, 0, 1); }
; __device__ __forceinline__ f32x2 hi2(const f32x4& v) { return __builtin_shufflevector(v, v, 2, 3); }
; __device__ __forceinline__ f32x2 splat2(float x) { return (f32x2){x, x}; }
; __device__ __forceinline__ void ss_load(SsRegs& R, const float* vb, const float* sb, int t, int n0, int prow0) {
;   const float* vt = vb + t * 320;
; #pragma unroll
;   for (int q = 0; q < 4; ++q) {
;     R.B[q] = *(const f32x4*)(vt + n0 + q * 4);
;     R.C[q] = *(const f32x4*)(vt + 128 + n0 + q * 4);
;   }
;   R.x = *(const f32x2*)(vt + 256 + prow0);
;   R.sc = *(const f32x2*)(sb + t * 2);
; }
; __device__ __forceinline__ f32x2 ss_step(f32x2 (&S)[2][8], const SsRegs& R) {
;   const f32x2 dA2 = splat2(R.sc.y);
;   f32x2 out;
; #pragma unroll
;   for (int r = 0; r < 2; ++r) {
;     const f32x2 xdt2 = splat2((r ? R.x.y : R.x.x) * R.sc.x);
;     f32x2 y0 = splat2(0.f), y1 = splat2(0.f);
; #pragma unroll
;     for (int q = 0; q < 4; ++q) {
;       S[r][2 * q] = S[r][2 * q] * dA2 + xdt2 * lo2(R.B[q]);
;       S[r][2 * q + 1] = S[r][2 * q + 1] * dA2 + xdt2 * hi2(R.B[q]);
;       y0 += S[r][2 * q] * lo2(R.C[q]);
;       y1 += S[r][2 * q + 1] * hi2(R.C[q]);
;     }
;     y0 += y1;
;     const float y = red8(y0.x + y0.y);
;     if (r) out.y = y; else out.x = y;
;   }
;   return out;
; }
	v_pk_mul_f32 v[102:103], v[100:101], v[72:73] op_sel_hi:[0,1]
	v_pk_mul_f32 v[104:105], v[100:101], v[72:73] op_sel:[1,0]
	v_pk_fma_f32 v[4:5], v[4:5], v[94:95], v[102:103] op_sel:[0,1,0]
	v_pk_fma_f32 v[16:17], v[16:17], v[94:95], v[104:105] op_sel:[0,1,0]
	v_pk_fma_f32 v[110:111], v[4:5], v[88:89], v[110:111]
	v_pk_fma_f32 v[112:113], v[16:17], v[88:89], v[112:113]
	v_pk_mul_f32 v[106:107], v[100:101], v[74:75] op_sel_hi:[0,1]
	v_pk_mul_f32 v[108:109], v[100:101], v[74:75] op_sel:[1,0]
	v_pk_fma_f32 v[6:7], v[6:7], v[94:95], v[106:107] op_sel:[0,1,0]
	v_pk_fma_f32 v[18:19], v[18:19], v[94:95], v[108:109] op_sel:[0,1,0]
	v_pk_fma_f32 v[110:111], v[6:7], v[90:91], v[110:111]
	v_pk_fma_f32 v[112:113], v[18:19], v[90:91], v[112:113]
	ds_read_b128 v[72:75], v116 offset:14128
	ds_read_b128 v[88:91], v116 offset:14640
	v_add_f32_e32 v114, v110, v111
	v_add_f32_e32 v115, v112, v113
	ds_read_b64 v[92:93], v117 offset:16384
	ds_read_b64 v[94:95], v118 offset:41056
	s_waitcnt lgkmcnt(4)
	v_pk_mul_f32 v[100:101], v[96:97], v[98:99] op_sel_hi:[1,0]
	v_pk_mul_f32 v[102:103], v[100:101], v[60:61] op_sel_hi:[0,1]
	v_pk_mul_f32 v[104:105], v[100:101], v[60:61] op_sel:[1,0]
	v_pk_fma_f32 v[28:29], v[28:29], v[98:99], v[102:103] op_sel:[0,1,0]
	v_pk_fma_f32 v[24:25], v[24:25], v[98:99], v[104:105] op_sel:[0,1,0]
	v_pk_mul_f32 v[110:111], v[28:29], v[76:77]
	v_pk_mul_f32 v[112:113], v[24:25], v[76:77]
	v_add_f32_dpp v114, v114, v114 quad_perm:[1,0,3,2] row_mask:0xf bank_mask:0xf bound_ctrl:1
	v_add_f32_dpp v115, v115, v115 quad_perm:[1,0,3,2] row_mask:0xf bank_mask:0xf bound_ctrl:1
	v_pk_mul_f32 v[106:107], v[100:101], v[62:63] op_sel_hi:[0,1]
	v_pk_mul_f32 v[108:109], v[100:101], v[62:63] op_sel:[1,0]
	v_pk_fma_f32 v[30:31], v[30:31], v[98:99], v[106:107] op_sel:[0,1,0]
	v_pk_fma_f32 v[26:27], v[26:27], v[98:99], v[108:109] op_sel:[0,1,0]
	v_pk_fma_f32 v[110:111], v[30:31], v[78:79], v[110:111]
	v_pk_fma_f32 v[112:113], v[26:27], v[78:79], v[112:113]
	ds_read_b128 v[60:63], v116 offset:15360
	ds_read_b128 v[76:79], v116 offset:15872
	v_add_f32_dpp v114, v114, v114 quad_perm:[2,3,0,1] row_mask:0xf bank_mask:0xf bound_ctrl:1
	v_add_f32_dpp v115, v115, v115 quad_perm:[2,3,0,1] row_mask:0xf bank_mask:0xf bound_ctrl:1
	v_pk_mul_f32 v[102:103], v[100:101], v[64:65] op_sel_hi:[0,1]
	v_pk_mul_f32 v[104:105], v[100:101], v[64:65] op_sel:[1,0]
	v_pk_fma_f32 v[12:13], v[12:13], v[98:99], v[102:103] op_sel:[0,1,0]
	v_pk_fma_f32 v[32:33], v[32:33], v[98:99], v[104:105] op_sel:[0,1,0]
	v_pk_fma_f32 v[110:111], v[12:13], v[80:81], v[110:111]
	v_pk_fma_f32 v[112:113], v[32:33], v[80:81], v[112:113]
	v_add_f32_dpp v114, v114, v114 row_half_mirror row_mask:0xf bank_mask:0xf bound_ctrl:1
	v_add_f32_dpp v115, v115, v115 row_half_mirror row_mask:0xf bank_mask:0xf bound_ctrl:1
	v_pk_mul_f32 v[106:107], v[100:101], v[66:67] op_sel_hi:[0,1]
	v_pk_mul_f32 v[108:109], v[100:101], v[66:67] op_sel:[1,0]
	v_pk_fma_f32 v[14:15], v[14:15], v[98:99], v[106:107] op_sel:[0,1,0]
	v_pk_fma_f32 v[34:35], v[34:35], v[98:99], v[108:109] op_sel:[0,1,0]
	v_pk_fma_f32 v[110:111], v[14:15], v[82:83], v[110:111]
	v_pk_fma_f32 v[112:113], v[34:35], v[82:83], v[112:113]
	ds_read_b128 v[64:67], v116 offset:15376
	ds_read_b128 v[80:83], v116 offset:15888
	ds_write_b64 v119, v[114:115] offset:2560
	v_pk_mul_f32 v[102:103], v[100:101], v[68:69] op_sel_hi:[0,1]
	v_pk_mul_f32 v[104:105], v[100:101], v[68:69] op_sel:[1,0]
	v_pk_fma_f32 v[8:9], v[8:9], v[98:99], v[102:103] op_sel:[0,1,0]
	v_pk_fma_f32 v[20:21], v[20:21], v[98:99], v[104:105] op_sel:[0,1,0]
	v_pk_fma_f32 v[110:111], v[8:9], v[84:85], v[110:111]
	v_pk_fma_f32 v[112:113], v[20:21], v[84:85], v[112:113]
	v_pk_mul_f32 v[106:107], v[100:101], v[70:71] op_sel_hi:[0,1]
	v_pk_mul_f32 v[108:109], v[100:101], v[70:71] op_sel:[1,0]
	v_pk_fma_f32 v[10:11], v[10:11], v[98:99], v[106:107] op_sel:[0,1,0]
	v_pk_fma_f32 v[22:23], v[22:23], v[98:99], v[108:109] op_sel:[0,1,0]
	v_pk_fma_f32 v[110:111], v[10:11], v[86:87], v[110:111]
	v_pk_fma_f32 v[112:113], v[22:23], v[86:87], v[112:113]
	ds_read_b128 v[68:71], v116 offset:15392
	ds_read_b128 v[84:87], v116 offset:15904
	s_waitcnt lgkmcnt(9)
	v_pk_mul_f32 v[102:103], v[100:101], v[72:73] op_sel_hi:[0,1]
	v_pk_mul_f32 v[104:105], v[100:101], v[72:73] op_sel:[1,0]
	v_pk_fma_f32 v[4:5], v[4:5], v[98:99], v[102:103] op_sel:[0,1,0]
	v_pk_fma_f32 v[16:17], v[16:17], v[98:99], v[104:105] op_sel:[0,1,0]
	v_pk_fma_f32 v[110:111], v[4:5], v[88:89], v[110:111]
	v_pk_fma_f32 v[112:113], v[16:17], v[88:89], v[112:113]
	v_pk_mul_f32 v[106:107], v[100:101], v[74:75] op_sel_hi:[0,1]
	v_pk_mul_f32 v[108:109], v[100:101], v[74:75] op_sel:[1,0]
	v_pk_fma_f32 v[6:7], v[6:7], v[98:99], v[106:107] op_sel:[0,1,0]
	v_pk_fma_f32 v[18:19], v[18:19], v[98:99], v[108:109] op_sel:[0,1,0]
	v_pk_fma_f32 v[110:111], v[6:7], v[90:91], v[110:111]
	v_pk_fma_f32 v[112:113], v[18:19], v[90:91], v[112:113]
	ds_read_b128 v[72:75], v116 offset:15408
	ds_read_b128 v[88:91], v116 offset:15920
	v_add_f32_e32 v114, v110, v111
	v_add_f32_e32 v115, v112, v113
	ds_read_b64 v[96:97], v117 offset:17664
	ds_read_b64 v[98:99], v118 offset:41064
	s_waitcnt lgkmcnt(4)
; __device__ __forceinline__ float red8(float v) { v = red4(v); v += dppf<0x141>(v); return v; }
; __device__ __forceinline__ f32x2 lo2(const f32x4& v) { return __builtin_shufflevector(v, v, 0, 1); }
; __device__ __forceinline__ f32x2 hi2(const f32x4& v) { return __builtin_shufflevector(v, v, 2, 3); }
; __device__ __forceinline__ f32x2 splat2(float x) { return (f32x2){x, x}; }
; __device__ __forceinline__ void ss_load(SsRegs& R, const float* vb, const float* sb, int t, int n0, int prow0) {
;   const float* vt = vb + t * 320;
; #pragma unroll
;   for (int q = 0; q < 4; ++q) {
;     R.B[q] = *(const f32x4*)(vt + n0 + q * 4);
;     R.C[q] = *(const f32x4*)(vt + 128 + n0 + q * 4);
;   }
;   R.x = *(const f32x2*)(vt + 256 + prow0);
;   R.sc = *(const f32x2*)(sb + t * 2);
; }
; __device__ __forceinline__ f32x2 ss_step(f32x2 (&S)[2][8], const SsRegs& R) {
;   const f32x2 dA2 = splat2(R.sc.y);
;   f32x2 out;
; #pragma unroll
;   for (int r = 0; r < 2; ++r) {
;     const f32x2 xdt2 = splat2((r ? R.x.y : R.x.x) * R.sc.x);
;     f32x2 y0 = splat2(0.f), y1 = splat2(0.f);
; #pragma unroll
;     for (int q = 0; q < 4; ++q) {
;       S[r][2 * q] = S[r][2 * q] * dA2 + xdt2 * lo2(R.B[q]);
;       S[r][2 * q + 1] = S[r][2 * q + 1] * dA2 + xdt2 * hi2(R.B[q]);
;       y0 += S[r][2 * q] * lo2(R.C[q]);
;       y1 += S[r][2 * q + 1] * hi2(R.C[q]);
;     }
;     y0 += y1;
;     const float y = red8(y0.x + y0.y);
;     if (r) out.y = y; else out.x = y;
;   }
;   return out;
; }
	v_pk_mul_f32 v[100:101], v[92:93], v[94:95] op_sel_hi:[1,0]
	v_pk_mul_f32 v[102:103], v[100:101], v[60:61] op_sel_hi:[0,1]
	v_pk_mul_f32 v[104:105], v[100:101], v[60:61] op_sel:[1,0]
	v_pk_fma_f32 v[28:29], v[28:29], v[94:95], v[102:103] op_sel:[0,1,0]
	v_pk_fma_f32 v[24:25], v[24:25], v[94:95], v[104:105] op_sel:[0,1,0]
	v_pk_mul_f32 v[110:111], v[28:29], v[76:77]
	v_pk_mul_f32 v[112:113], v[24:25], v[76:77]
	v_add_f32_dpp v114, v114, v114 quad_perm:[1,0,3,2] row_mask:0xf bank_mask:0xf bound_ctrl:1
	v_add_f32_dpp v115, v115, v115 quad_perm:[1,0,3,2] row_mask:0xf bank_mask:0xf bound_ctrl:1
	v_pk_mul_f32 v[106:107], v[100:101], v[62:63] op_sel_hi:[0,1]
	v_pk_mul_f32 v[108:109], v[100:101], v[62:63] op_sel:[1,0]
	v_pk_fma_f32 v[30:31], v[30:31], v[94:95], v[106:107] op_sel:[0,1,0]
	v_pk_fma_f32 v[26:27], v[26:27], v[94:95], v[108:109] op_sel:[0,1,0]
	v_pk_fma_f32 v[110:111], v[30:31], v[78:79], v[110:111]
	v_pk_fma_f32 v[112:113], v[26:27], v[78:79], v[112:113]
	ds_read_b128 v[60:63], v116 offset:16640
	ds_read_b128 v[76:79], v116 offset:17152
	v_add_f32_dpp v114, v114, v114 quad_perm:[2,3,0,1] row_mask:0xf bank_mask:0xf bound_ctrl:1
	v_add_f32_dpp v115, v115, v115 quad_perm:[2,3,0,1] row_mask:0xf bank_mask:0xf bound_ctrl:1
	v_pk_mul_f32 v[102:103], v[100:101], v[64:65] op_sel_hi:[0,1]
	v_pk_mul_f32 v[104:105], v[100:101], v[64:65] op_sel:[1,0]
	v_pk_fma_f32 v[12:13], v[12:13], v[94:95], v[102:103] op_sel:[0,1,0]
	v_pk_fma_f32 v[32:33], v[32:33], v[94:95], v[104:105] op_sel:[0,1,0]
	v_pk_fma_f32 v[110:111], v[12:13], v[80:81], v[110:111]
	v_pk_fma_f32 v[112:113], v[32:33], v[80:81], v[112:113]
	v_add_f32_dpp v114, v114, v114 row_half_mirror row_mask:0xf bank_mask:0xf bound_ctrl:1
	v_add_f32_dpp v115, v115, v115 row_half_mirror row_mask:0xf bank_mask:0xf bound_ctrl:1
	v_pk_mul_f32 v[106:107], v[100:101], v[66:67] op_sel_hi:[0,1]
	v_pk_mul_f32 v[108:109], v[100:101], v[66:67] op_sel:[1,0]
	v_pk_fma_f32 v[14:15], v[14:15], v[94:95], v[106:107] op_sel:[0,1,0]
	v_pk_fma_f32 v[34:35], v[34:35], v[94:95], v[108:109] op_sel:[0,1,0]
	v_pk_fma_f32 v[110:111], v[14:15], v[82:83], v[110:111]
	v_pk_fma_f32 v[112:113], v[34:35], v[82:83], v[112:113]
	ds_read_b128 v[64:67], v116 offset:16656
	ds_read_b128 v[80:83], v116 offset:17168
	ds_write_b64 v119, v[114:115] offset:2816
	v_pk_mul_f32 v[102:103], v[100:101], v[68:69] op_sel_hi:[0,1]
	v_pk_mul_f32 v[104:105], v[100:101], v[68:69] op_sel:[1,0]
	v_pk_fma_f32 v[8:9], v[8:9], v[94:95], v[102:103] op_sel:[0,1,0]
	v_pk_fma_f32 v[20:21], v[20:21], v[94:95], v[104:105] op_sel:[0,1,0]
	v_pk_fma_f32 v[110:111], v[8:9], v[84:85], v[110:111]
	v_pk_fma_f32 v[112:113], v[20:21], v[84:85], v[112:113]
	v_pk_mul_f32 v[106:107], v[100:101], v[70:71] op_sel_hi:[0,1]
	v_pk_mul_f32 v[108:109], v[100:101], v[70:71] op_sel:[1,0]
	v_pk_fma_f32 v[10:11], v[10:11], v[94:95], v[106:107] op_sel:[0,1,0]
	v_pk_fma_f32 v[22:23], v[22:23], v[94:95], v[108:109] op_sel:[0,1,0]
	v_pk_fma_f32 v[110:111], v[10:11], v[86:87], v[110:111]
	v_pk_fma_f32 v[112:113], v[22:23], v[86:87], v[112:113]
	ds_read_b128 v[68:71], v116 offset:16672
	ds_read_b128 v[84:87], v116 offset:17184
	s_waitcnt lgkmcnt(9)
	v_pk_mul_f32 v[102:103], v[100:101], v[72:73] op_sel_hi:[0,1]
	v_pk_mul_f32 v[104:105], v[100:101], v[72:73] op_sel:[1,0]
	v_pk_fma_f32 v[4:5], v[4:5], v[94:95], v[102:103] op_sel:[0,1,0]
	v_pk_fma_f32 v[16:17], v[16:17], v[94:95], v[104:105] op_sel:[0,1,0]
	v_pk_fma_f32 v[110:111], v[4:5], v[88:89], v[110:111]
	v_pk_fma_f32 v[112:113], v[16:17], v[88:89], v[112:113]
	v_pk_mul_f32 v[106:107], v[100:101], v[74:75] op_sel_hi:[0,1]
	v_pk_mul_f32 v[108:109], v[100:101], v[74:75] op_sel:[1,0]
	v_pk_fma_f32 v[6:7], v[6:7], v[94:95], v[106:107] op_sel:[0,1,0]
	v_pk_fma_f32 v[18:19], v[18:19], v[94:95], v[108:109] op_sel:[0,1,0]
	v_pk_fma_f32 v[110:111], v[6:7], v[90:91], v[110:111]
	v_pk_fma_f32 v[112:113], v[18:19], v[90:91], v[112:113]
	ds_read_b128 v[72:75], v116 offset:16688
	ds_read_b128 v[88:91], v116 offset:17200
	v_add_f32_e32 v114, v110, v111
	v_add_f32_e32 v115, v112, v113
	ds_read_b64 v[92:93], v117 offset:18944
	ds_read_b64 v[94:95], v118 offset:41072
	s_waitcnt lgkmcnt(4)
	v_pk_mul_f32 v[100:101], v[96:97], v[98:99] op_sel_hi:[1,0]
	v_pk_mul_f32 v[102:103], v[100:101], v[60:61] op_sel_hi:[0,1]
	v_pk_mul_f32 v[104:105], v[100:101], v[60:61] op_sel:[1,0]
	v_pk_fma_f32 v[28:29], v[28:29], v[98:99], v[102:103] op_sel:[0,1,0]
	v_pk_fma_f32 v[24:25], v[24:25], v[98:99], v[104:105] op_sel:[0,1,0]
	v_pk_mul_f32 v[110:111], v[28:29], v[76:77]
	v_pk_mul_f32 v[112:113], v[24:25], v[76:77]
	v_add_f32_dpp v114, v114, v114 quad_perm:[1,0,3,2] row_mask:0xf bank_mask:0xf bound_ctrl:1
	v_add_f32_dpp v115, v115, v115 quad_perm:[1,0,3,2] row_mask:0xf bank_mask:0xf bound_ctrl:1
	v_pk_mul_f32 v[106:107], v[100:101], v[62:63] op_sel_hi:[0,1]
	v_pk_mul_f32 v[108:109], v[100:101], v[62:63] op_sel:[1,0]
	v_pk_fma_f32 v[30:31], v[30:31], v[98:99], v[106:107] op_sel:[0,1,0]
	v_pk_fma_f32 v[26:27], v[26:27], v[98:99], v[108:109] op_sel:[0,1,0]
	v_pk_fma_f32 v[110:111], v[30:31], v[78:79], v[110:111]
	v_pk_fma_f32 v[112:113], v[26:27], v[78:79], v[112:113]
	ds_read_b128 v[60:63], v116 offset:17920
	ds_read_b128 v[76:79], v116 offset:18432
	v_add_f32_dpp v114, v114, v114 quad_perm:[2,3,0,1] row_mask:0xf bank_mask:0xf bound_ctrl:1
	v_add_f32_dpp v115, v115, v115 quad_perm:[2,3,0,1] row_mask:0xf bank_mask:0xf bound_ctrl:1
	v_pk_mul_f32 v[102:103], v[100:101], v[64:65] op_sel_hi:[0,1]
	v_pk_mul_f32 v[104:105], v[100:101], v[64:65] op_sel:[1,0]
	v_pk_fma_f32 v[12:13], v[12:13], v[98:99], v[102:103] op_sel:[0,1,0]
	v_pk_fma_f32 v[32:33], v[32:33], v[98:99], v[104:105] op_sel:[0,1,0]
; __device__ __forceinline__ float red8(float v) { v = red4(v); v += dppf<0x141>(v); return v; }
; __device__ __forceinline__ f32x2 lo2(const f32x4& v) { return __builtin_shufflevector(v, v, 0, 1); }
; __device__ __forceinline__ f32x2 hi2(const f32x4& v) { return __builtin_shufflevector(v, v, 2, 3); }
; __device__ __forceinline__ f32x2 splat2(float x) { return (f32x2){x, x}; }
; __device__ __forceinline__ void ss_load(SsRegs& R, const float* vb, const float* sb, int t, int n0, int prow0) {
;   const float* vt = vb + t * 320;
; #pragma unroll
;   for (int q = 0; q < 4; ++q) {
;     R.B[q] = *(const f32x4*)(vt + n0 + q * 4);
;     R.C[q] = *(const f32x4*)(vt + 128 + n0 + q * 4);
;   }
;   R.x = *(const f32x2*)(vt + 256 + prow0);
;   R.sc = *(const f32x2*)(sb + t * 2);
; }
; __device__ __forceinline__ f32x2 ss_step(f32x2 (&S)[2][8], const SsRegs& R) {
;   const f32x2 dA2 = splat2(R.sc.y);
;   f32x2 out;
; #pragma unroll
;   for (int r = 0; r < 2; ++r) {
;     const f32x2 xdt2 = splat2((r ? R.x.y : R.x.x) * R.sc.x);
;     f32x2 y0 = splat2(0.f), y1 = splat2(0.f);
; #pragma unroll
;     for (int q = 0; q < 4; ++q) {
;       S[r][2 * q] = S[r][2 * q] * dA2 + xdt2 * lo2(R.B[q]);
;       S[r][2 * q + 1] = S[r][2 * q + 1] * dA2 + xdt2 * hi2(R.B[q]);
;       y0 += S[r][2 * q] * lo2(R.C[q]);
;       y1 += S[r][2 * q + 1] * hi2(R.C[q]);
;     }
;     y0 += y1;
;     const float y = red8(y0.x + y0.y);
;     if (r) out.y = y; else out.x = y;
;   }
;   return out;
; }
	v_pk_fma_f32 v[110:111], v[12:13], v[80:81], v[110:111]
	v_pk_fma_f32 v[112:113], v[32:33], v[80:81], v[112:113]
	v_add_f32_dpp v114, v114, v114 row_half_mirror row_mask:0xf bank_mask:0xf bound_ctrl:1
	v_add_f32_dpp v115, v115, v115 row_half_mirror row_mask:0xf bank_mask:0xf bound_ctrl:1
	v_pk_mul_f32 v[106:107], v[100:101], v[66:67] op_sel_hi:[0,1]
	v_pk_mul_f32 v[108:109], v[100:101], v[66:67] op_sel:[1,0]
	v_pk_fma_f32 v[14:15], v[14:15], v[98:99], v[106:107] op_sel:[0,1,0]
	v_pk_fma_f32 v[34:35], v[34:35], v[98:99], v[108:109] op_sel:[0,1,0]
	v_pk_fma_f32 v[110:111], v[14:15], v[82:83], v[110:111]
	v_pk_fma_f32 v[112:113], v[34:35], v[82:83], v[112:113]
	ds_read_b128 v[64:67], v116 offset:17936
	ds_read_b128 v[80:83], v116 offset:18448
	ds_write_b64 v119, v[114:115] offset:3072
	v_pk_mul_f32 v[102:103], v[100:101], v[68:69] op_sel_hi:[0,1]
	v_pk_mul_f32 v[104:105], v[100:101], v[68:69] op_sel:[1,0]
	v_pk_fma_f32 v[8:9], v[8:9], v[98:99], v[102:103] op_sel:[0,1,0]
	v_pk_fma_f32 v[20:21], v[20:21], v[98:99], v[104:105] op_sel:[0,1,0]
	v_pk_fma_f32 v[110:111], v[8:9], v[84:85], v[110:111]
	v_pk_fma_f32 v[112:113], v[20:21], v[84:85], v[112:113]
	v_pk_mul_f32 v[106:107], v[100:101], v[70:71] op_sel_hi:[0,1]
	v_pk_mul_f32 v[108:109], v[100:101], v[70:71] op_sel:[1,0]
	v_pk_fma_f32 v[10:11], v[10:11], v[98:99], v[106:107] op_sel:[0,1,0]
	v_pk_fma_f32 v[22:23], v[22:23], v[98:99], v[108:109] op_sel:[0,1,0]
	v_pk_fma_f32 v[110:111], v[10:11], v[86:87], v[110:111]
	v_pk_fma_f32 v[112:113], v[22:23], v[86:87], v[112:113]
	ds_read_b128 v[68:71], v116 offset:17952
	ds_read_b128 v[84:87], v116 offset:18464
	s_waitcnt lgkmcnt(9)
	v_pk_mul_f32 v[102:103], v[100:101], v[72:73] op_sel_hi:[0,1]
	v_pk_mul_f32 v[104:105], v[100:101], v[72:73] op_sel:[1,0]
	v_pk_fma_f32 v[4:5], v[4:5], v[98:99], v[102:103] op_sel:[0,1,0]
	v_pk_fma_f32 v[16:17], v[16:17], v[98:99], v[104:105] op_sel:[0,1,0]
	v_pk_fma_f32 v[110:111], v[4:5], v[88:89], v[110:111]
	v_pk_fma_f32 v[112:113], v[16:17], v[88:89], v[112:113]
	v_pk_mul_f32 v[106:107], v[100:101], v[74:75] op_sel_hi:[0,1]
	v_pk_mul_f32 v[108:109], v[100:101], v[74:75] op_sel:[1,0]
	v_pk_fma_f32 v[6:7], v[6:7], v[98:99], v[106:107] op_sel:[0,1,0]
	v_pk_fma_f32 v[18:19], v[18:19], v[98:99], v[108:109] op_sel:[0,1,0]
	v_pk_fma_f32 v[110:111], v[6:7], v[90:91], v[110:111]
	v_pk_fma_f32 v[112:113], v[18:19], v[90:91], v[112:113]
	ds_read_b128 v[72:75], v116 offset:17968
	ds_read_b128 v[88:91], v116 offset:18480
	v_add_f32_e32 v114, v110, v111
	v_add_f32_e32 v115, v112, v113
	ds_read_b64 v[96:97], v117 offset:20224
	ds_read_b64 v[98:99], v118 offset:41080
	s_waitcnt lgkmcnt(4)
	v_pk_mul_f32 v[100:101], v[92:93], v[94:95] op_sel_hi:[1,0]
	v_pk_mul_f32 v[102:103], v[100:101], v[60:61] op_sel_hi:[0,1]
	v_pk_mul_f32 v[104:105], v[100:101], v[60:61] op_sel:[1,0]
	v_pk_fma_f32 v[28:29], v[28:29], v[94:95], v[102:103] op_sel:[0,1,0]
	v_pk_fma_f32 v[24:25], v[24:25], v[94:95], v[104:105] op_sel:[0,1,0]
	v_pk_mul_f32 v[110:111], v[28:29], v[76:77]
	v_pk_mul_f32 v[112:113], v[24:25], v[76:77]
	v_add_f32_dpp v114, v114, v114 quad_perm:[1,0,3,2] row_mask:0xf bank_mask:0xf bound_ctrl:1
	v_add_f32_dpp v115, v115, v115 quad_perm:[1,0,3,2] row_mask:0xf bank_mask:0xf bound_ctrl:1
	v_pk_mul_f32 v[106:107], v[100:101], v[62:63] op_sel_hi:[0,1]
	v_pk_mul_f32 v[108:109], v[100:101], v[62:63] op_sel:[1,0]
	v_pk_fma_f32 v[30:31], v[30:31], v[94:95], v[106:107] op_sel:[0,1,0]
	v_pk_fma_f32 v[26:27], v[26:27], v[94:95], v[108:109] op_sel:[0,1,0]
	v_pk_fma_f32 v[110:111], v[30:31], v[78:79], v[110:111]
	v_pk_fma_f32 v[112:113], v[26:27], v[78:79], v[112:113]
	ds_read_b128 v[60:63], v116 offset:19200
	ds_read_b128 v[76:79], v116 offset:19712
	v_add_f32_dpp v114, v114, v114 quad_perm:[2,3,0,1] row_mask:0xf bank_mask:0xf bound_ctrl:1
	v_add_f32_dpp v115, v115, v115 quad_perm:[2,3,0,1] row_mask:0xf bank_mask:0xf bound_ctrl:1
	v_pk_mul_f32 v[102:103], v[100:101], v[64:65] op_sel_hi:[0,1]
	v_pk_mul_f32 v[104:105], v[100:101], v[64:65] op_sel:[1,0]
	v_pk_fma_f32 v[12:13], v[12:13], v[94:95], v[102:103] op_sel:[0,1,0]
	v_pk_fma_f32 v[32:33], v[32:33], v[94:95], v[104:105] op_sel:[0,1,0]
	v_pk_fma_f32 v[110:111], v[12:13], v[80:81], v[110:111]
	v_pk_fma_f32 v[112:113], v[32:33], v[80:81], v[112:113]
	v_add_f32_dpp v114, v114, v114 row_half_mirror row_mask:0xf bank_mask:0xf bound_ctrl:1
	v_add_f32_dpp v115, v115, v115 row_half_mirror row_mask:0xf bank_mask:0xf bound_ctrl:1
	v_pk_mul_f32 v[106:107], v[100:101], v[66:67] op_sel_hi:[0,1]
	v_pk_mul_f32 v[108:109], v[100:101], v[66:67] op_sel:[1,0]
	v_pk_fma_f32 v[14:15], v[14:15], v[94:95], v[106:107] op_sel:[0,1,0]
	v_pk_fma_f32 v[34:35], v[34:35], v[94:95], v[108:109] op_sel:[0,1,0]
	v_pk_fma_f32 v[110:111], v[14:15], v[82:83], v[110:111]
	v_pk_fma_f32 v[112:113], v[34:35], v[82:83], v[112:113]
	ds_read_b128 v[64:67], v116 offset:19216
	ds_read_b128 v[80:83], v116 offset:19728
	ds_write_b64 v119, v[114:115] offset:3328
	v_pk_mul_f32 v[102:103], v[100:101], v[68:69] op_sel_hi:[0,1]
	v_pk_mul_f32 v[104:105], v[100:101], v[68:69] op_sel:[1,0]
	v_pk_fma_f32 v[8:9], v[8:9], v[94:95], v[102:103] op_sel:[0,1,0]
	v_pk_fma_f32 v[20:21], v[20:21], v[94:95], v[104:105] op_sel:[0,1,0]
	v_pk_fma_f32 v[110:111], v[8:9], v[84:85], v[110:111]
	v_pk_fma_f32 v[112:113], v[20:21], v[84:85], v[112:113]
	v_pk_mul_f32 v[106:107], v[100:101], v[70:71] op_sel_hi:[0,1]
	v_pk_mul_f32 v[108:109], v[100:101], v[70:71] op_sel:[1,0]
	v_pk_fma_f32 v[10:11], v[10:11], v[94:95], v[106:107] op_sel:[0,1,0]
	v_pk_fma_f32 v[22:23], v[22:23], v[94:95], v[108:109] op_sel:[0,1,0]
	v_pk_fma_f32 v[110:111], v[10:11], v[86:87], v[110:111]
	v_pk_fma_f32 v[112:113], v[22:23], v[86:87], v[112:113]
	ds_read_b128 v[68:71], v116 offset:19232
	ds_read_b128 v[84:87], v116 offset:19744
	s_waitcnt lgkmcnt(9)
; __device__ __forceinline__ float red8(float v) { v = red4(v); v += dppf<0x141>(v); return v; }
; __device__ __forceinline__ f32x2 lo2(const f32x4& v) { return __builtin_shufflevector(v, v, 0, 1); }
; __device__ __forceinline__ f32x2 hi2(const f32x4& v) { return __builtin_shufflevector(v, v, 2, 3); }
; __device__ __forceinline__ f32x2 splat2(float x) { return (f32x2){x, x}; }
; __device__ __forceinline__ void ss_load(SsRegs& R, const float* vb, const float* sb, int t, int n0, int prow0) {
;   const float* vt = vb + t * 320;
; #pragma unroll
;   for (int q = 0; q < 4; ++q) {
;     R.B[q] = *(const f32x4*)(vt + n0 + q * 4);
;     R.C[q] = *(const f32x4*)(vt + 128 + n0 + q * 4);
;   }
;   R.x = *(const f32x2*)(vt + 256 + prow0);
;   R.sc = *(const f32x2*)(sb + t * 2);
; }
; __device__ __forceinline__ f32x2 ss_step(f32x2 (&S)[2][8], const SsRegs& R) {
;   const f32x2 dA2 = splat2(R.sc.y);
;   f32x2 out;
; #pragma unroll
;   for (int r = 0; r < 2; ++r) {
;     const f32x2 xdt2 = splat2((r ? R.x.y : R.x.x) * R.sc.x);
;     f32x2 y0 = splat2(0.f), y1 = splat2(0.f);
; #pragma unroll
;     for (int q = 0; q < 4; ++q) {
;       S[r][2 * q] = S[r][2 * q] * dA2 + xdt2 * lo2(R.B[q]);
;       S[r][2 * q + 1] = S[r][2 * q + 1] * dA2 + xdt2 * hi2(R.B[q]);
;       y0 += S[r][2 * q] * lo2(R.C[q]);
;       y1 += S[r][2 * q + 1] * hi2(R.C[q]);
;     }
;     y0 += y1;
;     const float y = red8(y0.x + y0.y);
;     if (r) out.y = y; else out.x = y;
;   }
;   return out;
; }
; __device__ __forceinline__ void scan_ssm(const Params& p, int l, int seq, int h, char* smem, const unsigned* wflags, unsigned wexpect) {
;     ...
;     for (int t = 0; t < nsteps; t += 2) {
;       ss_load(RB, vb, sb, min(t + 1, 15), n0, prow0);
;       const f32x2 y0v = ss_step(S, RA);
;       *(f32x2*)((part == 0) ? (yb + t * 64 + prow0) : ydummy) = y0v;
;       SCAN_INTERLEAVE(10, 5);
;       if (t + 1 < nsteps) {
;         ss_load(RA, vb, sb, min(t + 2, 15), n0, prow0);
;         const f32x2 y1v = ss_step(S, RB);
;         *(f32x2*)((part == 0) ? (yb + (t + 1) * 64 + prow0) : ydummy) = y1v;
;         SCAN_INTERLEAVE(10, 5);
;       }
;     }
	v_pk_mul_f32 v[102:103], v[100:101], v[72:73] op_sel_hi:[0,1]
	v_pk_mul_f32 v[104:105], v[100:101], v[72:73] op_sel:[1,0]
	v_pk_fma_f32 v[4:5], v[4:5], v[94:95], v[102:103] op_sel:[0,1,0]
	v_pk_fma_f32 v[16:17], v[16:17], v[94:95], v[104:105] op_sel:[0,1,0]
	v_pk_fma_f32 v[110:111], v[4:5], v[88:89], v[110:111]
	v_pk_fma_f32 v[112:113], v[16:17], v[88:89], v[112:113]
	v_pk_mul_f32 v[106:107], v[100:101], v[74:75] op_sel_hi:[0,1]
	v_pk_mul_f32 v[108:109], v[100:101], v[74:75] op_sel:[1,0]
	v_pk_fma_f32 v[6:7], v[6:7], v[94:95], v[106:107] op_sel:[0,1,0]
	v_pk_fma_f32 v[18:19], v[18:19], v[94:95], v[108:109] op_sel:[0,1,0]
	v_pk_fma_f32 v[110:111], v[6:7], v[90:91], v[110:111]
	v_pk_fma_f32 v[112:113], v[18:19], v[90:91], v[112:113]
	ds_read_b128 v[72:75], v116 offset:19248
	ds_read_b128 v[88:91], v116 offset:19760
	v_add_f32_e32 v114, v110, v111
	v_add_f32_e32 v115, v112, v113
	s_waitcnt lgkmcnt(2)
	v_pk_mul_f32 v[100:101], v[96:97], v[98:99] op_sel_hi:[1,0]
	v_pk_mul_f32 v[102:103], v[100:101], v[60:61] op_sel_hi:[0,1]
	v_pk_mul_f32 v[104:105], v[100:101], v[60:61] op_sel:[1,0]
	v_pk_fma_f32 v[28:29], v[28:29], v[98:99], v[102:103] op_sel:[0,1,0]
	v_pk_fma_f32 v[24:25], v[24:25], v[98:99], v[104:105] op_sel:[0,1,0]
	v_pk_mul_f32 v[110:111], v[28:29], v[76:77]
	v_pk_mul_f32 v[112:113], v[24:25], v[76:77]
	v_add_f32_dpp v114, v114, v114 quad_perm:[1,0,3,2] row_mask:0xf bank_mask:0xf bound_ctrl:1
	v_add_f32_dpp v115, v115, v115 quad_perm:[1,0,3,2] row_mask:0xf bank_mask:0xf bound_ctrl:1
	v_pk_mul_f32 v[106:107], v[100:101], v[62:63] op_sel_hi:[0,1]
	v_pk_mul_f32 v[108:109], v[100:101], v[62:63] op_sel:[1,0]
	v_pk_fma_f32 v[30:31], v[30:31], v[98:99], v[106:107] op_sel:[0,1,0]
	v_pk_fma_f32 v[26:27], v[26:27], v[98:99], v[108:109] op_sel:[0,1,0]
	v_pk_fma_f32 v[110:111], v[30:31], v[78:79], v[110:111]
	v_pk_fma_f32 v[112:113], v[26:27], v[78:79], v[112:113]
	v_add_f32_dpp v114, v114, v114 quad_perm:[2,3,0,1] row_mask:0xf bank_mask:0xf bound_ctrl:1
	v_add_f32_dpp v115, v115, v115 quad_perm:[2,3,0,1] row_mask:0xf bank_mask:0xf bound_ctrl:1
	v_pk_mul_f32 v[102:103], v[100:101], v[64:65] op_sel_hi:[0,1]
	v_pk_mul_f32 v[104:105], v[100:101], v[64:65] op_sel:[1,0]
	v_pk_fma_f32 v[12:13], v[12:13], v[98:99], v[102:103] op_sel:[0,1,0]
	v_pk_fma_f32 v[32:33], v[32:33], v[98:99], v[104:105] op_sel:[0,1,0]
	v_pk_fma_f32 v[110:111], v[12:13], v[80:81], v[110:111]
	v_pk_fma_f32 v[112:113], v[32:33], v[80:81], v[112:113]
	v_add_f32_dpp v114, v114, v114 row_half_mirror row_mask:0xf bank_mask:0xf bound_ctrl:1
	v_add_f32_dpp v115, v115, v115 row_half_mirror row_mask:0xf bank_mask:0xf bound_ctrl:1
	v_pk_mul_f32 v[106:107], v[100:101], v[66:67] op_sel_hi:[0,1]
	v_pk_mul_f32 v[108:109], v[100:101], v[66:67] op_sel:[1,0]
	v_pk_fma_f32 v[14:15], v[14:15], v[98:99], v[106:107] op_sel:[0,1,0]
	v_pk_fma_f32 v[34:35], v[34:35], v[98:99], v[108:109] op_sel:[0,1,0]
	v_pk_fma_f32 v[110:111], v[14:15], v[82:83], v[110:111]
	v_pk_fma_f32 v[112:113], v[34:35], v[82:83], v[112:113]
	ds_write_b64 v119, v[114:115] offset:3584
	v_pk_mul_f32 v[102:103], v[100:101], v[68:69] op_sel_hi:[0,1]
	v_pk_mul_f32 v[104:105], v[100:101], v[68:69] op_sel:[1,0]
	v_pk_fma_f32 v[8:9], v[8:9], v[98:99], v[102:103] op_sel:[0,1,0]
	v_pk_fma_f32 v[20:21], v[20:21], v[98:99], v[104:105] op_sel:[0,1,0]
	v_pk_fma_f32 v[110:111], v[8:9], v[84:85], v[110:111]
	v_pk_fma_f32 v[112:113], v[20:21], v[84:85], v[112:113]
	v_pk_mul_f32 v[106:107], v[100:101], v[70:71] op_sel_hi:[0,1]
	v_pk_mul_f32 v[108:109], v[100:101], v[70:71] op_sel:[1,0]
	v_pk_fma_f32 v[10:11], v[10:11], v[98:99], v[106:107] op_sel:[0,1,0]
	v_pk_fma_f32 v[22:23], v[22:23], v[98:99], v[108:109] op_sel:[0,1,0]
	v_pk_fma_f32 v[110:111], v[10:11], v[86:87], v[110:111]
	v_pk_fma_f32 v[112:113], v[22:23], v[86:87], v[112:113]
	s_waitcnt lgkmcnt(1)
	v_pk_mul_f32 v[102:103], v[100:101], v[72:73] op_sel_hi:[0,1]
	v_pk_mul_f32 v[104:105], v[100:101], v[72:73] op_sel:[1,0]
	v_pk_fma_f32 v[4:5], v[4:5], v[98:99], v[102:103] op_sel:[0,1,0]
	v_pk_fma_f32 v[16:17], v[16:17], v[98:99], v[104:105] op_sel:[0,1,0]
	v_pk_fma_f32 v[110:111], v[4:5], v[88:89], v[110:111]
	v_pk_fma_f32 v[112:113], v[16:17], v[88:89], v[112:113]
	v_pk_mul_f32 v[106:107], v[100:101], v[74:75] op_sel_hi:[0,1]
	v_pk_mul_f32 v[108:109], v[100:101], v[74:75] op_sel:[1,0]
	v_pk_fma_f32 v[6:7], v[6:7], v[98:99], v[106:107] op_sel:[0,1,0]
	v_pk_fma_f32 v[18:19], v[18:19], v[98:99], v[108:109] op_sel:[0,1,0]
	v_pk_fma_f32 v[110:111], v[6:7], v[90:91], v[110:111]
	v_pk_fma_f32 v[112:113], v[18:19], v[90:91], v[112:113]
	v_add_f32_e32 v114, v110, v111
	v_add_f32_e32 v115, v112, v113
	s_nop 0
	v_add_f32_dpp v114, v114, v114 quad_perm:[1,0,3,2] row_mask:0xf bank_mask:0xf bound_ctrl:1
	v_add_f32_dpp v115, v115, v115 quad_perm:[1,0,3,2] row_mask:0xf bank_mask:0xf bound_ctrl:1
	s_nop 0
	v_add_f32_dpp v114, v114, v114 quad_perm:[2,3,0,1] row_mask:0xf bank_mask:0xf bound_ctrl:1
	v_add_f32_dpp v115, v115, v115 quad_perm:[2,3,0,1] row_mask:0xf bank_mask:0xf bound_ctrl:1
	s_nop 0
	v_add_f32_dpp v114, v114, v114 row_half_mirror row_mask:0xf bank_mask:0xf bound_ctrl:1
	v_add_f32_dpp v115, v115, v115 row_half_mirror row_mask:0xf bank_mask:0xf bound_ctrl:1
	ds_write_b64 v119, v[114:115] offset:3840
	s_cmp_eq_u32 s50, 0
	s_cbranch_scc1 .LBB0_648
	s_branch .LBB0_684
